# GEMM loops: s_setprio 0 issued before the last MFMA of each segment so that s_barrier follows the last MFMA directly (on top of saddr DMA addresses, setprio-1 hoist, f8f6f4 fp8 GEMM)
# speedup vs baseline: 1.0159x; 1.0003x over previous
; #define PG8_STAGE(bufoff, gbase, voff) do { _Pragma("unroll") for (int _i = 0; _i < 2; ++_i) \
;         __builtin_amdgcn_global_load_lds((const unsigned*)((const char*)(gbase) + (voff)[_i]), (LAS unsigned*)(lds + (bufoff) + ldsw + _i * 8192), 16, 0, 0); } while (0)
; #define PG8_LDA(dst, b, h) do { _Pragma("unroll") for (int m = 0; m < 4; ++m) _Pragma("unroll") for (int k = 0; k < 2; ++k) dst[m][k] = *(const LAS bf16x8*)(lds + PG8_SA(b, h) + aoff + m * 2048 + k * 1024); } while (0)
; #define PG8_LDB(dst, b, h) do { _Pragma("unroll") for (int n = 0; n < 2; ++n) _Pragma("unroll") for (int k = 0; k < 2; ++k) dst[n][k] = *(const LAS bf16x8*)(lds + PG8_SB(b, h) + boff + n * 2048 + k * 1024); } while (0)
; #define PG8_WAIT_V(n) asm volatile("s_waitcnt vmcnt(" #n ")" ::: "memory")
; #define PG8_WAIT_L(n) asm volatile("s_waitcnt lgkmcnt(" #n ")" ::: "memory")
; #define PG8_BAR __builtin_amdgcn_s_barrier()
; #define PG8_SCHED __builtin_amdgcn_sched_barrier(0)
; template <class Epi, bool FP8 = false>
; __device__ __forceinline__ void gemm_phase(LAS unsigned char* lds, const Gemm g, const StaticOrder& S_, const Epi& E, const int tid) {
;     ...
;             const bool last = (t == nt - 2);
;             const char* a1 = cA + (size_t)(t + 1) * kstep;
;             const char* a2 = last ? nA : cA + (size_t)(t + 2) * kstep; const char* b2 = last ? nB : cB + (size_t)(t + 2) * kstep;
;             const char* a3 = a2 + kstep; const char* b3 = b2 + kstep;
;             PG8_LDB(B0, 0, 0); PG8_LDB(B1, 0, 1); PG8_SCHED; PG8_LDA(At, 0, 0); PG8_STAGE(PG8_SA(1, 1), a1 + hstepA, voffA);
;             PG8_WAIT_V(8); PG8_WAIT_L(0); PG8_BAR; PG8_MMA(0, 0, At, B0); PG8_MMA(0, 1, At, B1); PG8_BAR; PG8_SCHED;
;             PG8_LDA(At, 0, 1); PG8_STAGE(PG8_SB(0, 0), b2, voffB); PG8_STAGE(PG8_SB(0, 1), b2 + hstepB, voffB); PG8_STAGE(PG8_SA(0, 0), a2, voffA);
;             PG8_WAIT_V(8); PG8_WAIT_L(0); PG8_BAR; PG8_MMA(1, 0, At, B0); PG8_MMA(1, 1, At, B1); PG8_BAR; PG8_SCHED;
.LBB0_233:
	ds_read_b128 v[150:153], v147
	ds_read_b128 v[154:157], v147 offset:1024
	ds_read_b128 v[158:161], v147 offset:2048
	ds_read_b128 v[162:165], v147 offset:3072
	ds_read_b128 v[166:169], v148
	ds_read_b128 v[170:173], v148 offset:1024
	ds_read_b128 v[174:177], v148 offset:2048
	ds_read_b128 v[178:181], v148 offset:3072
	s_add_u32 s44, s30, 0xfff80080
	s_addc_u32 s45, s31, -1
	s_cmp_eq_u32 s70, 28
	s_cselect_b32 s47, s17, s45
	s_cselect_b32 s46, s43, s44
	s_cselect_b32 s45, s15, s69
	s_cselect_b32 s44, s66, s68
	s_add_i32 m0, s29, 0xc000
	ds_read_b128 v[182:185], v149
	ds_read_b128 v[186:189], v149 offset:1024
	ds_read_b128 v[190:193], v149 offset:2048
	ds_read_b128 v[194:197], v149 offset:3072
	ds_read_b128 v[198:201], v149 offset:4096
	ds_read_b128 v[202:205], v149 offset:5120
	ds_read_b128 v[206:209], v149 offset:6144
	ds_read_b128 v[210:213], v149 offset:7168
	global_load_lds_dwordx4 v136, s[30:31]
	s_add_i32 m0, s29, 0xe000
	s_nop 0
	global_load_lds_dwordx4 v138, s[30:31]
	s_waitcnt vmcnt(8)
	s_waitcnt lgkmcnt(0)
	s_setprio 1
	s_barrier
	v_mfma_f32_16x16x32_bf16 v[124:127], v[150:153], v[182:185], v[124:127]
	v_mfma_f32_16x16x32_bf16 v[120:123], v[158:161], v[182:185], v[120:123]
	v_mfma_f32_16x16x32_bf16 v[108:111], v[150:153], v[190:193], v[108:111]
	v_mfma_f32_16x16x32_bf16 v[104:107], v[158:161], v[190:193], v[104:107]
	v_mfma_f32_16x16x32_bf16 v[92:95], v[150:153], v[198:201], v[92:95]
	v_mfma_f32_16x16x32_bf16 v[88:91], v[158:161], v[198:201], v[88:91]
	v_mfma_f32_16x16x32_bf16 v[76:79], v[150:153], v[206:209], v[76:79]
	v_mfma_f32_16x16x32_bf16 v[72:75], v[158:161], v[206:209], v[72:75]
	v_mfma_f32_16x16x32_bf16 v[124:127], v[154:157], v[186:189], v[124:127]
	v_mfma_f32_16x16x32_bf16 v[120:123], v[162:165], v[186:189], v[120:123]
	v_mfma_f32_16x16x32_bf16 v[108:111], v[154:157], v[194:197], v[108:111]
	v_mfma_f32_16x16x32_bf16 v[104:107], v[162:165], v[194:197], v[104:107]
	v_mfma_f32_16x16x32_bf16 v[92:95], v[154:157], v[202:205], v[92:95]
	v_mfma_f32_16x16x32_bf16 v[88:91], v[162:165], v[202:205], v[88:91]
	v_mfma_f32_16x16x32_bf16 v[76:79], v[154:157], v[210:213], v[76:79]
	v_mfma_f32_16x16x32_bf16 v[72:75], v[162:165], v[210:213], v[72:75]
	v_mfma_f32_16x16x32_bf16 v[116:119], v[166:169], v[182:185], v[116:119]
	v_mfma_f32_16x16x32_bf16 v[112:115], v[174:177], v[182:185], v[112:115]
	v_mfma_f32_16x16x32_bf16 v[100:103], v[166:169], v[190:193], v[100:103]
	v_mfma_f32_16x16x32_bf16 v[96:99], v[174:177], v[190:193], v[96:99]
	v_mfma_f32_16x16x32_bf16 v[84:87], v[166:169], v[198:201], v[84:87]
	v_mfma_f32_16x16x32_bf16 v[80:83], v[174:177], v[198:201], v[80:83]
	v_mfma_f32_16x16x32_bf16 v[68:71], v[166:169], v[206:209], v[68:71]
	v_mfma_f32_16x16x32_bf16 v[64:67], v[174:177], v[206:209], v[64:67]
	v_mfma_f32_16x16x32_bf16 v[116:119], v[170:173], v[186:189], v[116:119]
	v_mfma_f32_16x16x32_bf16 v[112:115], v[178:181], v[186:189], v[112:115]
	v_mfma_f32_16x16x32_bf16 v[100:103], v[170:173], v[194:197], v[100:103]
	v_mfma_f32_16x16x32_bf16 v[96:99], v[178:181], v[194:197], v[96:99]
	v_mfma_f32_16x16x32_bf16 v[84:87], v[170:173], v[202:205], v[84:87]
	v_mfma_f32_16x16x32_bf16 v[80:83], v[178:181], v[202:205], v[80:83]
	v_mfma_f32_16x16x32_bf16 v[68:71], v[170:173], v[210:213], v[68:71]
	s_setprio 0
	v_mfma_f32_16x16x32_bf16 v[64:67], v[178:181], v[210:213], v[64:67]
	s_barrier
	s_add_u32 s98, s44, s10
	s_addc_u32 s99, s45, s11
	s_add_u32 s100, s46, s10
	s_addc_u32 s101, s47, s11
	s_add_i32 s71, s61, s51
	s_mov_b32 m0, s71
	ds_read_b128 v[182:185], v149 offset:16384
	ds_read_b128 v[186:189], v149 offset:17408
	ds_read_b128 v[190:193], v149 offset:18432
	ds_read_b128 v[194:197], v149 offset:19456
	ds_read_b128 v[198:201], v149 offset:20480
	ds_read_b128 v[202:205], v149 offset:21504
	ds_read_b128 v[206:209], v149 offset:22528
	ds_read_b128 v[210:213], v149 offset:23552
	global_load_lds_dwordx4 v128, s[44:45]
	s_add_i32 m0, s71, 0x2000
	s_add_u32 s72, s44, 0x80000
	s_addc_u32 s73, s45, 0
	s_add_i32 s71, s62, s51
	global_load_lds_dwordx4 v130, s[44:45]
	s_mov_b32 m0, s71
	s_nop 0
	global_load_lds_dwordx4 v128, s[72:73]
	s_add_i32 m0, s71, 0x2000
	s_nop 0
	global_load_lds_dwordx4 v130, s[72:73]
	s_mov_b32 m0, s29
	s_nop 0
	global_load_lds_dwordx4 v134, s[46:47]
	s_mov_b32 m0, s54
	s_nop 0
	global_load_lds_dwordx4 v132, s[46:47]
	s_waitcnt vmcnt(8)
	s_waitcnt lgkmcnt(0)
	s_setprio 1
	s_barrier
	v_mfma_f32_16x16x32_bf16 v[60:63], v[150:153], v[182:185], v[60:63]
	v_mfma_f32_16x16x32_bf16 v[56:59], v[158:161], v[182:185], v[56:59]
	v_mfma_f32_16x16x32_bf16 v[44:47], v[150:153], v[190:193], v[44:47]
	v_mfma_f32_16x16x32_bf16 v[40:43], v[158:161], v[190:193], v[40:43]
	v_mfma_f32_16x16x32_bf16 v[28:31], v[150:153], v[198:201], v[28:31]
	v_mfma_f32_16x16x32_bf16 v[24:27], v[158:161], v[198:201], v[24:27]
	v_mfma_f32_16x16x32_bf16 v[12:15], v[150:153], v[206:209], v[12:15]
	v_mfma_f32_16x16x32_bf16 v[8:11], v[158:161], v[206:209], v[8:11]
	v_mfma_f32_16x16x32_bf16 v[60:63], v[154:157], v[186:189], v[60:63]
	v_mfma_f32_16x16x32_bf16 v[56:59], v[162:165], v[186:189], v[56:59]
	v_mfma_f32_16x16x32_bf16 v[44:47], v[154:157], v[194:197], v[44:47]
	v_mfma_f32_16x16x32_bf16 v[40:43], v[162:165], v[194:197], v[40:43]
	v_mfma_f32_16x16x32_bf16 v[28:31], v[154:157], v[202:205], v[28:31]
	v_mfma_f32_16x16x32_bf16 v[24:27], v[162:165], v[202:205], v[24:27]
	v_mfma_f32_16x16x32_bf16 v[12:15], v[154:157], v[210:213], v[12:15]
	v_mfma_f32_16x16x32_bf16 v[8:11], v[162:165], v[210:213], v[8:11]
	v_mfma_f32_16x16x32_bf16 v[52:55], v[166:169], v[182:185], v[52:55]
	v_mfma_f32_16x16x32_bf16 v[48:51], v[174:177], v[182:185], v[48:51]
	v_mfma_f32_16x16x32_bf16 v[36:39], v[166:169], v[190:193], v[36:39]
	v_mfma_f32_16x16x32_bf16 v[32:35], v[174:177], v[190:193], v[32:35]
	v_mfma_f32_16x16x32_bf16 v[20:23], v[166:169], v[198:201], v[20:23]
	v_mfma_f32_16x16x32_bf16 v[16:19], v[174:177], v[198:201], v[16:19]
	v_mfma_f32_16x16x32_bf16 v[4:7], v[166:169], v[206:209], v[4:7]
	v_mfma_f32_16x16x32_bf16 v[0:3], v[174:177], v[206:209], v[0:3]
	v_mfma_f32_16x16x32_bf16 v[52:55], v[170:173], v[186:189], v[52:55]
	v_mfma_f32_16x16x32_bf16 v[48:51], v[178:181], v[186:189], v[48:51]
	v_mfma_f32_16x16x32_bf16 v[36:39], v[170:173], v[194:197], v[36:39]
	v_mfma_f32_16x16x32_bf16 v[32:35], v[178:181], v[194:197], v[32:35]
	v_mfma_f32_16x16x32_bf16 v[20:23], v[170:173], v[202:205], v[20:23]
	v_mfma_f32_16x16x32_bf16 v[16:19], v[178:181], v[202:205], v[16:19]
	v_mfma_f32_16x16x32_bf16 v[4:7], v[170:173], v[210:213], v[4:7]
	s_setprio 0
	v_mfma_f32_16x16x32_bf16 v[0:3], v[178:181], v[210:213], v[0:3]
	s_barrier
; #define PG8_STAGE(bufoff, gbase, voff) do { _Pragma("unroll") for (int _i = 0; _i < 2; ++_i) \
;         __builtin_amdgcn_global_load_lds((const unsigned*)((const char*)(gbase) + (voff)[_i]), (LAS unsigned*)(lds + (bufoff) + ldsw + _i * 8192), 16, 0, 0); } while (0)
; #define PG8_LDA(dst, b, h) do { _Pragma("unroll") for (int m = 0; m < 4; ++m) _Pragma("unroll") for (int k = 0; k < 2; ++k) dst[m][k] = *(const LAS bf16x8*)(lds + PG8_SA(b, h) + aoff + m * 2048 + k * 1024); } while (0)
; #define PG8_LDB(dst, b, h) do { _Pragma("unroll") for (int n = 0; n < 2; ++n) _Pragma("unroll") for (int k = 0; k < 2; ++k) dst[n][k] = *(const LAS bf16x8*)(lds + PG8_SB(b, h) + boff + n * 2048 + k * 1024); } while (0)
; #define PG8_WAIT_V(n) asm volatile("s_waitcnt vmcnt(" #n ")" ::: "memory")
; #define PG8_WAIT_L(n) asm volatile("s_waitcnt lgkmcnt(" #n ")" ::: "memory")
; #define PG8_BAR __builtin_amdgcn_s_barrier()
; #define PG8_SCHED __builtin_amdgcn_sched_barrier(0)
; template <class Epi, bool FP8 = false>
; __device__ __forceinline__ void gemm_phase(LAS unsigned char* lds, const Gemm g, const StaticOrder& S_, const Epi& E, const int tid) {
;     ...
;             PG8_LDB(B0, 1, 0); PG8_LDB(B1, 1, 1); PG8_SCHED; PG8_LDA(At, 1, 0); PG8_STAGE(PG8_SA(0, 1), a2 + hstepA, voffA);
;             PG8_WAIT_V(8); PG8_WAIT_L(0); PG8_BAR; PG8_MMA(0, 0, At, B0); PG8_MMA(0, 1, At, B1); PG8_BAR; PG8_SCHED;
;             PG8_LDA(At, 1, 1); PG8_STAGE(PG8_SB(1, 0), b3, voffB); PG8_STAGE(PG8_SB(1, 1), b3 + hstepB, voffB); PG8_STAGE(PG8_SA(1, 0), a3, voffA);
;             PG8_WAIT_V(8); PG8_WAIT_L(0); PG8_BAR; PG8_MMA(1, 0, At, B0); PG8_MMA(1, 1, At, B1); PG8_BAR; PG8_SCHED;
;         }
;         if (wr == 0) PG8_BAR;
	s_add_i32 s71, 0, 0x18000
	s_add_i32 s72, 0, 0x1c000
	v_add_u32_e32 v162, s71, v145
	v_add_u32_e32 v178, s72, v145
	ds_read_b128 v[150:153], v162
	ds_read_b128 v[154:157], v162 offset:1024
	ds_read_b128 v[158:161], v162 offset:2048
	ds_read_b128 v[162:165], v162 offset:3072
	ds_read_b128 v[166:169], v178
	ds_read_b128 v[170:173], v178 offset:1024
	ds_read_b128 v[174:177], v178 offset:2048
	ds_read_b128 v[178:181], v178 offset:3072
	s_add_u32 s46, s46, 0x80000
	s_addc_u32 s47, s47, 0
	s_mov_b32 m0, s55
	ds_read_b128 v[182:185], v149 offset:32768
	ds_read_b128 v[186:189], v149 offset:33792
	ds_read_b128 v[190:193], v149 offset:34816
	ds_read_b128 v[194:197], v149 offset:35840
	ds_read_b128 v[198:201], v149 offset:36864
	ds_read_b128 v[202:205], v149 offset:37888
	ds_read_b128 v[206:209], v149 offset:38912
	ds_read_b128 v[210:213], v149 offset:39936
	global_load_lds_dwordx4 v134, s[46:47]
	s_mov_b32 m0, s56
	s_nop 0
	global_load_lds_dwordx4 v132, s[46:47]
	s_waitcnt vmcnt(8)
	s_waitcnt lgkmcnt(0)
	s_setprio 1
	s_barrier
	v_mfma_f32_16x16x32_bf16 v[124:127], v[150:153], v[182:185], v[124:127]
	v_mfma_f32_16x16x32_bf16 v[120:123], v[158:161], v[182:185], v[120:123]
	v_mfma_f32_16x16x32_bf16 v[108:111], v[150:153], v[190:193], v[108:111]
	v_mfma_f32_16x16x32_bf16 v[104:107], v[158:161], v[190:193], v[104:107]
	v_mfma_f32_16x16x32_bf16 v[92:95], v[150:153], v[198:201], v[92:95]
	v_mfma_f32_16x16x32_bf16 v[88:91], v[158:161], v[198:201], v[88:91]
	v_mfma_f32_16x16x32_bf16 v[76:79], v[150:153], v[206:209], v[76:79]
	v_mfma_f32_16x16x32_bf16 v[72:75], v[158:161], v[206:209], v[72:75]
	v_mfma_f32_16x16x32_bf16 v[124:127], v[154:157], v[186:189], v[124:127]
	v_mfma_f32_16x16x32_bf16 v[120:123], v[162:165], v[186:189], v[120:123]
	v_mfma_f32_16x16x32_bf16 v[108:111], v[154:157], v[194:197], v[108:111]
	v_mfma_f32_16x16x32_bf16 v[104:107], v[162:165], v[194:197], v[104:107]
	v_mfma_f32_16x16x32_bf16 v[92:95], v[154:157], v[202:205], v[92:95]
	v_mfma_f32_16x16x32_bf16 v[88:91], v[162:165], v[202:205], v[88:91]
	v_mfma_f32_16x16x32_bf16 v[76:79], v[154:157], v[210:213], v[76:79]
	v_mfma_f32_16x16x32_bf16 v[72:75], v[162:165], v[210:213], v[72:75]
	v_mfma_f32_16x16x32_bf16 v[116:119], v[166:169], v[182:185], v[116:119]
	v_mfma_f32_16x16x32_bf16 v[112:115], v[174:177], v[182:185], v[112:115]
	v_mfma_f32_16x16x32_bf16 v[100:103], v[166:169], v[190:193], v[100:103]
	v_mfma_f32_16x16x32_bf16 v[96:99], v[174:177], v[190:193], v[96:99]
	v_mfma_f32_16x16x32_bf16 v[84:87], v[166:169], v[198:201], v[84:87]
	v_mfma_f32_16x16x32_bf16 v[80:83], v[174:177], v[198:201], v[80:83]
	v_mfma_f32_16x16x32_bf16 v[68:71], v[166:169], v[206:209], v[68:71]
	v_mfma_f32_16x16x32_bf16 v[64:67], v[174:177], v[206:209], v[64:67]
	v_mfma_f32_16x16x32_bf16 v[116:119], v[170:173], v[186:189], v[116:119]
	v_mfma_f32_16x16x32_bf16 v[112:115], v[178:181], v[186:189], v[112:115]
	v_mfma_f32_16x16x32_bf16 v[100:103], v[170:173], v[194:197], v[100:103]
	v_mfma_f32_16x16x32_bf16 v[96:99], v[178:181], v[194:197], v[96:99]
	v_mfma_f32_16x16x32_bf16 v[84:87], v[170:173], v[202:205], v[84:87]
	v_mfma_f32_16x16x32_bf16 v[80:83], v[178:181], v[202:205], v[80:83]
	v_mfma_f32_16x16x32_bf16 v[68:71], v[170:173], v[210:213], v[68:71]
	s_setprio 0
	v_mfma_f32_16x16x32_bf16 v[64:67], v[178:181], v[210:213], v[64:67]
	s_barrier
	s_add_i32 s46, s71, s51
	s_mov_b32 m0, s46
	ds_read_b128 v[182:185], v149 offset:49152
	ds_read_b128 v[186:189], v149 offset:50176
	ds_read_b128 v[190:193], v149 offset:51200
	ds_read_b128 v[194:197], v149 offset:52224
	ds_read_b128 v[198:201], v149 offset:53248
	ds_read_b128 v[202:205], v149 offset:54272
	ds_read_b128 v[206:209], v149 offset:55296
	ds_read_b128 v[210:213], v149 offset:56320
	global_load_lds_dwordx4 v128, s[98:99]
	s_add_i32 m0, s46, 0x2000
	s_add_u32 s44, s44, 0x80080
	s_addc_u32 s45, s45, 0
	s_add_i32 s46, s72, s51
	global_load_lds_dwordx4 v130, s[98:99]
	s_mov_b32 m0, s46
	s_nop 0
	global_load_lds_dwordx4 v128, s[44:45]
	s_add_i32 m0, s46, 0x2000
	s_nop 0
	global_load_lds_dwordx4 v130, s[44:45]
	s_mov_b32 m0, s58
	s_nop 0
	global_load_lds_dwordx4 v134, s[100:101]
	s_mov_b32 m0, s59
	s_nop 0
	global_load_lds_dwordx4 v132, s[100:101]
	s_waitcnt vmcnt(8)
	s_waitcnt lgkmcnt(0)
	s_setprio 1
	s_barrier
	v_mfma_f32_16x16x32_bf16 v[60:63], v[150:153], v[182:185], v[60:63]
	v_mfma_f32_16x16x32_bf16 v[56:59], v[158:161], v[182:185], v[56:59]
	v_mfma_f32_16x16x32_bf16 v[44:47], v[150:153], v[190:193], v[44:47]
	v_mfma_f32_16x16x32_bf16 v[40:43], v[158:161], v[190:193], v[40:43]
	v_mfma_f32_16x16x32_bf16 v[28:31], v[150:153], v[198:201], v[28:31]
	v_mfma_f32_16x16x32_bf16 v[24:27], v[158:161], v[198:201], v[24:27]
	v_mfma_f32_16x16x32_bf16 v[12:15], v[150:153], v[206:209], v[12:15]
	v_mfma_f32_16x16x32_bf16 v[8:11], v[158:161], v[206:209], v[8:11]
	v_mfma_f32_16x16x32_bf16 v[60:63], v[154:157], v[186:189], v[60:63]
	v_mfma_f32_16x16x32_bf16 v[56:59], v[162:165], v[186:189], v[56:59]
	v_mfma_f32_16x16x32_bf16 v[44:47], v[154:157], v[194:197], v[44:47]
	v_mfma_f32_16x16x32_bf16 v[40:43], v[162:165], v[194:197], v[40:43]
	v_mfma_f32_16x16x32_bf16 v[28:31], v[154:157], v[202:205], v[28:31]
	v_mfma_f32_16x16x32_bf16 v[24:27], v[162:165], v[202:205], v[24:27]
	v_mfma_f32_16x16x32_bf16 v[12:15], v[154:157], v[210:213], v[12:15]
	v_mfma_f32_16x16x32_bf16 v[8:11], v[162:165], v[210:213], v[8:11]
	v_mfma_f32_16x16x32_bf16 v[52:55], v[166:169], v[182:185], v[52:55]
	v_mfma_f32_16x16x32_bf16 v[48:51], v[174:177], v[182:185], v[48:51]
	v_mfma_f32_16x16x32_bf16 v[36:39], v[166:169], v[190:193], v[36:39]
	v_mfma_f32_16x16x32_bf16 v[32:35], v[174:177], v[190:193], v[32:35]
	v_mfma_f32_16x16x32_bf16 v[20:23], v[166:169], v[198:201], v[20:23]
	v_mfma_f32_16x16x32_bf16 v[16:19], v[174:177], v[198:201], v[16:19]
	v_mfma_f32_16x16x32_bf16 v[4:7], v[166:169], v[206:209], v[4:7]
	v_mfma_f32_16x16x32_bf16 v[0:3], v[174:177], v[206:209], v[0:3]
	v_mfma_f32_16x16x32_bf16 v[52:55], v[170:173], v[186:189], v[52:55]
	v_mfma_f32_16x16x32_bf16 v[48:51], v[178:181], v[186:189], v[48:51]
	v_mfma_f32_16x16x32_bf16 v[36:39], v[170:173], v[194:197], v[36:39]
	v_mfma_f32_16x16x32_bf16 v[32:35], v[178:181], v[194:197], v[32:35]
	v_mfma_f32_16x16x32_bf16 v[20:23], v[170:173], v[202:205], v[20:23]
	v_mfma_f32_16x16x32_bf16 v[16:19], v[178:181], v[202:205], v[16:19]
	v_mfma_f32_16x16x32_bf16 v[4:7], v[170:173], v[210:213], v[4:7]
	s_setprio 0
	v_mfma_f32_16x16x32_bf16 v[0:3], v[178:181], v[210:213], v[0:3]
	s_barrier
	s_add_i32 s70, s70, 2
	s_add_u32 s30, s30, 0x100
	s_addc_u32 s31, s31, 0
	s_add_u32 s68, s68, 0x100
	s_addc_u32 s69, s69, 0
	s_cmp_gt_u32 s70, 29
	s_cbranch_scc0 .LBB0_233
	s_and_b64 vcc, exec, s[12:13]
	s_cbranch_vccz .LBB0_236
	s_barrier

; #define PG8_STAGE(bufoff, gbase, voff) do { _Pragma("unroll") for (int _i = 0; _i < 2; ++_i) \
;         __builtin_amdgcn_global_load_lds((const unsigned*)((const char*)(gbase) + (voff)[_i]), (LAS unsigned*)(lds + (bufoff) + ldsw + _i * 8192), 16, 0, 0); } while (0)
; #define PG8_LDA(dst, b, h) do { _Pragma("unroll") for (int m = 0; m < 4; ++m) _Pragma("unroll") for (int k = 0; k < 2; ++k) dst[m][k] = *(const LAS bf16x8*)(lds + PG8_SA(b, h) + aoff + m * 2048 + k * 1024); } while (0)
; #define PG8_LDB(dst, b, h) do { _Pragma("unroll") for (int n = 0; n < 2; ++n) _Pragma("unroll") for (int k = 0; k < 2; ++k) dst[n][k] = *(const LAS bf16x8*)(lds + PG8_SB(b, h) + boff + n * 2048 + k * 1024); } while (0)
; #define PG8_WAIT_V(n) asm volatile("s_waitcnt vmcnt(" #n ")" ::: "memory")
; #define PG8_WAIT_L(n) asm volatile("s_waitcnt lgkmcnt(" #n ")" ::: "memory")
; #define PG8_BAR __builtin_amdgcn_s_barrier()
; #define PG8_SCHED __builtin_amdgcn_sched_barrier(0)
; template <class Epi, bool FP8 = false>
; __device__ __forceinline__ void gemm_phase(LAS unsigned char* lds, const Gemm g, const StaticOrder& S_, const Epi& E, const int tid) {
;     ...
;             const bool last = (t == nt - 2);
;             const char* a1 = cA + (size_t)(t + 1) * kstep;
;             const char* a2 = last ? nA : cA + (size_t)(t + 2) * kstep; const char* b2 = last ? nB : cB + (size_t)(t + 2) * kstep;
;             const char* a3 = a2 + kstep; const char* b3 = b2 + kstep;
;             PG8_LDB(B0, 0, 0); PG8_LDB(B1, 0, 1); PG8_SCHED; PG8_LDA(At, 0, 0); PG8_STAGE(PG8_SA(1, 1), a1 + hstepA, voffA);
;             PG8_WAIT_V(8); PG8_WAIT_L(0); PG8_BAR; PG8_MMA(0, 0, At, B0); PG8_MMA(0, 1, At, B1); PG8_BAR; PG8_SCHED;
;             PG8_LDA(At, 0, 1); PG8_STAGE(PG8_SB(0, 0), b2, voffB); PG8_STAGE(PG8_SB(0, 1), b2 + hstepB, voffB); PG8_STAGE(PG8_SA(0, 0), a2, voffA);
;             PG8_WAIT_V(8); PG8_WAIT_L(0); PG8_BAR; PG8_MMA(1, 0, At, B0); PG8_MMA(1, 1, At, B1); PG8_BAR; PG8_SCHED;
.LBB0_319:
	ds_read_b128 v[150:153], v146
	ds_read_b128 v[154:157], v146 offset:1024
	ds_read_b128 v[158:161], v146 offset:2048
	ds_read_b128 v[162:165], v146 offset:3072
	ds_read_b128 v[166:169], v147
	ds_read_b128 v[170:173], v147 offset:1024
	ds_read_b128 v[174:177], v147 offset:2048
	ds_read_b128 v[178:181], v147 offset:3072
	s_add_u32 s50, s48, 0x100
	s_addc_u32 s51, s49, 0
	s_cmpk_eq_i32 s77, 0x54
	s_cselect_b32 s55, s7, s51
	s_cselect_b32 s54, s6, s50
	s_cselect_b32 s53, s45, s76
	s_cselect_b32 s52, s44, s75
	s_add_i32 m0, s60, 0xc000
	ds_read_b128 v[182:185], v148
	ds_read_b128 v[186:189], v148 offset:1024
	ds_read_b128 v[190:193], v148 offset:2048
	ds_read_b128 v[194:197], v148 offset:3072
	ds_read_b128 v[198:201], v148 offset:4096
	ds_read_b128 v[202:205], v148 offset:5120
	ds_read_b128 v[206:209], v148 offset:6144
	ds_read_b128 v[210:213], v148 offset:7168
	global_load_lds_dwordx4 v132, s[48:49]
	s_add_i32 m0, s60, 0xe000
	s_nop 0
	global_load_lds_dwordx4 v134, s[48:49]
	s_waitcnt vmcnt(8)
	s_waitcnt lgkmcnt(0)
	s_setprio 1
	s_barrier
	v_mfma_f32_16x16x32_bf16 v[124:127], v[150:153], v[182:185], v[124:127]
	v_mfma_f32_16x16x32_bf16 v[120:123], v[158:161], v[182:185], v[120:123]
	v_mfma_f32_16x16x32_bf16 v[112:115], v[150:153], v[190:193], v[112:115]
	v_mfma_f32_16x16x32_bf16 v[104:107], v[158:161], v[190:193], v[104:107]
	v_mfma_f32_16x16x32_bf16 v[96:99], v[150:153], v[198:201], v[96:99]
	v_mfma_f32_16x16x32_bf16 v[88:91], v[158:161], v[198:201], v[88:91]
	v_mfma_f32_16x16x32_bf16 v[80:83], v[150:153], v[206:209], v[80:83]
	v_mfma_f32_16x16x32_bf16 v[72:75], v[158:161], v[206:209], v[72:75]
	v_mfma_f32_16x16x32_bf16 v[124:127], v[154:157], v[186:189], v[124:127]
	v_mfma_f32_16x16x32_bf16 v[120:123], v[162:165], v[186:189], v[120:123]
	v_mfma_f32_16x16x32_bf16 v[112:115], v[154:157], v[194:197], v[112:115]
	v_mfma_f32_16x16x32_bf16 v[104:107], v[162:165], v[194:197], v[104:107]
	v_mfma_f32_16x16x32_bf16 v[96:99], v[154:157], v[202:205], v[96:99]
	v_mfma_f32_16x16x32_bf16 v[88:91], v[162:165], v[202:205], v[88:91]
	v_mfma_f32_16x16x32_bf16 v[80:83], v[154:157], v[210:213], v[80:83]
	v_mfma_f32_16x16x32_bf16 v[72:75], v[162:165], v[210:213], v[72:75]
	v_mfma_f32_16x16x32_bf16 v[116:119], v[166:169], v[182:185], v[116:119]
	v_mfma_f32_16x16x32_bf16 v[108:111], v[174:177], v[182:185], v[108:111]
	v_mfma_f32_16x16x32_bf16 v[100:103], v[166:169], v[190:193], v[100:103]
	v_mfma_f32_16x16x32_bf16 v[92:95], v[174:177], v[190:193], v[92:95]
	v_mfma_f32_16x16x32_bf16 v[84:87], v[166:169], v[198:201], v[84:87]
	v_mfma_f32_16x16x32_bf16 v[76:79], v[174:177], v[198:201], v[76:79]
	v_mfma_f32_16x16x32_bf16 v[68:71], v[166:169], v[206:209], v[68:71]
	v_mfma_f32_16x16x32_bf16 v[64:67], v[174:177], v[206:209], v[64:67]
	v_mfma_f32_16x16x32_bf16 v[116:119], v[170:173], v[186:189], v[116:119]
	v_mfma_f32_16x16x32_bf16 v[108:111], v[178:181], v[186:189], v[108:111]
	v_mfma_f32_16x16x32_bf16 v[100:103], v[170:173], v[194:197], v[100:103]
	v_mfma_f32_16x16x32_bf16 v[92:95], v[178:181], v[194:197], v[92:95]
	v_mfma_f32_16x16x32_bf16 v[84:87], v[170:173], v[202:205], v[84:87]
	v_mfma_f32_16x16x32_bf16 v[76:79], v[178:181], v[202:205], v[76:79]
	v_mfma_f32_16x16x32_bf16 v[68:71], v[170:173], v[210:213], v[68:71]
	s_setprio 0
	v_mfma_f32_16x16x32_bf16 v[64:67], v[178:181], v[210:213], v[64:67]
	s_barrier
	s_add_u32 s98, s52, s14
	s_addc_u32 s99, s53, s15
	s_add_u32 s100, s54, s14
	s_addc_u32 s101, s55, s15
	s_add_i32 s48, s71, s59
	s_mov_b32 m0, s48
	ds_read_b128 v[182:185], v148 offset:16384
	ds_read_b128 v[186:189], v148 offset:17408
	ds_read_b128 v[190:193], v148 offset:18432
	ds_read_b128 v[194:197], v148 offset:19456
	ds_read_b128 v[198:201], v148 offset:20480
	ds_read_b128 v[202:205], v148 offset:21504
	ds_read_b128 v[206:209], v148 offset:22528
	ds_read_b128 v[210:213], v148 offset:23552
	global_load_lds_dwordx4 v128, s[52:53]
	s_add_i32 m0, s48, 0x2000
	s_add_u32 s48, s52, 0x160000
	s_addc_u32 s49, s53, 0
	s_add_i32 s78, s72, s59
	global_load_lds_dwordx4 v130, s[52:53]
	s_mov_b32 m0, s78
	s_nop 0
	global_load_lds_dwordx4 v128, s[48:49]
	s_add_i32 m0, s78, 0x2000
	s_nop 0
	global_load_lds_dwordx4 v130, s[48:49]
	s_mov_b32 m0, s60
	s_nop 0
	global_load_lds_dwordx4 v128, s[54:55]
	s_mov_b32 m0, s61
	s_nop 0
	global_load_lds_dwordx4 v130, s[54:55]
	s_waitcnt vmcnt(8)
	s_waitcnt lgkmcnt(0)
	s_setprio 1
	s_barrier
	v_mfma_f32_16x16x32_bf16 v[60:63], v[150:153], v[182:185], v[60:63]
	v_mfma_f32_16x16x32_bf16 v[56:59], v[158:161], v[182:185], v[56:59]
	v_mfma_f32_16x16x32_bf16 v[48:51], v[150:153], v[190:193], v[48:51]
	v_mfma_f32_16x16x32_bf16 v[40:43], v[158:161], v[190:193], v[40:43]
	v_mfma_f32_16x16x32_bf16 v[32:35], v[150:153], v[198:201], v[32:35]
	v_mfma_f32_16x16x32_bf16 v[24:27], v[158:161], v[198:201], v[24:27]
	v_mfma_f32_16x16x32_bf16 v[16:19], v[150:153], v[206:209], v[16:19]
	v_mfma_f32_16x16x32_bf16 v[8:11], v[158:161], v[206:209], v[8:11]
	v_mfma_f32_16x16x32_bf16 v[60:63], v[154:157], v[186:189], v[60:63]
	v_mfma_f32_16x16x32_bf16 v[56:59], v[162:165], v[186:189], v[56:59]
	v_mfma_f32_16x16x32_bf16 v[48:51], v[154:157], v[194:197], v[48:51]
	v_mfma_f32_16x16x32_bf16 v[40:43], v[162:165], v[194:197], v[40:43]
	v_mfma_f32_16x16x32_bf16 v[32:35], v[154:157], v[202:205], v[32:35]
	v_mfma_f32_16x16x32_bf16 v[24:27], v[162:165], v[202:205], v[24:27]
	v_mfma_f32_16x16x32_bf16 v[16:19], v[154:157], v[210:213], v[16:19]
	v_mfma_f32_16x16x32_bf16 v[8:11], v[162:165], v[210:213], v[8:11]
	v_mfma_f32_16x16x32_bf16 v[52:55], v[166:169], v[182:185], v[52:55]
	v_mfma_f32_16x16x32_bf16 v[44:47], v[174:177], v[182:185], v[44:47]
	v_mfma_f32_16x16x32_bf16 v[36:39], v[166:169], v[190:193], v[36:39]
	v_mfma_f32_16x16x32_bf16 v[28:31], v[174:177], v[190:193], v[28:31]
	v_mfma_f32_16x16x32_bf16 v[20:23], v[166:169], v[198:201], v[20:23]
	v_mfma_f32_16x16x32_bf16 v[12:15], v[174:177], v[198:201], v[12:15]
	v_mfma_f32_16x16x32_bf16 v[4:7], v[166:169], v[206:209], v[4:7]
	v_mfma_f32_16x16x32_bf16 v[0:3], v[174:177], v[206:209], v[0:3]
	v_mfma_f32_16x16x32_bf16 v[52:55], v[170:173], v[186:189], v[52:55]
	v_mfma_f32_16x16x32_bf16 v[44:47], v[178:181], v[186:189], v[44:47]
	v_mfma_f32_16x16x32_bf16 v[36:39], v[170:173], v[194:197], v[36:39]
	v_mfma_f32_16x16x32_bf16 v[28:31], v[178:181], v[194:197], v[28:31]
	v_mfma_f32_16x16x32_bf16 v[20:23], v[170:173], v[202:205], v[20:23]
	v_mfma_f32_16x16x32_bf16 v[12:15], v[178:181], v[202:205], v[12:15]
	v_mfma_f32_16x16x32_bf16 v[4:7], v[170:173], v[210:213], v[4:7]
	s_setprio 0
	v_mfma_f32_16x16x32_bf16 v[0:3], v[178:181], v[210:213], v[0:3]
	s_barrier
; #define PG8_STAGE(bufoff, gbase, voff) do { _Pragma("unroll") for (int _i = 0; _i < 2; ++_i) \
;         __builtin_amdgcn_global_load_lds((const unsigned*)((const char*)(gbase) + (voff)[_i]), (LAS unsigned*)(lds + (bufoff) + ldsw + _i * 8192), 16, 0, 0); } while (0)
; #define PG8_LDA(dst, b, h) do { _Pragma("unroll") for (int m = 0; m < 4; ++m) _Pragma("unroll") for (int k = 0; k < 2; ++k) dst[m][k] = *(const LAS bf16x8*)(lds + PG8_SA(b, h) + aoff + m * 2048 + k * 1024); } while (0)
; #define PG8_LDB(dst, b, h) do { _Pragma("unroll") for (int n = 0; n < 2; ++n) _Pragma("unroll") for (int k = 0; k < 2; ++k) dst[n][k] = *(const LAS bf16x8*)(lds + PG8_SB(b, h) + boff + n * 2048 + k * 1024); } while (0)
; #define PG8_WAIT_V(n) asm volatile("s_waitcnt vmcnt(" #n ")" ::: "memory")
; #define PG8_WAIT_L(n) asm volatile("s_waitcnt lgkmcnt(" #n ")" ::: "memory")
; #define PG8_BAR __builtin_amdgcn_s_barrier()
; #define PG8_SCHED __builtin_amdgcn_sched_barrier(0)
; template <class Epi, bool FP8 = false>
; __device__ __forceinline__ void gemm_phase(LAS unsigned char* lds, const Gemm g, const StaticOrder& S_, const Epi& E, const int tid) {
;     ...
;             PG8_LDB(B0, 1, 0); PG8_LDB(B1, 1, 1); PG8_SCHED; PG8_LDA(At, 1, 0); PG8_STAGE(PG8_SA(0, 1), a2 + hstepA, voffA);
;             PG8_WAIT_V(8); PG8_WAIT_L(0); PG8_BAR; PG8_MMA(0, 0, At, B0); PG8_MMA(0, 1, At, B1); PG8_BAR; PG8_SCHED;
;             PG8_LDA(At, 1, 1); PG8_STAGE(PG8_SB(1, 0), b3, voffB); PG8_STAGE(PG8_SB(1, 1), b3 + hstepB, voffB); PG8_STAGE(PG8_SA(1, 0), a3, voffA);
;             PG8_WAIT_V(8); PG8_WAIT_L(0); PG8_BAR; PG8_MMA(1, 0, At, B0); PG8_MMA(1, 1, At, B1); PG8_BAR; PG8_SCHED;
;         }
;         if (wr == 0) PG8_BAR;
	s_add_i32 s78, 0, 0x18000
	v_add_u32_e32 v149, s78, v144
	s_add_i32 s79, 0, 0x1c000
	ds_read_b128 v[150:153], v149
	ds_read_b128 v[154:157], v149 offset:1024
	ds_read_b128 v[158:161], v149 offset:2048
	ds_read_b128 v[162:165], v149 offset:3072
	v_add_u32_e32 v149, s79, v144
	ds_read_b128 v[166:169], v149
	ds_read_b128 v[170:173], v149 offset:1024
	ds_read_b128 v[174:177], v149 offset:2048
	ds_read_b128 v[178:181], v149 offset:3072
	s_add_u32 s48, s54, 0x160000
	s_addc_u32 s49, s55, 0
	s_mov_b32 m0, s62
	ds_read_b128 v[182:185], v148 offset:32768
	ds_read_b128 v[186:189], v148 offset:33792
	ds_read_b128 v[190:193], v148 offset:34816
	ds_read_b128 v[194:197], v148 offset:35840
	ds_read_b128 v[198:201], v148 offset:36864
	ds_read_b128 v[202:205], v148 offset:37888
	ds_read_b128 v[206:209], v148 offset:38912
	ds_read_b128 v[210:213], v148 offset:39936
	global_load_lds_dwordx4 v128, s[48:49]
	s_mov_b32 m0, s63
	s_nop 0
	global_load_lds_dwordx4 v130, s[48:49]
	s_waitcnt vmcnt(8)
	s_waitcnt lgkmcnt(0)
	s_setprio 1
	s_barrier
	v_mfma_f32_16x16x32_bf16 v[124:127], v[150:153], v[182:185], v[124:127]
	v_mfma_f32_16x16x32_bf16 v[120:123], v[158:161], v[182:185], v[120:123]
	v_mfma_f32_16x16x32_bf16 v[112:115], v[150:153], v[190:193], v[112:115]
	v_mfma_f32_16x16x32_bf16 v[104:107], v[158:161], v[190:193], v[104:107]
	v_mfma_f32_16x16x32_bf16 v[96:99], v[150:153], v[198:201], v[96:99]
	v_mfma_f32_16x16x32_bf16 v[88:91], v[158:161], v[198:201], v[88:91]
	v_mfma_f32_16x16x32_bf16 v[80:83], v[150:153], v[206:209], v[80:83]
	v_mfma_f32_16x16x32_bf16 v[72:75], v[158:161], v[206:209], v[72:75]
	v_mfma_f32_16x16x32_bf16 v[124:127], v[154:157], v[186:189], v[124:127]
	v_mfma_f32_16x16x32_bf16 v[120:123], v[162:165], v[186:189], v[120:123]
	v_mfma_f32_16x16x32_bf16 v[112:115], v[154:157], v[194:197], v[112:115]
	v_mfma_f32_16x16x32_bf16 v[104:107], v[162:165], v[194:197], v[104:107]
	v_mfma_f32_16x16x32_bf16 v[96:99], v[154:157], v[202:205], v[96:99]
	v_mfma_f32_16x16x32_bf16 v[88:91], v[162:165], v[202:205], v[88:91]
	v_mfma_f32_16x16x32_bf16 v[80:83], v[154:157], v[210:213], v[80:83]
	v_mfma_f32_16x16x32_bf16 v[72:75], v[162:165], v[210:213], v[72:75]
	v_mfma_f32_16x16x32_bf16 v[116:119], v[166:169], v[182:185], v[116:119]
	v_mfma_f32_16x16x32_bf16 v[108:111], v[174:177], v[182:185], v[108:111]
	v_mfma_f32_16x16x32_bf16 v[100:103], v[166:169], v[190:193], v[100:103]
	v_mfma_f32_16x16x32_bf16 v[92:95], v[174:177], v[190:193], v[92:95]
	v_mfma_f32_16x16x32_bf16 v[84:87], v[166:169], v[198:201], v[84:87]
	v_mfma_f32_16x16x32_bf16 v[76:79], v[174:177], v[198:201], v[76:79]
	v_mfma_f32_16x16x32_bf16 v[68:71], v[166:169], v[206:209], v[68:71]
	v_mfma_f32_16x16x32_bf16 v[64:67], v[174:177], v[206:209], v[64:67]
	v_mfma_f32_16x16x32_bf16 v[116:119], v[170:173], v[186:189], v[116:119]
	v_mfma_f32_16x16x32_bf16 v[108:111], v[178:181], v[186:189], v[108:111]
	v_mfma_f32_16x16x32_bf16 v[100:103], v[170:173], v[194:197], v[100:103]
	v_mfma_f32_16x16x32_bf16 v[92:95], v[178:181], v[194:197], v[92:95]
	v_mfma_f32_16x16x32_bf16 v[84:87], v[170:173], v[202:205], v[84:87]
	v_mfma_f32_16x16x32_bf16 v[76:79], v[178:181], v[202:205], v[76:79]
	v_mfma_f32_16x16x32_bf16 v[68:71], v[170:173], v[210:213], v[68:71]
	s_setprio 0
	v_mfma_f32_16x16x32_bf16 v[64:67], v[178:181], v[210:213], v[64:67]
	s_barrier
	s_add_i32 s48, s78, s59
	s_mov_b32 m0, s48
	ds_read_b128 v[182:185], v148 offset:49152
	ds_read_b128 v[186:189], v148 offset:50176
	ds_read_b128 v[190:193], v148 offset:51200
	ds_read_b128 v[194:197], v148 offset:52224
	ds_read_b128 v[198:201], v148 offset:53248
	ds_read_b128 v[202:205], v148 offset:54272
	ds_read_b128 v[206:209], v148 offset:55296
	ds_read_b128 v[210:213], v148 offset:56320
	global_load_lds_dwordx4 v128, s[98:99]
	s_add_i32 m0, s48, 0x2000
	s_add_u32 s48, s52, 0x160080
	s_addc_u32 s49, s53, 0
	s_add_i32 s52, s79, s59
	global_load_lds_dwordx4 v130, s[98:99]
	s_mov_b32 m0, s52
	s_nop 0
	global_load_lds_dwordx4 v128, s[48:49]
	s_add_i32 m0, s52, 0x2000
	s_nop 0
	global_load_lds_dwordx4 v130, s[48:49]
	s_mov_b32 m0, s68
	s_nop 0
	global_load_lds_dwordx4 v128, s[100:101]
	s_mov_b32 m0, s69
	s_nop 0
	global_load_lds_dwordx4 v130, s[100:101]
	s_waitcnt vmcnt(8)
	s_waitcnt lgkmcnt(0)
	s_setprio 1
	s_barrier
	v_mfma_f32_16x16x32_bf16 v[60:63], v[150:153], v[182:185], v[60:63]
	v_mfma_f32_16x16x32_bf16 v[56:59], v[158:161], v[182:185], v[56:59]
	v_mfma_f32_16x16x32_bf16 v[48:51], v[150:153], v[190:193], v[48:51]
	v_mfma_f32_16x16x32_bf16 v[40:43], v[158:161], v[190:193], v[40:43]
	v_mfma_f32_16x16x32_bf16 v[32:35], v[150:153], v[198:201], v[32:35]
	v_mfma_f32_16x16x32_bf16 v[24:27], v[158:161], v[198:201], v[24:27]
	v_mfma_f32_16x16x32_bf16 v[16:19], v[150:153], v[206:209], v[16:19]
	v_mfma_f32_16x16x32_bf16 v[8:11], v[158:161], v[206:209], v[8:11]
	v_mfma_f32_16x16x32_bf16 v[60:63], v[154:157], v[186:189], v[60:63]
	v_mfma_f32_16x16x32_bf16 v[56:59], v[162:165], v[186:189], v[56:59]
	v_mfma_f32_16x16x32_bf16 v[48:51], v[154:157], v[194:197], v[48:51]
	v_mfma_f32_16x16x32_bf16 v[40:43], v[162:165], v[194:197], v[40:43]
	v_mfma_f32_16x16x32_bf16 v[32:35], v[154:157], v[202:205], v[32:35]
	v_mfma_f32_16x16x32_bf16 v[24:27], v[162:165], v[202:205], v[24:27]
	v_mfma_f32_16x16x32_bf16 v[16:19], v[154:157], v[210:213], v[16:19]
	v_mfma_f32_16x16x32_bf16 v[8:11], v[162:165], v[210:213], v[8:11]
	v_mfma_f32_16x16x32_bf16 v[52:55], v[166:169], v[182:185], v[52:55]
	v_mfma_f32_16x16x32_bf16 v[44:47], v[174:177], v[182:185], v[44:47]
	v_mfma_f32_16x16x32_bf16 v[36:39], v[166:169], v[190:193], v[36:39]
	v_mfma_f32_16x16x32_bf16 v[28:31], v[174:177], v[190:193], v[28:31]
	v_mfma_f32_16x16x32_bf16 v[20:23], v[166:169], v[198:201], v[20:23]
	v_mfma_f32_16x16x32_bf16 v[12:15], v[174:177], v[198:201], v[12:15]
	v_mfma_f32_16x16x32_bf16 v[4:7], v[166:169], v[206:209], v[4:7]
	v_mfma_f32_16x16x32_bf16 v[0:3], v[174:177], v[206:209], v[0:3]
	v_mfma_f32_16x16x32_bf16 v[52:55], v[170:173], v[186:189], v[52:55]
	v_mfma_f32_16x16x32_bf16 v[44:47], v[178:181], v[186:189], v[44:47]
	v_mfma_f32_16x16x32_bf16 v[36:39], v[170:173], v[194:197], v[36:39]
	v_mfma_f32_16x16x32_bf16 v[28:31], v[178:181], v[194:197], v[28:31]
	v_mfma_f32_16x16x32_bf16 v[20:23], v[170:173], v[202:205], v[20:23]
	v_mfma_f32_16x16x32_bf16 v[12:15], v[178:181], v[202:205], v[12:15]
	v_mfma_f32_16x16x32_bf16 v[4:7], v[170:173], v[210:213], v[4:7]
	s_setprio 0
	v_mfma_f32_16x16x32_bf16 v[0:3], v[178:181], v[210:213], v[0:3]
	s_barrier
	s_add_i32 s77, s77, 2
	s_add_u32 s75, s75, 0x100
	s_addc_u32 s76, s76, 0
	s_cmpk_gt_u32 s77, 0x55
	s_mov_b64 s[48:49], s[50:51]
	s_cbranch_scc0 .LBB0_319
	s_and_b64 vcc, exec, s[16:17]
	s_cbranch_vccz .LBB0_322
	s_barrier

; #define PG8_STAGE(bufoff, gbase, voff) do { _Pragma("unroll") for (int _i = 0; _i < 2; ++_i) \
;         __builtin_amdgcn_global_load_lds((const unsigned*)((const char*)(gbase) + (voff)[_i]), (LAS unsigned*)(lds + (bufoff) + ldsw + _i * 8192), 16, 0, 0); } while (0)
; #define PG8_LDA(dst, b, h) do { _Pragma("unroll") for (int m = 0; m < 4; ++m) _Pragma("unroll") for (int k = 0; k < 2; ++k) dst[m][k] = *(const LAS bf16x8*)(lds + PG8_SA(b, h) + aoff + m * 2048 + k * 1024); } while (0)
; #define PG8_LDB(dst, b, h) do { _Pragma("unroll") for (int n = 0; n < 2; ++n) _Pragma("unroll") for (int k = 0; k < 2; ++k) dst[n][k] = *(const LAS bf16x8*)(lds + PG8_SB(b, h) + boff + n * 2048 + k * 1024); } while (0)
; #define PG8_WAIT_V(n) asm volatile("s_waitcnt vmcnt(" #n ")" ::: "memory")
; #define PG8_WAIT_L(n) asm volatile("s_waitcnt lgkmcnt(" #n ")" ::: "memory")
; #define PG8_BAR __builtin_amdgcn_s_barrier()
; #define PG8_SCHED __builtin_amdgcn_sched_barrier(0)
; template <class Epi, bool FP8 = false>
; __device__ __forceinline__ void gemm_phase(LAS unsigned char* lds, const Gemm g, const StaticOrder& S_, const Epi& E, const int tid) {
;     ...
;             const bool last = (t == nt - 2);
;             const char* a1 = cA + (size_t)(t + 1) * kstep;
;             const char* a2 = last ? nA : cA + (size_t)(t + 2) * kstep; const char* b2 = last ? nB : cB + (size_t)(t + 2) * kstep;
;             const char* a3 = a2 + kstep; const char* b3 = b2 + kstep;
;             PG8_LDB(B0, 0, 0); PG8_LDB(B1, 0, 1); PG8_SCHED; PG8_LDA(At, 0, 0); PG8_STAGE(PG8_SA(1, 1), a1 + hstepA, voffA);
;             PG8_WAIT_V(8); PG8_WAIT_L(0); PG8_BAR; PG8_MMA(0, 0, At, B0); PG8_MMA(0, 1, At, B1); PG8_BAR; PG8_SCHED;
;             PG8_LDA(At, 0, 1); PG8_STAGE(PG8_SB(0, 0), b2, voffB); PG8_STAGE(PG8_SB(0, 1), b2 + hstepB, voffB); PG8_STAGE(PG8_SA(0, 0), a2, voffA);
;             PG8_WAIT_V(8); PG8_WAIT_L(0); PG8_BAR; PG8_MMA(1, 0, At, B0); PG8_MMA(1, 1, At, B1); PG8_BAR; PG8_SCHED;
.LBB0_457:
	ds_read_b128 v[128:131], v190
	ds_read_b128 v[132:135], v190 offset:1024
	ds_read_b128 v[136:139], v190 offset:2048
	ds_read_b128 v[140:143], v190 offset:3072
	ds_read_b128 v[182:185], v192
	ds_read_b128 v[194:197], v192 offset:1024
	ds_read_b128 v[198:201], v192 offset:2048
	ds_read_b128 v[202:205], v192 offset:3072
	s_add_u32 s56, s54, 0xfff80080
	s_addc_u32 s57, s55, -1
	s_cmp_eq_u32 s61, 28
	s_cselect_b32 s59, s7, s57
	s_cselect_b32 s58, s42, s56
	s_cselect_b32 s57, s27, s60
	s_cselect_b32 s56, s43, s49
	s_add_i32 m0, s71, 0xc000
	ds_read_b128 v[206:209], v191
	ds_read_b128 v[210:213], v191 offset:1024
	ds_read_b128 v[214:217], v191 offset:2048
	ds_read_b128 v[218:221], v191 offset:3072
	ds_read_b128 v[222:225], v191 offset:4096
	ds_read_b128 v[226:229], v191 offset:5120
	ds_read_b128 v[230:233], v191 offset:6144
	ds_read_b128 v[234:237], v191 offset:7168
	global_load_lds_dwordx4 v174, s[54:55]
	s_add_i32 m0, s71, 0xe000
	s_nop 0
	global_load_lds_dwordx4 v176, s[54:55]
	s_waitcnt vmcnt(8)
	s_waitcnt lgkmcnt(0)
	s_setprio 1
	s_barrier
	v_mfma_f32_16x16x32_bf16 v[124:127], v[128:131], v[206:209], v[124:127]
	v_mfma_f32_16x16x32_bf16 v[120:123], v[136:139], v[206:209], v[120:123]
	v_mfma_f32_16x16x32_bf16 v[108:111], v[128:131], v[214:217], v[108:111]
	v_mfma_f32_16x16x32_bf16 v[104:107], v[136:139], v[214:217], v[104:107]
	v_mfma_f32_16x16x32_bf16 v[92:95], v[128:131], v[222:225], v[92:95]
	v_mfma_f32_16x16x32_bf16 v[88:91], v[136:139], v[222:225], v[88:91]
	v_mfma_f32_16x16x32_bf16 v[76:79], v[128:131], v[230:233], v[76:79]
	v_mfma_f32_16x16x32_bf16 v[72:75], v[136:139], v[230:233], v[72:75]
	v_mfma_f32_16x16x32_bf16 v[124:127], v[132:135], v[210:213], v[124:127]
	v_mfma_f32_16x16x32_bf16 v[120:123], v[140:143], v[210:213], v[120:123]
	v_mfma_f32_16x16x32_bf16 v[108:111], v[132:135], v[218:221], v[108:111]
	v_mfma_f32_16x16x32_bf16 v[104:107], v[140:143], v[218:221], v[104:107]
	v_mfma_f32_16x16x32_bf16 v[92:95], v[132:135], v[226:229], v[92:95]
	v_mfma_f32_16x16x32_bf16 v[88:91], v[140:143], v[226:229], v[88:91]
	v_mfma_f32_16x16x32_bf16 v[76:79], v[132:135], v[234:237], v[76:79]
	v_mfma_f32_16x16x32_bf16 v[72:75], v[140:143], v[234:237], v[72:75]
	v_mfma_f32_16x16x32_bf16 v[116:119], v[182:185], v[206:209], v[116:119]
	v_mfma_f32_16x16x32_bf16 v[112:115], v[198:201], v[206:209], v[112:115]
	v_mfma_f32_16x16x32_bf16 v[100:103], v[182:185], v[214:217], v[100:103]
	v_mfma_f32_16x16x32_bf16 v[96:99], v[198:201], v[214:217], v[96:99]
	v_mfma_f32_16x16x32_bf16 v[84:87], v[182:185], v[222:225], v[84:87]
	v_mfma_f32_16x16x32_bf16 v[80:83], v[198:201], v[222:225], v[80:83]
	v_mfma_f32_16x16x32_bf16 v[68:71], v[182:185], v[230:233], v[68:71]
	v_mfma_f32_16x16x32_bf16 v[64:67], v[198:201], v[230:233], v[64:67]
	v_mfma_f32_16x16x32_bf16 v[116:119], v[194:197], v[210:213], v[116:119]
	v_mfma_f32_16x16x32_bf16 v[112:115], v[202:205], v[210:213], v[112:115]
	v_mfma_f32_16x16x32_bf16 v[100:103], v[194:197], v[218:221], v[100:103]
	v_mfma_f32_16x16x32_bf16 v[96:99], v[202:205], v[218:221], v[96:99]
	v_mfma_f32_16x16x32_bf16 v[84:87], v[194:197], v[226:229], v[84:87]
	v_mfma_f32_16x16x32_bf16 v[80:83], v[202:205], v[226:229], v[80:83]
	v_mfma_f32_16x16x32_bf16 v[68:71], v[194:197], v[234:237], v[68:71]
	s_setprio 0
	v_mfma_f32_16x16x32_bf16 v[64:67], v[202:205], v[234:237], v[64:67]
	s_barrier
	s_add_u32 s98, s56, s14
	s_addc_u32 s99, s57, s15
	s_add_u32 s100, s58, s14
	s_addc_u32 s101, s59, s15
	s_add_i32 s62, s85, s70
	s_mov_b32 m0, s62
	ds_read_b128 v[206:209], v191 offset:16384
	ds_read_b128 v[210:213], v191 offset:17408
	ds_read_b128 v[214:217], v191 offset:18432
	ds_read_b128 v[218:221], v191 offset:19456
	ds_read_b128 v[222:225], v191 offset:20480
	ds_read_b128 v[226:229], v191 offset:21504
	ds_read_b128 v[230:233], v191 offset:22528
	ds_read_b128 v[234:237], v191 offset:23552
	global_load_lds_dwordx4 v146, s[56:57]
	s_add_i32 m0, s62, 0x2000
	s_add_u32 s62, s56, 0x80000
	s_addc_u32 s63, s57, 0
	s_add_i32 s66, s86, s70
	global_load_lds_dwordx4 v150, s[56:57]
	s_mov_b32 m0, s66
	s_nop 0
	global_load_lds_dwordx4 v146, s[62:63]
	s_add_i32 m0, s66, 0x2000
	s_nop 0
	global_load_lds_dwordx4 v150, s[62:63]
	s_mov_b32 m0, s71
	s_nop 0
	global_load_lds_dwordx4 v144, s[58:59]
	s_mov_b32 m0, s72
	s_nop 0
	global_load_lds_dwordx4 v148, s[58:59]
	s_waitcnt vmcnt(8)
	s_waitcnt lgkmcnt(0)
	s_setprio 1
	s_barrier
	v_mfma_f32_16x16x32_bf16 v[60:63], v[128:131], v[206:209], v[60:63]
	v_mfma_f32_16x16x32_bf16 v[56:59], v[136:139], v[206:209], v[56:59]
	v_mfma_f32_16x16x32_bf16 v[44:47], v[128:131], v[214:217], v[44:47]
	v_mfma_f32_16x16x32_bf16 v[40:43], v[136:139], v[214:217], v[40:43]
	v_mfma_f32_16x16x32_bf16 v[28:31], v[128:131], v[222:225], v[28:31]
	v_mfma_f32_16x16x32_bf16 v[24:27], v[136:139], v[222:225], v[24:27]
	v_mfma_f32_16x16x32_bf16 v[12:15], v[128:131], v[230:233], v[12:15]
	v_mfma_f32_16x16x32_bf16 v[8:11], v[136:139], v[230:233], v[8:11]
	v_mfma_f32_16x16x32_bf16 v[60:63], v[132:135], v[210:213], v[60:63]
	v_mfma_f32_16x16x32_bf16 v[56:59], v[140:143], v[210:213], v[56:59]
	v_mfma_f32_16x16x32_bf16 v[44:47], v[132:135], v[218:221], v[44:47]
	v_mfma_f32_16x16x32_bf16 v[40:43], v[140:143], v[218:221], v[40:43]
	v_mfma_f32_16x16x32_bf16 v[28:31], v[132:135], v[226:229], v[28:31]
	v_mfma_f32_16x16x32_bf16 v[24:27], v[140:143], v[226:229], v[24:27]
	v_mfma_f32_16x16x32_bf16 v[12:15], v[132:135], v[234:237], v[12:15]
	v_mfma_f32_16x16x32_bf16 v[8:11], v[140:143], v[234:237], v[8:11]
	v_mfma_f32_16x16x32_bf16 v[52:55], v[182:185], v[206:209], v[52:55]
	v_mfma_f32_16x16x32_bf16 v[48:51], v[198:201], v[206:209], v[48:51]
	v_mfma_f32_16x16x32_bf16 v[36:39], v[182:185], v[214:217], v[36:39]
	v_mfma_f32_16x16x32_bf16 v[32:35], v[198:201], v[214:217], v[32:35]
	v_mfma_f32_16x16x32_bf16 v[20:23], v[182:185], v[222:225], v[20:23]
	v_mfma_f32_16x16x32_bf16 v[16:19], v[198:201], v[222:225], v[16:19]
	v_mfma_f32_16x16x32_bf16 v[4:7], v[182:185], v[230:233], v[4:7]
	v_mfma_f32_16x16x32_bf16 v[0:3], v[198:201], v[230:233], v[0:3]
	v_mfma_f32_16x16x32_bf16 v[52:55], v[194:197], v[210:213], v[52:55]
	v_mfma_f32_16x16x32_bf16 v[48:51], v[202:205], v[210:213], v[48:51]
	v_mfma_f32_16x16x32_bf16 v[36:39], v[194:197], v[218:221], v[36:39]
	v_mfma_f32_16x16x32_bf16 v[32:35], v[202:205], v[218:221], v[32:35]
	v_mfma_f32_16x16x32_bf16 v[20:23], v[194:197], v[226:229], v[20:23]
	v_mfma_f32_16x16x32_bf16 v[16:19], v[202:205], v[226:229], v[16:19]
	v_mfma_f32_16x16x32_bf16 v[4:7], v[194:197], v[234:237], v[4:7]
	s_setprio 0
	v_mfma_f32_16x16x32_bf16 v[0:3], v[202:205], v[234:237], v[0:3]
	s_barrier
; #define PG8_STAGE(bufoff, gbase, voff) do { _Pragma("unroll") for (int _i = 0; _i < 2; ++_i) \
;         __builtin_amdgcn_global_load_lds((const unsigned*)((const char*)(gbase) + (voff)[_i]), (LAS unsigned*)(lds + (bufoff) + ldsw + _i * 8192), 16, 0, 0); } while (0)
; #define PG8_LDA(dst, b, h) do { _Pragma("unroll") for (int m = 0; m < 4; ++m) _Pragma("unroll") for (int k = 0; k < 2; ++k) dst[m][k] = *(const LAS bf16x8*)(lds + PG8_SA(b, h) + aoff + m * 2048 + k * 1024); } while (0)
; #define PG8_LDB(dst, b, h) do { _Pragma("unroll") for (int n = 0; n < 2; ++n) _Pragma("unroll") for (int k = 0; k < 2; ++k) dst[n][k] = *(const LAS bf16x8*)(lds + PG8_SB(b, h) + boff + n * 2048 + k * 1024); } while (0)
; #define PG8_WAIT_V(n) asm volatile("s_waitcnt vmcnt(" #n ")" ::: "memory")
; #define PG8_WAIT_L(n) asm volatile("s_waitcnt lgkmcnt(" #n ")" ::: "memory")
; #define PG8_BAR __builtin_amdgcn_s_barrier()
; #define PG8_SCHED __builtin_amdgcn_sched_barrier(0)
; template <class Epi, bool FP8 = false>
; __device__ __forceinline__ void gemm_phase(LAS unsigned char* lds, const Gemm g, const StaticOrder& S_, const Epi& E, const int tid) {
;     ...
;             PG8_LDB(B0, 1, 0); PG8_LDB(B1, 1, 1); PG8_SCHED; PG8_LDA(At, 1, 0); PG8_STAGE(PG8_SA(0, 1), a2 + hstepA, voffA);
;             PG8_WAIT_V(8); PG8_WAIT_L(0); PG8_BAR; PG8_MMA(0, 0, At, B0); PG8_MMA(0, 1, At, B1); PG8_BAR; PG8_SCHED;
;             PG8_LDA(At, 1, 1); PG8_STAGE(PG8_SB(1, 0), b3, voffB); PG8_STAGE(PG8_SB(1, 1), b3 + hstepB, voffB); PG8_STAGE(PG8_SA(1, 0), a3, voffA);
;             PG8_WAIT_V(8); PG8_WAIT_L(0); PG8_BAR; PG8_MMA(1, 0, At, B0); PG8_MMA(1, 1, At, B1); PG8_BAR; PG8_SCHED;
;         }
;         if (wr == 0) PG8_BAR;
	s_add_i32 s62, 0, 0x18000
	s_add_i32 s63, 0, 0x1c000
	v_add_u32_e32 v140, s62, v163
	v_add_u32_e32 v152, s63, v163
	ds_read_b128 v[128:131], v140
	ds_read_b128 v[132:135], v140 offset:1024
	ds_read_b128 v[136:139], v140 offset:2048
	ds_read_b128 v[140:143], v140 offset:3072
	ds_read_b128 v[182:185], v152
	ds_read_b128 v[194:197], v152 offset:1024
	ds_read_b128 v[198:201], v152 offset:2048
	ds_read_b128 v[202:205], v152 offset:3072
	s_add_u32 s58, s58, 0x80000
	s_addc_u32 s59, s59, 0
	s_mov_b32 m0, s73
	ds_read_b128 v[206:209], v191 offset:32768
	ds_read_b128 v[210:213], v191 offset:33792
	ds_read_b128 v[214:217], v191 offset:34816
	ds_read_b128 v[218:221], v191 offset:35840
	ds_read_b128 v[222:225], v191 offset:36864
	ds_read_b128 v[226:229], v191 offset:37888
	ds_read_b128 v[230:233], v191 offset:38912
	ds_read_b128 v[234:237], v191 offset:39936
	global_load_lds_dwordx4 v144, s[58:59]
	s_mov_b32 m0, s74
	s_nop 0
	global_load_lds_dwordx4 v148, s[58:59]
	s_waitcnt vmcnt(8)
	s_waitcnt lgkmcnt(0)
	s_setprio 1
	s_barrier
	v_mfma_f32_16x16x32_bf16 v[124:127], v[128:131], v[206:209], v[124:127]
	v_mfma_f32_16x16x32_bf16 v[120:123], v[136:139], v[206:209], v[120:123]
	v_mfma_f32_16x16x32_bf16 v[108:111], v[128:131], v[214:217], v[108:111]
	v_mfma_f32_16x16x32_bf16 v[104:107], v[136:139], v[214:217], v[104:107]
	v_mfma_f32_16x16x32_bf16 v[92:95], v[128:131], v[222:225], v[92:95]
	v_mfma_f32_16x16x32_bf16 v[88:91], v[136:139], v[222:225], v[88:91]
	v_mfma_f32_16x16x32_bf16 v[76:79], v[128:131], v[230:233], v[76:79]
	v_mfma_f32_16x16x32_bf16 v[72:75], v[136:139], v[230:233], v[72:75]
	v_mfma_f32_16x16x32_bf16 v[124:127], v[132:135], v[210:213], v[124:127]
	v_mfma_f32_16x16x32_bf16 v[120:123], v[140:143], v[210:213], v[120:123]
	v_mfma_f32_16x16x32_bf16 v[108:111], v[132:135], v[218:221], v[108:111]
	v_mfma_f32_16x16x32_bf16 v[104:107], v[140:143], v[218:221], v[104:107]
	v_mfma_f32_16x16x32_bf16 v[92:95], v[132:135], v[226:229], v[92:95]
	v_mfma_f32_16x16x32_bf16 v[88:91], v[140:143], v[226:229], v[88:91]
	v_mfma_f32_16x16x32_bf16 v[76:79], v[132:135], v[234:237], v[76:79]
	v_mfma_f32_16x16x32_bf16 v[72:75], v[140:143], v[234:237], v[72:75]
	v_mfma_f32_16x16x32_bf16 v[116:119], v[182:185], v[206:209], v[116:119]
	v_mfma_f32_16x16x32_bf16 v[112:115], v[198:201], v[206:209], v[112:115]
	v_mfma_f32_16x16x32_bf16 v[100:103], v[182:185], v[214:217], v[100:103]
	v_mfma_f32_16x16x32_bf16 v[96:99], v[198:201], v[214:217], v[96:99]
	v_mfma_f32_16x16x32_bf16 v[84:87], v[182:185], v[222:225], v[84:87]
	v_mfma_f32_16x16x32_bf16 v[80:83], v[198:201], v[222:225], v[80:83]
	v_mfma_f32_16x16x32_bf16 v[68:71], v[182:185], v[230:233], v[68:71]
	v_mfma_f32_16x16x32_bf16 v[64:67], v[198:201], v[230:233], v[64:67]
	v_mfma_f32_16x16x32_bf16 v[116:119], v[194:197], v[210:213], v[116:119]
	v_mfma_f32_16x16x32_bf16 v[112:115], v[202:205], v[210:213], v[112:115]
	v_mfma_f32_16x16x32_bf16 v[100:103], v[194:197], v[218:221], v[100:103]
	v_mfma_f32_16x16x32_bf16 v[96:99], v[202:205], v[218:221], v[96:99]
	v_mfma_f32_16x16x32_bf16 v[84:87], v[194:197], v[226:229], v[84:87]
	v_mfma_f32_16x16x32_bf16 v[80:83], v[202:205], v[226:229], v[80:83]
	v_mfma_f32_16x16x32_bf16 v[68:71], v[194:197], v[234:237], v[68:71]
	s_setprio 0
	v_mfma_f32_16x16x32_bf16 v[64:67], v[202:205], v[234:237], v[64:67]
	s_barrier
	s_add_i32 s58, s62, s70
	s_mov_b32 m0, s58
	ds_read_b128 v[206:209], v191 offset:49152
	ds_read_b128 v[210:213], v191 offset:50176
	ds_read_b128 v[214:217], v191 offset:51200
	ds_read_b128 v[218:221], v191 offset:52224
	ds_read_b128 v[222:225], v191 offset:53248
	ds_read_b128 v[226:229], v191 offset:54272
	ds_read_b128 v[230:233], v191 offset:55296
	ds_read_b128 v[234:237], v191 offset:56320
	global_load_lds_dwordx4 v146, s[98:99]
	s_add_i32 m0, s58, 0x2000
	s_add_u32 s56, s56, 0x80080
	s_addc_u32 s57, s57, 0
	s_add_i32 s58, s63, s70
	global_load_lds_dwordx4 v150, s[98:99]
	s_mov_b32 m0, s58
	s_nop 0
	global_load_lds_dwordx4 v146, s[56:57]
	s_add_i32 m0, s58, 0x2000
	s_nop 0
	global_load_lds_dwordx4 v150, s[56:57]
	s_mov_b32 m0, s79
	s_nop 0
	global_load_lds_dwordx4 v144, s[100:101]
	s_mov_b32 m0, s80
	s_nop 0
	global_load_lds_dwordx4 v148, s[100:101]
	s_waitcnt vmcnt(8)
	s_waitcnt lgkmcnt(0)
	s_setprio 1
	s_barrier
	v_mfma_f32_16x16x32_bf16 v[60:63], v[128:131], v[206:209], v[60:63]
	v_mfma_f32_16x16x32_bf16 v[56:59], v[136:139], v[206:209], v[56:59]
	v_mfma_f32_16x16x32_bf16 v[44:47], v[128:131], v[214:217], v[44:47]
	v_mfma_f32_16x16x32_bf16 v[40:43], v[136:139], v[214:217], v[40:43]
	v_mfma_f32_16x16x32_bf16 v[28:31], v[128:131], v[222:225], v[28:31]
	v_mfma_f32_16x16x32_bf16 v[24:27], v[136:139], v[222:225], v[24:27]
	v_mfma_f32_16x16x32_bf16 v[12:15], v[128:131], v[230:233], v[12:15]
	v_mfma_f32_16x16x32_bf16 v[8:11], v[136:139], v[230:233], v[8:11]
	v_mfma_f32_16x16x32_bf16 v[60:63], v[132:135], v[210:213], v[60:63]
	v_mfma_f32_16x16x32_bf16 v[56:59], v[140:143], v[210:213], v[56:59]
	v_mfma_f32_16x16x32_bf16 v[44:47], v[132:135], v[218:221], v[44:47]
	v_mfma_f32_16x16x32_bf16 v[40:43], v[140:143], v[218:221], v[40:43]
	v_mfma_f32_16x16x32_bf16 v[28:31], v[132:135], v[226:229], v[28:31]
	v_mfma_f32_16x16x32_bf16 v[24:27], v[140:143], v[226:229], v[24:27]
	v_mfma_f32_16x16x32_bf16 v[12:15], v[132:135], v[234:237], v[12:15]
	v_mfma_f32_16x16x32_bf16 v[8:11], v[140:143], v[234:237], v[8:11]
	v_mfma_f32_16x16x32_bf16 v[52:55], v[182:185], v[206:209], v[52:55]
	v_mfma_f32_16x16x32_bf16 v[48:51], v[198:201], v[206:209], v[48:51]
	v_mfma_f32_16x16x32_bf16 v[36:39], v[182:185], v[214:217], v[36:39]
	v_mfma_f32_16x16x32_bf16 v[32:35], v[198:201], v[214:217], v[32:35]
	v_mfma_f32_16x16x32_bf16 v[20:23], v[182:185], v[222:225], v[20:23]
	v_mfma_f32_16x16x32_bf16 v[16:19], v[198:201], v[222:225], v[16:19]
	v_mfma_f32_16x16x32_bf16 v[4:7], v[182:185], v[230:233], v[4:7]
	v_mfma_f32_16x16x32_bf16 v[0:3], v[198:201], v[230:233], v[0:3]
	v_mfma_f32_16x16x32_bf16 v[52:55], v[194:197], v[210:213], v[52:55]
	v_mfma_f32_16x16x32_bf16 v[48:51], v[202:205], v[210:213], v[48:51]
	v_mfma_f32_16x16x32_bf16 v[36:39], v[194:197], v[218:221], v[36:39]
	v_mfma_f32_16x16x32_bf16 v[32:35], v[202:205], v[218:221], v[32:35]
	v_mfma_f32_16x16x32_bf16 v[20:23], v[194:197], v[226:229], v[20:23]
	v_mfma_f32_16x16x32_bf16 v[16:19], v[202:205], v[226:229], v[16:19]
	v_mfma_f32_16x16x32_bf16 v[4:7], v[194:197], v[234:237], v[4:7]
	s_setprio 0
	v_mfma_f32_16x16x32_bf16 v[0:3], v[202:205], v[234:237], v[0:3]
	s_barrier
	s_add_i32 s61, s61, 2
	s_add_u32 s54, s54, 0x100
	s_addc_u32 s55, s55, 0
	s_add_u32 s49, s49, 0x100
	s_addc_u32 s60, s60, 0
	s_cmp_gt_u32 s61, 29
	s_cbranch_scc0 .LBB0_457
	s_and_b64 vcc, exec, s[16:17]
	s_cbranch_vccz .LBB0_460
	s_barrier

; #define PG8_STAGE(bufoff, gbase, voff) do { _Pragma("unroll") for (int _i = 0; _i < 2; ++_i) \
;         __builtin_amdgcn_global_load_lds((const unsigned*)((const char*)(gbase) + (voff)[_i]), (LAS unsigned*)(lds + (bufoff) + ldsw + _i * 8192), 16, 0, 0); } while (0)
; #define PG8_LDA(dst, b, h) do { _Pragma("unroll") for (int m = 0; m < 4; ++m) _Pragma("unroll") for (int k = 0; k < 2; ++k) dst[m][k] = *(const LAS bf16x8*)(lds + PG8_SA(b, h) + aoff + m * 2048 + k * 1024); } while (0)
; #define PG8_LDB(dst, b, h) do { _Pragma("unroll") for (int n = 0; n < 2; ++n) _Pragma("unroll") for (int k = 0; k < 2; ++k) dst[n][k] = *(const LAS bf16x8*)(lds + PG8_SB(b, h) + boff + n * 2048 + k * 1024); } while (0)
; #define PG8_WAIT_V(n) asm volatile("s_waitcnt vmcnt(" #n ")" ::: "memory")
; #define PG8_WAIT_L(n) asm volatile("s_waitcnt lgkmcnt(" #n ")" ::: "memory")
; #define PG8_BAR __builtin_amdgcn_s_barrier()
; #define PG8_SCHED __builtin_amdgcn_sched_barrier(0)
; template <class Epi, bool FP8 = false>
; __device__ __forceinline__ void gemm_phase(LAS unsigned char* lds, const Gemm g, const StaticOrder& S_, const Epi& E, const int tid) {
;     ...
;             const bool last = (t == nt - 2);
;             const char* a1 = cA + (size_t)(t + 1) * kstep;
;             const char* a2 = last ? nA : cA + (size_t)(t + 2) * kstep; const char* b2 = last ? nB : cB + (size_t)(t + 2) * kstep;
;             const char* a3 = a2 + kstep; const char* b3 = b2 + kstep;
;             PG8_LDB(B0, 0, 0); PG8_LDB(B1, 0, 1); PG8_SCHED; PG8_LDA(At, 0, 0); PG8_STAGE(PG8_SA(1, 1), a1 + hstepA, voffA);
;             PG8_WAIT_V(8); PG8_WAIT_L(0); PG8_BAR; PG8_MMA(0, 0, At, B0); PG8_MMA(0, 1, At, B1); PG8_BAR; PG8_SCHED;
;             PG8_LDA(At, 0, 1); PG8_STAGE(PG8_SB(0, 0), b2, voffB); PG8_STAGE(PG8_SB(0, 1), b2 + hstepB, voffB); PG8_STAGE(PG8_SA(0, 0), a2, voffA);
;             PG8_WAIT_V(8); PG8_WAIT_L(0); PG8_BAR; PG8_MMA(1, 0, At, B0); PG8_MMA(1, 1, At, B1); PG8_BAR; PG8_SCHED;
.LBB0_596:
	ds_read_b128 v[156:159], v197 offset:1024
	ds_read_b128 v[152:155], v197
	ds_read_b128 v[148:151], v197 offset:3072
	ds_read_b128 v[144:147], v197 offset:2048
	ds_read_b128 v[140:143], v198 offset:1024
	ds_read_b128 v[136:139], v198
	ds_read_b128 v[132:135], v198 offset:3072
	ds_read_b128 v[128:131], v198 offset:2048
	s_add_u32 s54, s52, 0xfffc0080
	s_addc_u32 s55, s53, -1
	s_cmp_eq_u32 s85, 12
	s_cselect_b32 s57, s27, s55
	s_cselect_b32 s56, s42, s54
	s_cselect_b32 s55, s25, s84
	s_cselect_b32 s54, s43, s66
	s_add_i32 m0, s63, 0xc000
	ds_read_b128 v[186:189], v199
	ds_read_b128 v[190:193], v199 offset:1024
	ds_read_b128 v[200:203], v199 offset:2048
	ds_read_b128 v[204:207], v199 offset:3072
	ds_read_b128 v[208:211], v199 offset:4096
	ds_read_b128 v[212:215], v199 offset:5120
	ds_read_b128 v[216:219], v199 offset:6144
	ds_read_b128 v[220:223], v199 offset:7168
	global_load_lds_dwordx4 v178, s[52:53]
	s_add_i32 m0, s63, 0xe000
	s_nop 0
	global_load_lds_dwordx4 v180, s[52:53]
	s_waitcnt vmcnt(8)
	s_waitcnt lgkmcnt(0)
	s_setprio 1
	s_barrier
	v_mfma_f32_16x16x128_f8f6f4 v[124:127], v[152:159], v[186:193], v[124:127]
	v_mfma_f32_16x16x128_f8f6f4 v[120:123], v[144:151], v[186:193], v[120:123]
	v_mfma_f32_16x16x128_f8f6f4 v[112:115], v[152:159], v[200:207], v[112:115]
	v_mfma_f32_16x16x128_f8f6f4 v[104:107], v[144:151], v[200:207], v[104:107]
	v_mfma_f32_16x16x128_f8f6f4 v[96:99], v[152:159], v[208:215], v[96:99]
	v_mfma_f32_16x16x128_f8f6f4 v[88:91], v[144:151], v[208:215], v[88:91]
	v_mfma_f32_16x16x128_f8f6f4 v[84:87], v[152:159], v[216:223], v[84:87]
	v_mfma_f32_16x16x128_f8f6f4 v[72:75], v[144:151], v[216:223], v[72:75]
	v_mfma_f32_16x16x128_f8f6f4 v[116:119], v[136:143], v[186:193], v[116:119]
	v_mfma_f32_16x16x128_f8f6f4 v[108:111], v[128:135], v[186:193], v[108:111]
	v_mfma_f32_16x16x128_f8f6f4 v[100:103], v[136:143], v[200:207], v[100:103]
	v_mfma_f32_16x16x128_f8f6f4 v[92:95], v[128:135], v[200:207], v[92:95]
	v_mfma_f32_16x16x128_f8f6f4 v[80:83], v[136:143], v[208:215], v[80:83]
	v_mfma_f32_16x16x128_f8f6f4 v[76:79], v[128:135], v[208:215], v[76:79]
	v_mfma_f32_16x16x128_f8f6f4 v[68:71], v[136:143], v[216:223], v[68:71]
	s_setprio 0
	v_mfma_f32_16x16x128_f8f6f4 v[64:67], v[128:135], v[216:223], v[64:67]
	s_barrier
	s_add_u32 s98, s54, s10
	s_addc_u32 s99, s55, s11
	s_add_u32 s100, s56, s10
	s_addc_u32 s101, s57, s11
	s_add_i32 s86, s74, s60
	s_mov_b32 m0, s86
	ds_read_b128 v[200:203], v199 offset:16384
	ds_read_b128 v[204:207], v199 offset:17408
	ds_read_b128 v[208:211], v199 offset:18432
	ds_read_b128 v[212:215], v199 offset:19456
	ds_read_b128 v[216:219], v199 offset:20480
	ds_read_b128 v[220:223], v199 offset:21504
	ds_read_b128 v[224:227], v199 offset:22528
	ds_read_b128 v[228:231], v199 offset:23552
	global_load_lds_dwordx4 v160, s[54:55]
	s_add_i32 m0, s86, 0x2000
	s_add_u32 s86, s54, 0x40000
	s_addc_u32 s87, s55, 0
	s_add_i32 s88, s75, s60
	global_load_lds_dwordx4 v162, s[54:55]
	s_mov_b32 m0, s88
	s_nop 0
	global_load_lds_dwordx4 v160, s[86:87]
	s_add_i32 m0, s88, 0x2000
	s_nop 0
	global_load_lds_dwordx4 v162, s[86:87]
	s_mov_b32 m0, s63
	s_nop 0
	global_load_lds_dwordx4 v166, s[56:57]
	s_mov_b32 m0, s68
	s_nop 0
	global_load_lds_dwordx4 v164, s[56:57]
	s_waitcnt vmcnt(8)
	s_waitcnt lgkmcnt(0)
	s_setprio 1
	s_barrier
	v_mfma_f32_16x16x128_f8f6f4 v[60:63], v[152:159], v[200:207], v[60:63]
	v_mfma_f32_16x16x128_f8f6f4 v[56:59], v[144:151], v[200:207], v[56:59]
	v_mfma_f32_16x16x128_f8f6f4 v[48:51], v[152:159], v[208:215], v[48:51]
	v_mfma_f32_16x16x128_f8f6f4 v[40:43], v[144:151], v[208:215], v[40:43]
	v_mfma_f32_16x16x128_f8f6f4 v[32:35], v[152:159], v[216:223], v[32:35]
	v_mfma_f32_16x16x128_f8f6f4 v[24:27], v[144:151], v[216:223], v[24:27]
	v_mfma_f32_16x16x128_f8f6f4 v[16:19], v[152:159], v[224:231], v[16:19]
	v_mfma_f32_16x16x128_f8f6f4 v[8:11], v[144:151], v[224:231], v[8:11]
	v_mfma_f32_16x16x128_f8f6f4 v[52:55], v[136:143], v[200:207], v[52:55]
	v_mfma_f32_16x16x128_f8f6f4 v[44:47], v[128:135], v[200:207], v[44:47]
	v_mfma_f32_16x16x128_f8f6f4 v[36:39], v[136:143], v[208:215], v[36:39]
	v_mfma_f32_16x16x128_f8f6f4 v[28:31], v[128:135], v[208:215], v[28:31]
	v_mfma_f32_16x16x128_f8f6f4 v[20:23], v[136:143], v[216:223], v[20:23]
	v_mfma_f32_16x16x128_f8f6f4 v[12:15], v[128:135], v[216:223], v[12:15]
	v_mfma_f32_16x16x128_f8f6f4 v[4:7], v[136:143], v[224:231], v[4:7]
	s_setprio 0
	v_mfma_f32_16x16x128_f8f6f4 v[0:3], v[128:135], v[224:231], v[0:3]
	s_barrier
; #define PG8_STAGE(bufoff, gbase, voff) do { _Pragma("unroll") for (int _i = 0; _i < 2; ++_i) \
;         __builtin_amdgcn_global_load_lds((const unsigned*)((const char*)(gbase) + (voff)[_i]), (LAS unsigned*)(lds + (bufoff) + ldsw + _i * 8192), 16, 0, 0); } while (0)
; #define PG8_LDA(dst, b, h) do { _Pragma("unroll") for (int m = 0; m < 4; ++m) _Pragma("unroll") for (int k = 0; k < 2; ++k) dst[m][k] = *(const LAS bf16x8*)(lds + PG8_SA(b, h) + aoff + m * 2048 + k * 1024); } while (0)
; #define PG8_LDB(dst, b, h) do { _Pragma("unroll") for (int n = 0; n < 2; ++n) _Pragma("unroll") for (int k = 0; k < 2; ++k) dst[n][k] = *(const LAS bf16x8*)(lds + PG8_SB(b, h) + boff + n * 2048 + k * 1024); } while (0)
; #define PG8_WAIT_V(n) asm volatile("s_waitcnt vmcnt(" #n ")" ::: "memory")
; #define PG8_WAIT_L(n) asm volatile("s_waitcnt lgkmcnt(" #n ")" ::: "memory")
; #define PG8_BAR __builtin_amdgcn_s_barrier()
; #define PG8_SCHED __builtin_amdgcn_sched_barrier(0)
; template <class Epi, bool FP8 = false>
; __device__ __forceinline__ void gemm_phase(LAS unsigned char* lds, const Gemm g, const StaticOrder& S_, const Epi& E, const int tid) {
;     ...
;             PG8_LDB(B0, 1, 0); PG8_LDB(B1, 1, 1); PG8_SCHED; PG8_LDA(At, 1, 0); PG8_STAGE(PG8_SA(0, 1), a2 + hstepA, voffA);
;             PG8_WAIT_V(8); PG8_WAIT_L(0); PG8_BAR; PG8_MMA(0, 0, At, B0); PG8_MMA(0, 1, At, B1); PG8_BAR; PG8_SCHED;
;             PG8_LDA(At, 1, 1); PG8_STAGE(PG8_SB(1, 0), b3, voffB); PG8_STAGE(PG8_SB(1, 1), b3 + hstepB, voffB); PG8_STAGE(PG8_SA(1, 0), a3, voffA);
;             PG8_WAIT_V(8); PG8_WAIT_L(0); PG8_BAR; PG8_MMA(1, 0, At, B0); PG8_MMA(1, 1, At, B1); PG8_BAR; PG8_SCHED;
;         }
;         if (wr == 0) PG8_BAR;
	s_add_i32 s86, 0, 0x18000
	v_add_u32_e32 v128, s86, v195
	s_add_i32 s87, 0, 0x1c000
	ds_read_b128 v[156:159], v128 offset:1024
	ds_read_b128 v[152:155], v128
	ds_read_b128 v[148:151], v128 offset:3072
	ds_read_b128 v[144:147], v128 offset:2048
	v_add_u32_e32 v128, s87, v195
	ds_read_b128 v[140:143], v128 offset:1024
	ds_read_b128 v[136:139], v128
	ds_read_b128 v[132:135], v128 offset:3072
	ds_read_b128 v[128:131], v128 offset:2048
	s_add_u32 s56, s56, 0x40000
	s_addc_u32 s57, s57, 0
	s_mov_b32 m0, s69
	ds_read_b128 v[200:203], v199 offset:32768
	ds_read_b128 v[204:207], v199 offset:33792
	ds_read_b128 v[208:211], v199 offset:34816
	ds_read_b128 v[212:215], v199 offset:35840
	ds_read_b128 v[216:219], v199 offset:36864
	ds_read_b128 v[220:223], v199 offset:37888
	ds_read_b128 v[224:227], v199 offset:38912
	ds_read_b128 v[228:231], v199 offset:39936
	global_load_lds_dwordx4 v166, s[56:57]
	s_mov_b32 m0, s70
	s_nop 0
	global_load_lds_dwordx4 v164, s[56:57]
	s_waitcnt vmcnt(8)
	s_waitcnt lgkmcnt(0)
	s_setprio 1
	s_barrier
	v_mfma_f32_16x16x128_f8f6f4 v[124:127], v[152:159], v[200:207], v[124:127]
	v_mfma_f32_16x16x128_f8f6f4 v[120:123], v[144:151], v[200:207], v[120:123]
	v_mfma_f32_16x16x128_f8f6f4 v[112:115], v[152:159], v[208:215], v[112:115]
	v_mfma_f32_16x16x128_f8f6f4 v[104:107], v[144:151], v[208:215], v[104:107]
	v_mfma_f32_16x16x128_f8f6f4 v[96:99], v[152:159], v[216:223], v[96:99]
	v_mfma_f32_16x16x128_f8f6f4 v[88:91], v[144:151], v[216:223], v[88:91]
	v_mfma_f32_16x16x128_f8f6f4 v[84:87], v[152:159], v[224:231], v[84:87]
	v_mfma_f32_16x16x128_f8f6f4 v[72:75], v[144:151], v[224:231], v[72:75]
	v_mfma_f32_16x16x128_f8f6f4 v[116:119], v[136:143], v[200:207], v[116:119]
	v_mfma_f32_16x16x128_f8f6f4 v[108:111], v[128:135], v[200:207], v[108:111]
	v_mfma_f32_16x16x128_f8f6f4 v[100:103], v[136:143], v[208:215], v[100:103]
	v_mfma_f32_16x16x128_f8f6f4 v[92:95], v[128:135], v[208:215], v[92:95]
	v_mfma_f32_16x16x128_f8f6f4 v[80:83], v[136:143], v[216:223], v[80:83]
	v_mfma_f32_16x16x128_f8f6f4 v[76:79], v[128:135], v[216:223], v[76:79]
	v_mfma_f32_16x16x128_f8f6f4 v[68:71], v[136:143], v[224:231], v[68:71]
	s_setprio 0
	v_mfma_f32_16x16x128_f8f6f4 v[64:67], v[128:135], v[224:231], v[64:67]
	s_barrier
	s_add_i32 s56, s86, s60
	s_mov_b32 m0, s56
	ds_read_b128 v[200:203], v199 offset:49152
	ds_read_b128 v[204:207], v199 offset:50176
	ds_read_b128 v[208:211], v199 offset:51200
	ds_read_b128 v[212:215], v199 offset:52224
	ds_read_b128 v[216:219], v199 offset:53248
	ds_read_b128 v[220:223], v199 offset:54272
	ds_read_b128 v[224:227], v199 offset:55296
	ds_read_b128 v[228:231], v199 offset:56320
	global_load_lds_dwordx4 v160, s[98:99]
	s_add_i32 m0, s56, 0x2000
	s_add_u32 s54, s54, 0x40080
	s_addc_u32 s55, s55, 0
	s_add_i32 s56, s87, s60
	global_load_lds_dwordx4 v162, s[98:99]
	s_mov_b32 m0, s56
	s_nop 0
	global_load_lds_dwordx4 v160, s[54:55]
	s_add_i32 m0, s56, 0x2000
	s_nop 0
	global_load_lds_dwordx4 v162, s[54:55]
	s_mov_b32 m0, s72
	s_nop 0
	global_load_lds_dwordx4 v166, s[100:101]
	s_mov_b32 m0, s73
	s_nop 0
	global_load_lds_dwordx4 v164, s[100:101]
	s_waitcnt vmcnt(8)
	s_waitcnt lgkmcnt(0)
	s_setprio 1
	s_barrier
	v_mfma_f32_16x16x128_f8f6f4 v[60:63], v[152:159], v[200:207], v[60:63]
	v_mfma_f32_16x16x128_f8f6f4 v[56:59], v[144:151], v[200:207], v[56:59]
	v_mfma_f32_16x16x128_f8f6f4 v[48:51], v[152:159], v[208:215], v[48:51]
	v_mfma_f32_16x16x128_f8f6f4 v[40:43], v[144:151], v[208:215], v[40:43]
	v_mfma_f32_16x16x128_f8f6f4 v[32:35], v[152:159], v[216:223], v[32:35]
	v_mfma_f32_16x16x128_f8f6f4 v[24:27], v[144:151], v[216:223], v[24:27]
	v_mfma_f32_16x16x128_f8f6f4 v[16:19], v[152:159], v[224:231], v[16:19]
	v_mfma_f32_16x16x128_f8f6f4 v[8:11], v[144:151], v[224:231], v[8:11]
	v_mfma_f32_16x16x128_f8f6f4 v[52:55], v[136:143], v[200:207], v[52:55]
	v_mfma_f32_16x16x128_f8f6f4 v[44:47], v[128:135], v[200:207], v[44:47]
	v_mfma_f32_16x16x128_f8f6f4 v[36:39], v[136:143], v[208:215], v[36:39]
	v_mfma_f32_16x16x128_f8f6f4 v[28:31], v[128:135], v[208:215], v[28:31]
	v_mfma_f32_16x16x128_f8f6f4 v[20:23], v[136:143], v[216:223], v[20:23]
	v_mfma_f32_16x16x128_f8f6f4 v[12:15], v[128:135], v[216:223], v[12:15]
	v_mfma_f32_16x16x128_f8f6f4 v[4:7], v[136:143], v[224:231], v[4:7]
	s_setprio 0
	v_mfma_f32_16x16x128_f8f6f4 v[0:3], v[128:135], v[224:231], v[0:3]
	s_barrier
	s_add_i32 s85, s85, 2
	s_add_u32 s52, s52, 0x100
	s_addc_u32 s53, s53, 0
	s_add_u32 s66, s66, 0x100
	s_addc_u32 s84, s84, 0
	s_cmp_gt_u32 s85, 13
	s_cbranch_scc0 .LBB0_596
	s_and_b64 vcc, exec, s[12:13]
	s_cbranch_vccz .LBB0_599
	s_barrier

; #define PG8_STAGE(bufoff, gbase, voff) do { _Pragma("unroll") for (int _i = 0; _i < 2; ++_i) \
;         __builtin_amdgcn_global_load_lds((const unsigned*)((const char*)(gbase) + (voff)[_i]), (LAS unsigned*)(lds + (bufoff) + ldsw + _i * 8192), 16, 0, 0); } while (0)
; #define PG8_LDA(dst, b, h) do { _Pragma("unroll") for (int m = 0; m < 4; ++m) _Pragma("unroll") for (int k = 0; k < 2; ++k) dst[m][k] = *(const LAS bf16x8*)(lds + PG8_SA(b, h) + aoff + m * 2048 + k * 1024); } while (0)
; #define PG8_LDB(dst, b, h) do { _Pragma("unroll") for (int n = 0; n < 2; ++n) _Pragma("unroll") for (int k = 0; k < 2; ++k) dst[n][k] = *(const LAS bf16x8*)(lds + PG8_SB(b, h) + boff + n * 2048 + k * 1024); } while (0)
; #define PG8_WAIT_V(n) asm volatile("s_waitcnt vmcnt(" #n ")" ::: "memory")
; #define PG8_WAIT_L(n) asm volatile("s_waitcnt lgkmcnt(" #n ")" ::: "memory")
; #define PG8_BAR __builtin_amdgcn_s_barrier()
; #define PG8_SCHED __builtin_amdgcn_sched_barrier(0)
; template <class Epi, bool FP8 = false>
; __device__ __forceinline__ void gemm_phase(LAS unsigned char* lds, const Gemm g, const StaticOrder& S_, const Epi& E, const int tid) {
;     ...
;             const bool last = (t == nt - 2);
;             const char* a1 = cA + (size_t)(t + 1) * kstep;
;             const char* a2 = last ? nA : cA + (size_t)(t + 2) * kstep; const char* b2 = last ? nB : cB + (size_t)(t + 2) * kstep;
;             const char* a3 = a2 + kstep; const char* b3 = b2 + kstep;
;             PG8_LDB(B0, 0, 0); PG8_LDB(B1, 0, 1); PG8_SCHED; PG8_LDA(At, 0, 0); PG8_STAGE(PG8_SA(1, 1), a1 + hstepA, voffA);
;             PG8_WAIT_V(8); PG8_WAIT_L(0); PG8_BAR; PG8_MMA(0, 0, At, B0); PG8_MMA(0, 1, At, B1); PG8_BAR; PG8_SCHED;
;             PG8_LDA(At, 0, 1); PG8_STAGE(PG8_SB(0, 0), b2, voffB); PG8_STAGE(PG8_SB(0, 1), b2 + hstepB, voffB); PG8_STAGE(PG8_SA(0, 0), a2, voffA);
;             PG8_WAIT_V(8); PG8_WAIT_L(0); PG8_BAR; PG8_MMA(1, 0, At, B0); PG8_MMA(1, 1, At, B1); PG8_BAR; PG8_SCHED;
.LBB0_1095:
	ds_read_b128 v[144:147], v174
	ds_read_b128 v[178:181], v174 offset:1024
	ds_read_b128 v[182:185], v174 offset:2048
	ds_read_b128 v[186:189], v174 offset:3072
	ds_read_b128 v[190:193], v175
	ds_read_b128 v[194:197], v175 offset:1024
	ds_read_b128 v[198:201], v175 offset:2048
	ds_read_b128 v[202:205], v175 offset:3072
	s_add_u32 s8, s26, 0x100
	s_addc_u32 s9, s27, 0
	s_cmp_eq_u32 s69, 12
	s_cselect_b32 s49, s23, s9
	s_cselect_b32 s48, s22, s8
	s_cselect_b32 s47, s21, s68
	s_cselect_b32 s46, s66, s67
	s_add_i32 m0, s54, 0xc000
	ds_read_b128 v[206:209], v176
	ds_read_b128 v[210:213], v176 offset:1024
	ds_read_b128 v[214:217], v176 offset:2048
	ds_read_b128 v[218:221], v176 offset:3072
	ds_read_b128 v[222:225], v176 offset:4096
	ds_read_b128 v[226:229], v176 offset:5120
	ds_read_b128 v[230:233], v176 offset:6144
	ds_read_b128 v[234:237], v176 offset:7168
	global_load_lds_dwordx4 v136, s[26:27]
	s_add_i32 m0, s54, 0xe000
	s_nop 0
	global_load_lds_dwordx4 v138, s[26:27]
	s_waitcnt vmcnt(8)
	s_waitcnt lgkmcnt(0)
	s_setprio 1
	s_barrier
	v_mfma_f32_16x16x32_bf16 v[124:127], v[144:147], v[206:209], v[124:127]
	v_mfma_f32_16x16x32_bf16 v[120:123], v[182:185], v[206:209], v[120:123]
	v_mfma_f32_16x16x32_bf16 v[108:111], v[144:147], v[214:217], v[108:111]
	v_mfma_f32_16x16x32_bf16 v[104:107], v[182:185], v[214:217], v[104:107]
	v_mfma_f32_16x16x32_bf16 v[92:95], v[144:147], v[222:225], v[92:95]
	v_mfma_f32_16x16x32_bf16 v[88:91], v[182:185], v[222:225], v[88:91]
	v_mfma_f32_16x16x32_bf16 v[76:79], v[144:147], v[230:233], v[76:79]
	v_mfma_f32_16x16x32_bf16 v[72:75], v[182:185], v[230:233], v[72:75]
	v_mfma_f32_16x16x32_bf16 v[124:127], v[178:181], v[210:213], v[124:127]
	v_mfma_f32_16x16x32_bf16 v[120:123], v[186:189], v[210:213], v[120:123]
	v_mfma_f32_16x16x32_bf16 v[108:111], v[178:181], v[218:221], v[108:111]
	v_mfma_f32_16x16x32_bf16 v[104:107], v[186:189], v[218:221], v[104:107]
	v_mfma_f32_16x16x32_bf16 v[92:95], v[178:181], v[226:229], v[92:95]
	v_mfma_f32_16x16x32_bf16 v[88:91], v[186:189], v[226:229], v[88:91]
	v_mfma_f32_16x16x32_bf16 v[76:79], v[178:181], v[234:237], v[76:79]
	v_mfma_f32_16x16x32_bf16 v[72:75], v[186:189], v[234:237], v[72:75]
	v_mfma_f32_16x16x32_bf16 v[116:119], v[190:193], v[206:209], v[116:119]
	v_mfma_f32_16x16x32_bf16 v[112:115], v[198:201], v[206:209], v[112:115]
	v_mfma_f32_16x16x32_bf16 v[100:103], v[190:193], v[214:217], v[100:103]
	v_mfma_f32_16x16x32_bf16 v[96:99], v[198:201], v[214:217], v[96:99]
	v_mfma_f32_16x16x32_bf16 v[84:87], v[190:193], v[222:225], v[84:87]
	v_mfma_f32_16x16x32_bf16 v[80:83], v[198:201], v[222:225], v[80:83]
	v_mfma_f32_16x16x32_bf16 v[68:71], v[190:193], v[230:233], v[68:71]
	v_mfma_f32_16x16x32_bf16 v[64:67], v[198:201], v[230:233], v[64:67]
	v_mfma_f32_16x16x32_bf16 v[116:119], v[194:197], v[210:213], v[116:119]
	v_mfma_f32_16x16x32_bf16 v[112:115], v[202:205], v[210:213], v[112:115]
	v_mfma_f32_16x16x32_bf16 v[100:103], v[194:197], v[218:221], v[100:103]
	v_mfma_f32_16x16x32_bf16 v[96:99], v[202:205], v[218:221], v[96:99]
	v_mfma_f32_16x16x32_bf16 v[84:87], v[194:197], v[226:229], v[84:87]
	v_mfma_f32_16x16x32_bf16 v[80:83], v[202:205], v[226:229], v[80:83]
	v_mfma_f32_16x16x32_bf16 v[68:71], v[194:197], v[234:237], v[68:71]
	s_setprio 0
	v_mfma_f32_16x16x32_bf16 v[64:67], v[202:205], v[234:237], v[64:67]
	s_barrier
	s_add_u32 s98, s46, s16
	s_addc_u32 s99, s47, s17
	s_add_u32 s100, s48, s16
	s_addc_u32 s101, s49, s17
	s_add_i32 s26, s61, s53
	s_mov_b32 m0, s26
	ds_read_b128 v[206:209], v176 offset:16384
	ds_read_b128 v[210:213], v176 offset:17408
	ds_read_b128 v[214:217], v176 offset:18432
	ds_read_b128 v[218:221], v176 offset:19456
	ds_read_b128 v[222:225], v176 offset:20480
	ds_read_b128 v[226:229], v176 offset:21504
	ds_read_b128 v[230:233], v176 offset:22528
	ds_read_b128 v[234:237], v176 offset:23552
	global_load_lds_dwordx4 v132, s[46:47]
	s_add_i32 m0, s26, 0x2000
	s_add_u32 s26, s46, 0x40000
	s_addc_u32 s27, s47, 0
	s_add_i32 s70, s62, s53
	global_load_lds_dwordx4 v134, s[46:47]
	s_mov_b32 m0, s70
	s_nop 0
	global_load_lds_dwordx4 v132, s[26:27]
	s_add_i32 m0, s70, 0x2000
	s_nop 0
	global_load_lds_dwordx4 v134, s[26:27]
	s_mov_b32 m0, s54
	s_nop 0
	global_load_lds_dwordx4 v128, s[48:49]
	s_mov_b32 m0, s55
	s_nop 0
	global_load_lds_dwordx4 v130, s[48:49]
	s_waitcnt vmcnt(8)
	s_waitcnt lgkmcnt(0)
	s_setprio 1
	s_barrier
	v_mfma_f32_16x16x32_bf16 v[60:63], v[144:147], v[206:209], v[60:63]
	v_mfma_f32_16x16x32_bf16 v[56:59], v[182:185], v[206:209], v[56:59]
	v_mfma_f32_16x16x32_bf16 v[44:47], v[144:147], v[214:217], v[44:47]
	v_mfma_f32_16x16x32_bf16 v[40:43], v[182:185], v[214:217], v[40:43]
	v_mfma_f32_16x16x32_bf16 v[28:31], v[144:147], v[222:225], v[28:31]
	v_mfma_f32_16x16x32_bf16 v[24:27], v[182:185], v[222:225], v[24:27]
	v_mfma_f32_16x16x32_bf16 v[12:15], v[144:147], v[230:233], v[12:15]
	v_mfma_f32_16x16x32_bf16 v[8:11], v[182:185], v[230:233], v[8:11]
	v_mfma_f32_16x16x32_bf16 v[60:63], v[178:181], v[210:213], v[60:63]
	v_mfma_f32_16x16x32_bf16 v[56:59], v[186:189], v[210:213], v[56:59]
	v_mfma_f32_16x16x32_bf16 v[44:47], v[178:181], v[218:221], v[44:47]
	v_mfma_f32_16x16x32_bf16 v[40:43], v[186:189], v[218:221], v[40:43]
	v_mfma_f32_16x16x32_bf16 v[28:31], v[178:181], v[226:229], v[28:31]
	v_mfma_f32_16x16x32_bf16 v[24:27], v[186:189], v[226:229], v[24:27]
	v_mfma_f32_16x16x32_bf16 v[12:15], v[178:181], v[234:237], v[12:15]
	v_mfma_f32_16x16x32_bf16 v[8:11], v[186:189], v[234:237], v[8:11]
	v_mfma_f32_16x16x32_bf16 v[52:55], v[190:193], v[206:209], v[52:55]
	v_mfma_f32_16x16x32_bf16 v[48:51], v[198:201], v[206:209], v[48:51]
	v_mfma_f32_16x16x32_bf16 v[36:39], v[190:193], v[214:217], v[36:39]
	v_mfma_f32_16x16x32_bf16 v[32:35], v[198:201], v[214:217], v[32:35]
	v_mfma_f32_16x16x32_bf16 v[20:23], v[190:193], v[222:225], v[20:23]
	v_mfma_f32_16x16x32_bf16 v[16:19], v[198:201], v[222:225], v[16:19]
	v_mfma_f32_16x16x32_bf16 v[4:7], v[190:193], v[230:233], v[4:7]
	v_mfma_f32_16x16x32_bf16 v[0:3], v[198:201], v[230:233], v[0:3]
	v_mfma_f32_16x16x32_bf16 v[52:55], v[194:197], v[210:213], v[52:55]
	v_mfma_f32_16x16x32_bf16 v[48:51], v[202:205], v[210:213], v[48:51]
	v_mfma_f32_16x16x32_bf16 v[36:39], v[194:197], v[218:221], v[36:39]
	v_mfma_f32_16x16x32_bf16 v[32:35], v[202:205], v[218:221], v[32:35]
	v_mfma_f32_16x16x32_bf16 v[20:23], v[194:197], v[226:229], v[20:23]
	v_mfma_f32_16x16x32_bf16 v[16:19], v[202:205], v[226:229], v[16:19]
	v_mfma_f32_16x16x32_bf16 v[4:7], v[194:197], v[234:237], v[4:7]
	s_setprio 0
	v_mfma_f32_16x16x32_bf16 v[0:3], v[202:205], v[234:237], v[0:3]
	s_barrier
; #define PG8_STAGE(bufoff, gbase, voff) do { _Pragma("unroll") for (int _i = 0; _i < 2; ++_i) \
;         __builtin_amdgcn_global_load_lds((const unsigned*)((const char*)(gbase) + (voff)[_i]), (LAS unsigned*)(lds + (bufoff) + ldsw + _i * 8192), 16, 0, 0); } while (0)
; #define PG8_LDA(dst, b, h) do { _Pragma("unroll") for (int m = 0; m < 4; ++m) _Pragma("unroll") for (int k = 0; k < 2; ++k) dst[m][k] = *(const LAS bf16x8*)(lds + PG8_SA(b, h) + aoff + m * 2048 + k * 1024); } while (0)
; #define PG8_LDB(dst, b, h) do { _Pragma("unroll") for (int n = 0; n < 2; ++n) _Pragma("unroll") for (int k = 0; k < 2; ++k) dst[n][k] = *(const LAS bf16x8*)(lds + PG8_SB(b, h) + boff + n * 2048 + k * 1024); } while (0)
; #define PG8_WAIT_V(n) asm volatile("s_waitcnt vmcnt(" #n ")" ::: "memory")
; #define PG8_WAIT_L(n) asm volatile("s_waitcnt lgkmcnt(" #n ")" ::: "memory")
; #define PG8_BAR __builtin_amdgcn_s_barrier()
; #define PG8_SCHED __builtin_amdgcn_sched_barrier(0)
; template <class Epi, bool FP8 = false>
; __device__ __forceinline__ void gemm_phase(LAS unsigned char* lds, const Gemm g, const StaticOrder& S_, const Epi& E, const int tid) {
;     ...
;             PG8_LDB(B0, 1, 0); PG8_LDB(B1, 1, 1); PG8_SCHED; PG8_LDA(At, 1, 0); PG8_STAGE(PG8_SA(0, 1), a2 + hstepA, voffA);
;             PG8_WAIT_V(8); PG8_WAIT_L(0); PG8_BAR; PG8_MMA(0, 0, At, B0); PG8_MMA(0, 1, At, B1); PG8_BAR; PG8_SCHED;
;             PG8_LDA(At, 1, 1); PG8_STAGE(PG8_SB(1, 0), b3, voffB); PG8_STAGE(PG8_SB(1, 1), b3 + hstepB, voffB); PG8_STAGE(PG8_SA(1, 0), a3, voffA);
;             PG8_WAIT_V(8); PG8_WAIT_L(0); PG8_BAR; PG8_MMA(1, 0, At, B0); PG8_MMA(1, 1, At, B1); PG8_BAR; PG8_SCHED;
;         }
;         if (wr == 0) PG8_BAR;
	s_add_i32 s70, 0, 0x18000
	v_add_u32_e32 v177, s70, v172
	s_add_i32 s71, 0, 0x1c000
	ds_read_b128 v[144:147], v177
	ds_read_b128 v[178:181], v177 offset:1024
	ds_read_b128 v[182:185], v177 offset:2048
	ds_read_b128 v[186:189], v177 offset:3072
	v_add_u32_e32 v177, s71, v172
	ds_read_b128 v[190:193], v177
	ds_read_b128 v[194:197], v177 offset:1024
	ds_read_b128 v[198:201], v177 offset:2048
	ds_read_b128 v[202:205], v177 offset:3072
	s_add_u32 s26, s48, 0x60000
	s_addc_u32 s27, s49, 0
	s_mov_b32 m0, s56
	ds_read_b128 v[206:209], v176 offset:32768
	ds_read_b128 v[210:213], v176 offset:33792
	ds_read_b128 v[214:217], v176 offset:34816
	ds_read_b128 v[218:221], v176 offset:35840
	ds_read_b128 v[222:225], v176 offset:36864
	ds_read_b128 v[226:229], v176 offset:37888
	ds_read_b128 v[230:233], v176 offset:38912
	ds_read_b128 v[234:237], v176 offset:39936
	global_load_lds_dwordx4 v128, s[26:27]
	s_mov_b32 m0, s57
	s_nop 0
	global_load_lds_dwordx4 v130, s[26:27]
	s_waitcnt vmcnt(8)
	s_waitcnt lgkmcnt(0)
	s_setprio 1
	s_barrier
	v_mfma_f32_16x16x32_bf16 v[124:127], v[144:147], v[206:209], v[124:127]
	v_mfma_f32_16x16x32_bf16 v[120:123], v[182:185], v[206:209], v[120:123]
	v_mfma_f32_16x16x32_bf16 v[108:111], v[144:147], v[214:217], v[108:111]
	v_mfma_f32_16x16x32_bf16 v[104:107], v[182:185], v[214:217], v[104:107]
	v_mfma_f32_16x16x32_bf16 v[92:95], v[144:147], v[222:225], v[92:95]
	v_mfma_f32_16x16x32_bf16 v[88:91], v[182:185], v[222:225], v[88:91]
	v_mfma_f32_16x16x32_bf16 v[76:79], v[144:147], v[230:233], v[76:79]
	v_mfma_f32_16x16x32_bf16 v[72:75], v[182:185], v[230:233], v[72:75]
	v_mfma_f32_16x16x32_bf16 v[124:127], v[178:181], v[210:213], v[124:127]
	v_mfma_f32_16x16x32_bf16 v[120:123], v[186:189], v[210:213], v[120:123]
	v_mfma_f32_16x16x32_bf16 v[108:111], v[178:181], v[218:221], v[108:111]
	v_mfma_f32_16x16x32_bf16 v[104:107], v[186:189], v[218:221], v[104:107]
	v_mfma_f32_16x16x32_bf16 v[92:95], v[178:181], v[226:229], v[92:95]
	v_mfma_f32_16x16x32_bf16 v[88:91], v[186:189], v[226:229], v[88:91]
	v_mfma_f32_16x16x32_bf16 v[76:79], v[178:181], v[234:237], v[76:79]
	v_mfma_f32_16x16x32_bf16 v[72:75], v[186:189], v[234:237], v[72:75]
	v_mfma_f32_16x16x32_bf16 v[116:119], v[190:193], v[206:209], v[116:119]
	v_mfma_f32_16x16x32_bf16 v[112:115], v[198:201], v[206:209], v[112:115]
	v_mfma_f32_16x16x32_bf16 v[100:103], v[190:193], v[214:217], v[100:103]
	v_mfma_f32_16x16x32_bf16 v[96:99], v[198:201], v[214:217], v[96:99]
	v_mfma_f32_16x16x32_bf16 v[84:87], v[190:193], v[222:225], v[84:87]
	v_mfma_f32_16x16x32_bf16 v[80:83], v[198:201], v[222:225], v[80:83]
	v_mfma_f32_16x16x32_bf16 v[68:71], v[190:193], v[230:233], v[68:71]
	v_mfma_f32_16x16x32_bf16 v[64:67], v[198:201], v[230:233], v[64:67]
	v_mfma_f32_16x16x32_bf16 v[116:119], v[194:197], v[210:213], v[116:119]
	v_mfma_f32_16x16x32_bf16 v[112:115], v[202:205], v[210:213], v[112:115]
	v_mfma_f32_16x16x32_bf16 v[100:103], v[194:197], v[218:221], v[100:103]
	v_mfma_f32_16x16x32_bf16 v[96:99], v[202:205], v[218:221], v[96:99]
	v_mfma_f32_16x16x32_bf16 v[84:87], v[194:197], v[226:229], v[84:87]
	v_mfma_f32_16x16x32_bf16 v[80:83], v[202:205], v[226:229], v[80:83]
	v_mfma_f32_16x16x32_bf16 v[68:71], v[194:197], v[234:237], v[68:71]
	s_setprio 0
	v_mfma_f32_16x16x32_bf16 v[64:67], v[202:205], v[234:237], v[64:67]
	s_barrier
	s_add_i32 s26, s70, s53
	s_mov_b32 m0, s26
	ds_read_b128 v[206:209], v176 offset:49152
	ds_read_b128 v[210:213], v176 offset:50176
	ds_read_b128 v[214:217], v176 offset:51200
	ds_read_b128 v[218:221], v176 offset:52224
	ds_read_b128 v[222:225], v176 offset:53248
	ds_read_b128 v[226:229], v176 offset:54272
	ds_read_b128 v[230:233], v176 offset:55296
	ds_read_b128 v[234:237], v176 offset:56320
	global_load_lds_dwordx4 v132, s[98:99]
	s_add_i32 m0, s26, 0x2000
	s_add_u32 s26, s46, 0x40080
	s_addc_u32 s27, s47, 0
	s_add_i32 s46, s71, s53
	global_load_lds_dwordx4 v134, s[98:99]
	s_mov_b32 m0, s46
	s_nop 0
	global_load_lds_dwordx4 v132, s[26:27]
	s_add_i32 m0, s46, 0x2000
	s_nop 0
	global_load_lds_dwordx4 v134, s[26:27]
	s_mov_b32 m0, s59
	s_nop 0
	global_load_lds_dwordx4 v128, s[100:101]
	s_mov_b32 m0, s60
	s_nop 0
	global_load_lds_dwordx4 v130, s[100:101]
	s_waitcnt vmcnt(8)
	s_waitcnt lgkmcnt(0)
	s_setprio 1
	s_barrier
	v_mfma_f32_16x16x32_bf16 v[60:63], v[144:147], v[206:209], v[60:63]
	v_mfma_f32_16x16x32_bf16 v[56:59], v[182:185], v[206:209], v[56:59]
	v_mfma_f32_16x16x32_bf16 v[44:47], v[144:147], v[214:217], v[44:47]
	v_mfma_f32_16x16x32_bf16 v[40:43], v[182:185], v[214:217], v[40:43]
	v_mfma_f32_16x16x32_bf16 v[28:31], v[144:147], v[222:225], v[28:31]
	v_mfma_f32_16x16x32_bf16 v[24:27], v[182:185], v[222:225], v[24:27]
	v_mfma_f32_16x16x32_bf16 v[12:15], v[144:147], v[230:233], v[12:15]
	v_mfma_f32_16x16x32_bf16 v[8:11], v[182:185], v[230:233], v[8:11]
	v_mfma_f32_16x16x32_bf16 v[60:63], v[178:181], v[210:213], v[60:63]
	v_mfma_f32_16x16x32_bf16 v[56:59], v[186:189], v[210:213], v[56:59]
	v_mfma_f32_16x16x32_bf16 v[44:47], v[178:181], v[218:221], v[44:47]
	v_mfma_f32_16x16x32_bf16 v[40:43], v[186:189], v[218:221], v[40:43]
	v_mfma_f32_16x16x32_bf16 v[28:31], v[178:181], v[226:229], v[28:31]
	v_mfma_f32_16x16x32_bf16 v[24:27], v[186:189], v[226:229], v[24:27]
	v_mfma_f32_16x16x32_bf16 v[12:15], v[178:181], v[234:237], v[12:15]
	v_mfma_f32_16x16x32_bf16 v[8:11], v[186:189], v[234:237], v[8:11]
	v_mfma_f32_16x16x32_bf16 v[52:55], v[190:193], v[206:209], v[52:55]
	v_mfma_f32_16x16x32_bf16 v[48:51], v[198:201], v[206:209], v[48:51]
	v_mfma_f32_16x16x32_bf16 v[36:39], v[190:193], v[214:217], v[36:39]
	v_mfma_f32_16x16x32_bf16 v[32:35], v[198:201], v[214:217], v[32:35]
	v_mfma_f32_16x16x32_bf16 v[20:23], v[190:193], v[222:225], v[20:23]
	v_mfma_f32_16x16x32_bf16 v[16:19], v[198:201], v[222:225], v[16:19]
	v_mfma_f32_16x16x32_bf16 v[4:7], v[190:193], v[230:233], v[4:7]
	v_mfma_f32_16x16x32_bf16 v[0:3], v[198:201], v[230:233], v[0:3]
	v_mfma_f32_16x16x32_bf16 v[52:55], v[194:197], v[210:213], v[52:55]
	v_mfma_f32_16x16x32_bf16 v[48:51], v[202:205], v[210:213], v[48:51]
	v_mfma_f32_16x16x32_bf16 v[36:39], v[194:197], v[218:221], v[36:39]
	v_mfma_f32_16x16x32_bf16 v[32:35], v[202:205], v[218:221], v[32:35]
	v_mfma_f32_16x16x32_bf16 v[20:23], v[194:197], v[226:229], v[20:23]
	v_mfma_f32_16x16x32_bf16 v[16:19], v[202:205], v[226:229], v[16:19]
	v_mfma_f32_16x16x32_bf16 v[4:7], v[194:197], v[234:237], v[4:7]
	s_setprio 0
	v_mfma_f32_16x16x32_bf16 v[0:3], v[202:205], v[234:237], v[0:3]
	s_barrier
	s_add_i32 s69, s69, 2
	s_add_u32 s67, s67, 0x100
	s_addc_u32 s68, s68, 0
	s_cmp_gt_u32 s69, 13
	s_mov_b64 s[26:27], s[8:9]
	s_cbranch_scc0 .LBB0_1095
	s_and_b64 vcc, exec, s[18:19]
	s_cbranch_vccz .LBB0_1098
	s_barrier

; #define PG8_STAGE(bufoff, gbase, voff) do { _Pragma("unroll") for (int _i = 0; _i < 2; ++_i) \
;         __builtin_amdgcn_global_load_lds((const unsigned*)((const char*)(gbase) + (voff)[_i]), (LAS unsigned*)(lds + (bufoff) + ldsw + _i * 8192), 16, 0, 0); } while (0)
; #define PG8_LDA(dst, b, h) do { _Pragma("unroll") for (int m = 0; m < 4; ++m) _Pragma("unroll") for (int k = 0; k < 2; ++k) dst[m][k] = *(const LAS bf16x8*)(lds + PG8_SA(b, h) + aoff + m * 2048 + k * 1024); } while (0)
; #define PG8_LDB(dst, b, h) do { _Pragma("unroll") for (int n = 0; n < 2; ++n) _Pragma("unroll") for (int k = 0; k < 2; ++k) dst[n][k] = *(const LAS bf16x8*)(lds + PG8_SB(b, h) + boff + n * 2048 + k * 1024); } while (0)
; #define PG8_WAIT_V(n) asm volatile("s_waitcnt vmcnt(" #n ")" ::: "memory")
; #define PG8_WAIT_L(n) asm volatile("s_waitcnt lgkmcnt(" #n ")" ::: "memory")
; #define PG8_BAR __builtin_amdgcn_s_barrier()
; #define PG8_SCHED __builtin_amdgcn_sched_barrier(0)
; template <class Epi, bool FP8 = false>
; __device__ __forceinline__ void gemm_phase(LAS unsigned char* lds, const Gemm g, const StaticOrder& S_, const Epi& E, const int tid) {
;     ...
;             const bool last = (t == nt - 2);
;             const char* a1 = cA + (size_t)(t + 1) * kstep;
;             const char* a2 = last ? nA : cA + (size_t)(t + 2) * kstep; const char* b2 = last ? nB : cB + (size_t)(t + 2) * kstep;
;             const char* a3 = a2 + kstep; const char* b3 = b2 + kstep;
;             PG8_LDB(B0, 0, 0); PG8_LDB(B1, 0, 1); PG8_SCHED; PG8_LDA(At, 0, 0); PG8_STAGE(PG8_SA(1, 1), a1 + hstepA, voffA);
;             PG8_WAIT_V(8); PG8_WAIT_L(0); PG8_BAR; PG8_MMA(0, 0, At, B0); PG8_MMA(0, 1, At, B1); PG8_BAR; PG8_SCHED;
;             PG8_LDA(At, 0, 1); PG8_STAGE(PG8_SB(0, 0), b2, voffB); PG8_STAGE(PG8_SB(0, 1), b2 + hstepB, voffB); PG8_STAGE(PG8_SA(0, 0), a2, voffA);
;             PG8_WAIT_V(8); PG8_WAIT_L(0); PG8_BAR; PG8_MMA(1, 0, At, B0); PG8_MMA(1, 1, At, B1); PG8_BAR; PG8_SCHED;
.LBB0_1121:
	ds_read_b128 v[144:147], v148
	ds_read_b128 v[152:155], v148 offset:1024
	ds_read_b128 v[160:163], v148 offset:2048
	ds_read_b128 v[164:167], v148 offset:3072
	ds_read_b128 v[168:171], v149
	ds_read_b128 v[172:175], v149 offset:1024
	ds_read_b128 v[176:179], v149 offset:2048
	ds_read_b128 v[180:183], v149 offset:3072
	s_add_u32 s8, s26, 0x100
	s_addc_u32 s9, s27, 0
	s_cmp_eq_u32 s69, 4
	s_cselect_b32 s49, s23, s9
	s_cselect_b32 s48, s22, s8
	s_cselect_b32 s47, s21, s68
	s_cselect_b32 s46, s66, s67
	s_add_i32 m0, s54, 0xc000
	ds_read_b128 v[184:187], v150
	ds_read_b128 v[188:191], v150 offset:1024
	ds_read_b128 v[192:195], v150 offset:2048
	ds_read_b128 v[196:199], v150 offset:3072
	ds_read_b128 v[200:203], v150 offset:4096
	ds_read_b128 v[204:207], v150 offset:5120
	ds_read_b128 v[208:211], v150 offset:6144
	ds_read_b128 v[212:215], v150 offset:7168
	global_load_lds_dwordx4 v136, s[26:27]
	s_add_i32 m0, s54, 0xe000
	s_nop 0
	global_load_lds_dwordx4 v138, s[26:27]
	s_waitcnt vmcnt(8)
	s_waitcnt lgkmcnt(0)
	s_setprio 1
	s_barrier
	v_mfma_f32_16x16x32_bf16 v[124:127], v[144:147], v[184:187], v[124:127]
	v_mfma_f32_16x16x32_bf16 v[120:123], v[160:163], v[184:187], v[120:123]
	v_mfma_f32_16x16x32_bf16 v[108:111], v[144:147], v[192:195], v[108:111]
	v_mfma_f32_16x16x32_bf16 v[104:107], v[160:163], v[192:195], v[104:107]
	v_mfma_f32_16x16x32_bf16 v[92:95], v[144:147], v[200:203], v[92:95]
	v_mfma_f32_16x16x32_bf16 v[88:91], v[160:163], v[200:203], v[88:91]
	v_mfma_f32_16x16x32_bf16 v[76:79], v[144:147], v[208:211], v[76:79]
	v_mfma_f32_16x16x32_bf16 v[72:75], v[160:163], v[208:211], v[72:75]
	v_mfma_f32_16x16x32_bf16 v[124:127], v[152:155], v[188:191], v[124:127]
	v_mfma_f32_16x16x32_bf16 v[120:123], v[164:167], v[188:191], v[120:123]
	v_mfma_f32_16x16x32_bf16 v[108:111], v[152:155], v[196:199], v[108:111]
	v_mfma_f32_16x16x32_bf16 v[104:107], v[164:167], v[196:199], v[104:107]
	v_mfma_f32_16x16x32_bf16 v[92:95], v[152:155], v[204:207], v[92:95]
	v_mfma_f32_16x16x32_bf16 v[88:91], v[164:167], v[204:207], v[88:91]
	v_mfma_f32_16x16x32_bf16 v[76:79], v[152:155], v[212:215], v[76:79]
	v_mfma_f32_16x16x32_bf16 v[72:75], v[164:167], v[212:215], v[72:75]
	v_mfma_f32_16x16x32_bf16 v[116:119], v[168:171], v[184:187], v[116:119]
	v_mfma_f32_16x16x32_bf16 v[112:115], v[176:179], v[184:187], v[112:115]
	v_mfma_f32_16x16x32_bf16 v[100:103], v[168:171], v[192:195], v[100:103]
	v_mfma_f32_16x16x32_bf16 v[96:99], v[176:179], v[192:195], v[96:99]
	v_mfma_f32_16x16x32_bf16 v[84:87], v[168:171], v[200:203], v[84:87]
	v_mfma_f32_16x16x32_bf16 v[80:83], v[176:179], v[200:203], v[80:83]
	v_mfma_f32_16x16x32_bf16 v[68:71], v[168:171], v[208:211], v[68:71]
	v_mfma_f32_16x16x32_bf16 v[64:67], v[176:179], v[208:211], v[64:67]
	v_mfma_f32_16x16x32_bf16 v[116:119], v[172:175], v[188:191], v[116:119]
	v_mfma_f32_16x16x32_bf16 v[112:115], v[180:183], v[188:191], v[112:115]
	v_mfma_f32_16x16x32_bf16 v[100:103], v[172:175], v[196:199], v[100:103]
	v_mfma_f32_16x16x32_bf16 v[96:99], v[180:183], v[196:199], v[96:99]
	v_mfma_f32_16x16x32_bf16 v[84:87], v[172:175], v[204:207], v[84:87]
	v_mfma_f32_16x16x32_bf16 v[80:83], v[180:183], v[204:207], v[80:83]
	v_mfma_f32_16x16x32_bf16 v[68:71], v[172:175], v[212:215], v[68:71]
	s_setprio 0
	v_mfma_f32_16x16x32_bf16 v[64:67], v[180:183], v[212:215], v[64:67]
	s_barrier
	s_add_u32 s98, s46, s16
	s_addc_u32 s99, s47, s17
	s_add_u32 s100, s48, s16
	s_addc_u32 s101, s49, s17
	s_add_i32 s26, s61, s53
	s_mov_b32 m0, s26
	ds_read_b128 v[184:187], v150 offset:16384
	ds_read_b128 v[188:191], v150 offset:17408
	ds_read_b128 v[192:195], v150 offset:18432
	ds_read_b128 v[196:199], v150 offset:19456
	ds_read_b128 v[200:203], v150 offset:20480
	ds_read_b128 v[204:207], v150 offset:21504
	ds_read_b128 v[208:211], v150 offset:22528
	ds_read_b128 v[212:215], v150 offset:23552
	global_load_lds_dwordx4 v132, s[46:47]
	s_add_i32 m0, s26, 0x2000
	s_add_u32 s26, s46, 0x20000
	s_addc_u32 s27, s47, 0
	s_add_i32 s70, s62, s53
	global_load_lds_dwordx4 v134, s[46:47]
	s_mov_b32 m0, s70
	s_nop 0
	global_load_lds_dwordx4 v132, s[26:27]
	s_add_i32 m0, s70, 0x2000
	s_nop 0
	global_load_lds_dwordx4 v134, s[26:27]
	s_mov_b32 m0, s54
	s_nop 0
	global_load_lds_dwordx4 v128, s[48:49]
	s_mov_b32 m0, s55
	s_nop 0
	global_load_lds_dwordx4 v130, s[48:49]
	s_waitcnt vmcnt(8)
	s_waitcnt lgkmcnt(0)
	s_setprio 1
	s_barrier
	v_mfma_f32_16x16x32_bf16 v[60:63], v[144:147], v[184:187], v[60:63]
	v_mfma_f32_16x16x32_bf16 v[56:59], v[160:163], v[184:187], v[56:59]
	v_mfma_f32_16x16x32_bf16 v[44:47], v[144:147], v[192:195], v[44:47]
	v_mfma_f32_16x16x32_bf16 v[40:43], v[160:163], v[192:195], v[40:43]
	v_mfma_f32_16x16x32_bf16 v[28:31], v[144:147], v[200:203], v[28:31]
	v_mfma_f32_16x16x32_bf16 v[24:27], v[160:163], v[200:203], v[24:27]
	v_mfma_f32_16x16x32_bf16 v[12:15], v[144:147], v[208:211], v[12:15]
	v_mfma_f32_16x16x32_bf16 v[8:11], v[160:163], v[208:211], v[8:11]
	v_mfma_f32_16x16x32_bf16 v[60:63], v[152:155], v[188:191], v[60:63]
	v_mfma_f32_16x16x32_bf16 v[56:59], v[164:167], v[188:191], v[56:59]
	v_mfma_f32_16x16x32_bf16 v[44:47], v[152:155], v[196:199], v[44:47]
	v_mfma_f32_16x16x32_bf16 v[40:43], v[164:167], v[196:199], v[40:43]
	v_mfma_f32_16x16x32_bf16 v[28:31], v[152:155], v[204:207], v[28:31]
	v_mfma_f32_16x16x32_bf16 v[24:27], v[164:167], v[204:207], v[24:27]
	v_mfma_f32_16x16x32_bf16 v[12:15], v[152:155], v[212:215], v[12:15]
	v_mfma_f32_16x16x32_bf16 v[8:11], v[164:167], v[212:215], v[8:11]
	v_mfma_f32_16x16x32_bf16 v[52:55], v[168:171], v[184:187], v[52:55]
	v_mfma_f32_16x16x32_bf16 v[48:51], v[176:179], v[184:187], v[48:51]
	v_mfma_f32_16x16x32_bf16 v[36:39], v[168:171], v[192:195], v[36:39]
	v_mfma_f32_16x16x32_bf16 v[32:35], v[176:179], v[192:195], v[32:35]
	v_mfma_f32_16x16x32_bf16 v[20:23], v[168:171], v[200:203], v[20:23]
	v_mfma_f32_16x16x32_bf16 v[16:19], v[176:179], v[200:203], v[16:19]
	v_mfma_f32_16x16x32_bf16 v[4:7], v[168:171], v[208:211], v[4:7]
	v_mfma_f32_16x16x32_bf16 v[0:3], v[176:179], v[208:211], v[0:3]
	v_mfma_f32_16x16x32_bf16 v[52:55], v[172:175], v[188:191], v[52:55]
	v_mfma_f32_16x16x32_bf16 v[48:51], v[180:183], v[188:191], v[48:51]
	v_mfma_f32_16x16x32_bf16 v[36:39], v[172:175], v[196:199], v[36:39]
	v_mfma_f32_16x16x32_bf16 v[32:35], v[180:183], v[196:199], v[32:35]
	v_mfma_f32_16x16x32_bf16 v[20:23], v[172:175], v[204:207], v[20:23]
	v_mfma_f32_16x16x32_bf16 v[16:19], v[180:183], v[204:207], v[16:19]
	v_mfma_f32_16x16x32_bf16 v[4:7], v[172:175], v[212:215], v[4:7]
	s_setprio 0
	v_mfma_f32_16x16x32_bf16 v[0:3], v[180:183], v[212:215], v[0:3]
	s_barrier
; #define PG8_STAGE(bufoff, gbase, voff) do { _Pragma("unroll") for (int _i = 0; _i < 2; ++_i) \
;         __builtin_amdgcn_global_load_lds((const unsigned*)((const char*)(gbase) + (voff)[_i]), (LAS unsigned*)(lds + (bufoff) + ldsw + _i * 8192), 16, 0, 0); } while (0)
; #define PG8_LDA(dst, b, h) do { _Pragma("unroll") for (int m = 0; m < 4; ++m) _Pragma("unroll") for (int k = 0; k < 2; ++k) dst[m][k] = *(const LAS bf16x8*)(lds + PG8_SA(b, h) + aoff + m * 2048 + k * 1024); } while (0)
; #define PG8_LDB(dst, b, h) do { _Pragma("unroll") for (int n = 0; n < 2; ++n) _Pragma("unroll") for (int k = 0; k < 2; ++k) dst[n][k] = *(const LAS bf16x8*)(lds + PG8_SB(b, h) + boff + n * 2048 + k * 1024); } while (0)
; #define PG8_WAIT_V(n) asm volatile("s_waitcnt vmcnt(" #n ")" ::: "memory")
; #define PG8_WAIT_L(n) asm volatile("s_waitcnt lgkmcnt(" #n ")" ::: "memory")
; #define PG8_BAR __builtin_amdgcn_s_barrier()
; #define PG8_SCHED __builtin_amdgcn_sched_barrier(0)
; template <class Epi, bool FP8 = false>
; __device__ __forceinline__ void gemm_phase(LAS unsigned char* lds, const Gemm g, const StaticOrder& S_, const Epi& E, const int tid) {
;     ...
;             PG8_LDB(B0, 1, 0); PG8_LDB(B1, 1, 1); PG8_SCHED; PG8_LDA(At, 1, 0); PG8_STAGE(PG8_SA(0, 1), a2 + hstepA, voffA);
;             PG8_WAIT_V(8); PG8_WAIT_L(0); PG8_BAR; PG8_MMA(0, 0, At, B0); PG8_MMA(0, 1, At, B1); PG8_BAR; PG8_SCHED;
;             PG8_LDA(At, 1, 1); PG8_STAGE(PG8_SB(1, 0), b3, voffB); PG8_STAGE(PG8_SB(1, 1), b3 + hstepB, voffB); PG8_STAGE(PG8_SA(1, 0), a3, voffA);
;             PG8_WAIT_V(8); PG8_WAIT_L(0); PG8_BAR; PG8_MMA(1, 0, At, B0); PG8_MMA(1, 1, At, B1); PG8_BAR; PG8_SCHED;
;         }
;         if (wr == 0) PG8_BAR;
	s_add_i32 s70, 0, 0x18000
	v_add_u32_e32 v151, s70, v157
	s_add_i32 s71, 0, 0x1c000
	ds_read_b128 v[144:147], v151
	ds_read_b128 v[152:155], v151 offset:1024
	ds_read_b128 v[160:163], v151 offset:2048
	ds_read_b128 v[164:167], v151 offset:3072
	v_add_u32_e32 v151, s71, v157
	ds_read_b128 v[168:171], v151
	ds_read_b128 v[172:175], v151 offset:1024
	ds_read_b128 v[176:179], v151 offset:2048
	ds_read_b128 v[180:183], v151 offset:3072
	s_add_u32 s26, s48, 0x60000
	s_addc_u32 s27, s49, 0
	s_mov_b32 m0, s56
	ds_read_b128 v[184:187], v150 offset:32768
	ds_read_b128 v[188:191], v150 offset:33792
	ds_read_b128 v[192:195], v150 offset:34816
	ds_read_b128 v[196:199], v150 offset:35840
	ds_read_b128 v[200:203], v150 offset:36864
	ds_read_b128 v[204:207], v150 offset:37888
	ds_read_b128 v[208:211], v150 offset:38912
	ds_read_b128 v[212:215], v150 offset:39936
	global_load_lds_dwordx4 v128, s[26:27]
	s_mov_b32 m0, s57
	s_nop 0
	global_load_lds_dwordx4 v130, s[26:27]
	s_waitcnt vmcnt(8)
	s_waitcnt lgkmcnt(0)
	s_setprio 1
	s_barrier
	v_mfma_f32_16x16x32_bf16 v[124:127], v[144:147], v[184:187], v[124:127]
	v_mfma_f32_16x16x32_bf16 v[120:123], v[160:163], v[184:187], v[120:123]
	v_mfma_f32_16x16x32_bf16 v[108:111], v[144:147], v[192:195], v[108:111]
	v_mfma_f32_16x16x32_bf16 v[104:107], v[160:163], v[192:195], v[104:107]
	v_mfma_f32_16x16x32_bf16 v[92:95], v[144:147], v[200:203], v[92:95]
	v_mfma_f32_16x16x32_bf16 v[88:91], v[160:163], v[200:203], v[88:91]
	v_mfma_f32_16x16x32_bf16 v[76:79], v[144:147], v[208:211], v[76:79]
	v_mfma_f32_16x16x32_bf16 v[72:75], v[160:163], v[208:211], v[72:75]
	v_mfma_f32_16x16x32_bf16 v[124:127], v[152:155], v[188:191], v[124:127]
	v_mfma_f32_16x16x32_bf16 v[120:123], v[164:167], v[188:191], v[120:123]
	v_mfma_f32_16x16x32_bf16 v[108:111], v[152:155], v[196:199], v[108:111]
	v_mfma_f32_16x16x32_bf16 v[104:107], v[164:167], v[196:199], v[104:107]
	v_mfma_f32_16x16x32_bf16 v[92:95], v[152:155], v[204:207], v[92:95]
	v_mfma_f32_16x16x32_bf16 v[88:91], v[164:167], v[204:207], v[88:91]
	v_mfma_f32_16x16x32_bf16 v[76:79], v[152:155], v[212:215], v[76:79]
	v_mfma_f32_16x16x32_bf16 v[72:75], v[164:167], v[212:215], v[72:75]
	v_mfma_f32_16x16x32_bf16 v[116:119], v[168:171], v[184:187], v[116:119]
	v_mfma_f32_16x16x32_bf16 v[112:115], v[176:179], v[184:187], v[112:115]
	v_mfma_f32_16x16x32_bf16 v[100:103], v[168:171], v[192:195], v[100:103]
	v_mfma_f32_16x16x32_bf16 v[96:99], v[176:179], v[192:195], v[96:99]
	v_mfma_f32_16x16x32_bf16 v[84:87], v[168:171], v[200:203], v[84:87]
	v_mfma_f32_16x16x32_bf16 v[80:83], v[176:179], v[200:203], v[80:83]
	v_mfma_f32_16x16x32_bf16 v[68:71], v[168:171], v[208:211], v[68:71]
	v_mfma_f32_16x16x32_bf16 v[64:67], v[176:179], v[208:211], v[64:67]
	v_mfma_f32_16x16x32_bf16 v[116:119], v[172:175], v[188:191], v[116:119]
	v_mfma_f32_16x16x32_bf16 v[112:115], v[180:183], v[188:191], v[112:115]
	v_mfma_f32_16x16x32_bf16 v[100:103], v[172:175], v[196:199], v[100:103]
	v_mfma_f32_16x16x32_bf16 v[96:99], v[180:183], v[196:199], v[96:99]
	v_mfma_f32_16x16x32_bf16 v[84:87], v[172:175], v[204:207], v[84:87]
	v_mfma_f32_16x16x32_bf16 v[80:83], v[180:183], v[204:207], v[80:83]
	v_mfma_f32_16x16x32_bf16 v[68:71], v[172:175], v[212:215], v[68:71]
	s_setprio 0
	v_mfma_f32_16x16x32_bf16 v[64:67], v[180:183], v[212:215], v[64:67]
	s_barrier
	s_add_i32 s26, s70, s53
	s_mov_b32 m0, s26
	ds_read_b128 v[184:187], v150 offset:49152
	ds_read_b128 v[188:191], v150 offset:50176
	ds_read_b128 v[192:195], v150 offset:51200
	ds_read_b128 v[196:199], v150 offset:52224
	ds_read_b128 v[200:203], v150 offset:53248
	ds_read_b128 v[204:207], v150 offset:54272
	ds_read_b128 v[208:211], v150 offset:55296
	ds_read_b128 v[212:215], v150 offset:56320
	global_load_lds_dwordx4 v132, s[98:99]
	s_add_i32 m0, s26, 0x2000
	s_add_u32 s26, s46, 0x20080
	s_addc_u32 s27, s47, 0
	s_add_i32 s46, s71, s53
	global_load_lds_dwordx4 v134, s[98:99]
	s_mov_b32 m0, s46
	s_nop 0
	global_load_lds_dwordx4 v132, s[26:27]
	s_add_i32 m0, s46, 0x2000
	s_nop 0
	global_load_lds_dwordx4 v134, s[26:27]
	s_mov_b32 m0, s59
	s_nop 0
	global_load_lds_dwordx4 v128, s[100:101]
	s_mov_b32 m0, s60
	s_nop 0
	global_load_lds_dwordx4 v130, s[100:101]
	s_waitcnt vmcnt(8)
	s_waitcnt lgkmcnt(0)
	s_setprio 1
	s_barrier
	v_mfma_f32_16x16x32_bf16 v[60:63], v[144:147], v[184:187], v[60:63]
	v_mfma_f32_16x16x32_bf16 v[56:59], v[160:163], v[184:187], v[56:59]
	v_mfma_f32_16x16x32_bf16 v[44:47], v[144:147], v[192:195], v[44:47]
	v_mfma_f32_16x16x32_bf16 v[40:43], v[160:163], v[192:195], v[40:43]
	v_mfma_f32_16x16x32_bf16 v[28:31], v[144:147], v[200:203], v[28:31]
	v_mfma_f32_16x16x32_bf16 v[24:27], v[160:163], v[200:203], v[24:27]
	v_mfma_f32_16x16x32_bf16 v[12:15], v[144:147], v[208:211], v[12:15]
	v_mfma_f32_16x16x32_bf16 v[8:11], v[160:163], v[208:211], v[8:11]
	v_mfma_f32_16x16x32_bf16 v[60:63], v[152:155], v[188:191], v[60:63]
	v_mfma_f32_16x16x32_bf16 v[56:59], v[164:167], v[188:191], v[56:59]
	v_mfma_f32_16x16x32_bf16 v[44:47], v[152:155], v[196:199], v[44:47]
	v_mfma_f32_16x16x32_bf16 v[40:43], v[164:167], v[196:199], v[40:43]
	v_mfma_f32_16x16x32_bf16 v[28:31], v[152:155], v[204:207], v[28:31]
	v_mfma_f32_16x16x32_bf16 v[24:27], v[164:167], v[204:207], v[24:27]
	v_mfma_f32_16x16x32_bf16 v[12:15], v[152:155], v[212:215], v[12:15]
	v_mfma_f32_16x16x32_bf16 v[8:11], v[164:167], v[212:215], v[8:11]
	v_mfma_f32_16x16x32_bf16 v[52:55], v[168:171], v[184:187], v[52:55]
	v_mfma_f32_16x16x32_bf16 v[48:51], v[176:179], v[184:187], v[48:51]
	v_mfma_f32_16x16x32_bf16 v[36:39], v[168:171], v[192:195], v[36:39]
	v_mfma_f32_16x16x32_bf16 v[32:35], v[176:179], v[192:195], v[32:35]
	v_mfma_f32_16x16x32_bf16 v[20:23], v[168:171], v[200:203], v[20:23]
	v_mfma_f32_16x16x32_bf16 v[16:19], v[176:179], v[200:203], v[16:19]
	v_mfma_f32_16x16x32_bf16 v[4:7], v[168:171], v[208:211], v[4:7]
	v_mfma_f32_16x16x32_bf16 v[0:3], v[176:179], v[208:211], v[0:3]
	v_mfma_f32_16x16x32_bf16 v[52:55], v[172:175], v[188:191], v[52:55]
	v_mfma_f32_16x16x32_bf16 v[48:51], v[180:183], v[188:191], v[48:51]
	v_mfma_f32_16x16x32_bf16 v[36:39], v[172:175], v[196:199], v[36:39]
	v_mfma_f32_16x16x32_bf16 v[32:35], v[180:183], v[196:199], v[32:35]
	v_mfma_f32_16x16x32_bf16 v[20:23], v[172:175], v[204:207], v[20:23]
	v_mfma_f32_16x16x32_bf16 v[16:19], v[180:183], v[204:207], v[16:19]
	v_mfma_f32_16x16x32_bf16 v[4:7], v[172:175], v[212:215], v[4:7]
	s_setprio 0
	v_mfma_f32_16x16x32_bf16 v[0:3], v[180:183], v[212:215], v[0:3]
	s_barrier
	s_add_i32 s69, s69, 2
	s_add_u32 s67, s67, 0x100
	s_addc_u32 s68, s68, 0
	s_cmp_gt_u32 s69, 5
	s_mov_b64 s[26:27], s[8:9]
	s_cbranch_scc0 .LBB0_1121
	s_and_b64 vcc, exec, s[18:19]
	s_cbranch_vccz .LBB0_1124
	s_barrier

; #define PG8_STAGE(bufoff, gbase, voff) do { _Pragma("unroll") for (int _i = 0; _i < 2; ++_i) \
;         __builtin_amdgcn_global_load_lds((const unsigned*)((const char*)(gbase) + (voff)[_i]), (LAS unsigned*)(lds + (bufoff) + ldsw + _i * 8192), 16, 0, 0); } while (0)
; #define PG8_LDA(dst, b, h) do { _Pragma("unroll") for (int m = 0; m < 4; ++m) _Pragma("unroll") for (int k = 0; k < 2; ++k) dst[m][k] = *(const LAS bf16x8*)(lds + PG8_SA(b, h) + aoff + m * 2048 + k * 1024); } while (0)
; #define PG8_LDB(dst, b, h) do { _Pragma("unroll") for (int n = 0; n < 2; ++n) _Pragma("unroll") for (int k = 0; k < 2; ++k) dst[n][k] = *(const LAS bf16x8*)(lds + PG8_SB(b, h) + boff + n * 2048 + k * 1024); } while (0)
; #define PG8_WAIT_V(n) asm volatile("s_waitcnt vmcnt(" #n ")" ::: "memory")
; #define PG8_WAIT_L(n) asm volatile("s_waitcnt lgkmcnt(" #n ")" ::: "memory")
; #define PG8_BAR __builtin_amdgcn_s_barrier()
; #define PG8_SCHED __builtin_amdgcn_sched_barrier(0)
; template <class Epi, bool FP8 = false>
; __device__ __forceinline__ void gemm_phase(LAS unsigned char* lds, const Gemm g, const StaticOrder& S_, const Epi& E, const int tid) {
;     ...
;             const bool last = (t == nt - 2);
;             const char* a1 = cA + (size_t)(t + 1) * kstep;
;             const char* a2 = last ? nA : cA + (size_t)(t + 2) * kstep; const char* b2 = last ? nB : cB + (size_t)(t + 2) * kstep;
;             const char* a3 = a2 + kstep; const char* b3 = b2 + kstep;
;             PG8_LDB(B0, 0, 0); PG8_LDB(B1, 0, 1); PG8_SCHED; PG8_LDA(At, 0, 0); PG8_STAGE(PG8_SA(1, 1), a1 + hstepA, voffA);
;             PG8_WAIT_V(8); PG8_WAIT_L(0); PG8_BAR; PG8_MMA(0, 0, At, B0); PG8_MMA(0, 1, At, B1); PG8_BAR; PG8_SCHED;
;             PG8_LDA(At, 0, 1); PG8_STAGE(PG8_SB(0, 0), b2, voffB); PG8_STAGE(PG8_SB(0, 1), b2 + hstepB, voffB); PG8_STAGE(PG8_SA(0, 0), a2, voffA);
;             PG8_WAIT_V(8); PG8_WAIT_L(0); PG8_BAR; PG8_MMA(1, 0, At, B0); PG8_MMA(1, 1, At, B1); PG8_BAR; PG8_SCHED;
.LBB0_1197:
	ds_read_b128 v[140:143], v152
	ds_read_b128 v[144:147], v152 offset:1024
	ds_read_b128 v[156:159], v152 offset:2048
	ds_read_b128 v[160:163], v152 offset:3072
	ds_read_b128 v[164:167], v153
	ds_read_b128 v[168:171], v153 offset:1024
	ds_read_b128 v[172:175], v153 offset:2048
	ds_read_b128 v[176:179], v153 offset:3072
	s_add_u32 s50, s48, 0xfff80080
	s_addc_u32 s51, s49, -1
	s_cmp_eq_u32 s70, 28
	s_cselect_b32 s53, s23, s51
	s_cselect_b32 s52, s43, s50
	s_cselect_b32 s51, s21, s69
	s_cselect_b32 s50, s66, s68
	s_add_i32 m0, s47, 0xc000
	ds_read_b128 v[180:183], v154
	ds_read_b128 v[184:187], v154 offset:1024
	ds_read_b128 v[188:191], v154 offset:2048
	ds_read_b128 v[192:195], v154 offset:3072
	ds_read_b128 v[196:199], v154 offset:4096
	ds_read_b128 v[200:203], v154 offset:5120
	ds_read_b128 v[204:207], v154 offset:6144
	ds_read_b128 v[208:211], v154 offset:7168
	global_load_lds_dwordx4 v132, s[48:49]
	s_add_i32 m0, s47, 0xe000
	s_nop 0
	global_load_lds_dwordx4 v134, s[48:49]
	s_waitcnt vmcnt(8)
	s_waitcnt lgkmcnt(0)
	s_setprio 1
	s_barrier
	v_mfma_f32_16x16x32_bf16 v[124:127], v[140:143], v[180:183], v[124:127]
	v_mfma_f32_16x16x32_bf16 v[120:123], v[156:159], v[180:183], v[120:123]
	v_mfma_f32_16x16x32_bf16 v[108:111], v[140:143], v[188:191], v[108:111]
	v_mfma_f32_16x16x32_bf16 v[104:107], v[156:159], v[188:191], v[104:107]
	v_mfma_f32_16x16x32_bf16 v[92:95], v[140:143], v[196:199], v[92:95]
	v_mfma_f32_16x16x32_bf16 v[88:91], v[156:159], v[196:199], v[88:91]
	v_mfma_f32_16x16x32_bf16 v[76:79], v[140:143], v[204:207], v[76:79]
	v_mfma_f32_16x16x32_bf16 v[72:75], v[156:159], v[204:207], v[72:75]
	v_mfma_f32_16x16x32_bf16 v[124:127], v[144:147], v[184:187], v[124:127]
	v_mfma_f32_16x16x32_bf16 v[120:123], v[160:163], v[184:187], v[120:123]
	v_mfma_f32_16x16x32_bf16 v[108:111], v[144:147], v[192:195], v[108:111]
	v_mfma_f32_16x16x32_bf16 v[104:107], v[160:163], v[192:195], v[104:107]
	v_mfma_f32_16x16x32_bf16 v[92:95], v[144:147], v[200:203], v[92:95]
	v_mfma_f32_16x16x32_bf16 v[88:91], v[160:163], v[200:203], v[88:91]
	v_mfma_f32_16x16x32_bf16 v[76:79], v[144:147], v[208:211], v[76:79]
	v_mfma_f32_16x16x32_bf16 v[72:75], v[160:163], v[208:211], v[72:75]
	v_mfma_f32_16x16x32_bf16 v[116:119], v[164:167], v[180:183], v[116:119]
	v_mfma_f32_16x16x32_bf16 v[112:115], v[172:175], v[180:183], v[112:115]
	v_mfma_f32_16x16x32_bf16 v[100:103], v[164:167], v[188:191], v[100:103]
	v_mfma_f32_16x16x32_bf16 v[96:99], v[172:175], v[188:191], v[96:99]
	v_mfma_f32_16x16x32_bf16 v[84:87], v[164:167], v[196:199], v[84:87]
	v_mfma_f32_16x16x32_bf16 v[80:83], v[172:175], v[196:199], v[80:83]
	v_mfma_f32_16x16x32_bf16 v[68:71], v[164:167], v[204:207], v[68:71]
	v_mfma_f32_16x16x32_bf16 v[64:67], v[172:175], v[204:207], v[64:67]
	v_mfma_f32_16x16x32_bf16 v[116:119], v[168:171], v[184:187], v[116:119]
	v_mfma_f32_16x16x32_bf16 v[112:115], v[176:179], v[184:187], v[112:115]
	v_mfma_f32_16x16x32_bf16 v[100:103], v[168:171], v[192:195], v[100:103]
	v_mfma_f32_16x16x32_bf16 v[96:99], v[176:179], v[192:195], v[96:99]
	v_mfma_f32_16x16x32_bf16 v[84:87], v[168:171], v[200:203], v[84:87]
	v_mfma_f32_16x16x32_bf16 v[80:83], v[176:179], v[200:203], v[80:83]
	v_mfma_f32_16x16x32_bf16 v[68:71], v[168:171], v[208:211], v[68:71]
	s_setprio 0
	v_mfma_f32_16x16x32_bf16 v[64:67], v[176:179], v[208:211], v[64:67]
	s_barrier
	s_add_u32 s98, s50, s14
	s_addc_u32 s99, s51, s15
	s_add_u32 s100, s52, s14
	s_addc_u32 s101, s53, s15
	s_add_i32 s71, s63, s56
	s_mov_b32 m0, s71
	ds_read_b128 v[180:183], v154 offset:16384
	ds_read_b128 v[184:187], v154 offset:17408
	ds_read_b128 v[188:191], v154 offset:18432
	ds_read_b128 v[192:195], v154 offset:19456
	ds_read_b128 v[196:199], v154 offset:20480
	ds_read_b128 v[200:203], v154 offset:21504
	ds_read_b128 v[204:207], v154 offset:22528
	ds_read_b128 v[208:211], v154 offset:23552
	global_load_lds_dwordx4 v128, s[50:51]
	s_add_i32 m0, s71, 0x2000
	s_add_u32 s72, s50, 0x80000
	s_addc_u32 s73, s51, 0
	s_add_i32 s71, s67, s56
	global_load_lds_dwordx4 v130, s[50:51]
	s_mov_b32 m0, s71
	s_nop 0
	global_load_lds_dwordx4 v128, s[72:73]
	s_add_i32 m0, s71, 0x2000
	s_nop 0
	global_load_lds_dwordx4 v130, s[72:73]
	s_mov_b32 m0, s47
	s_nop 0
	global_load_lds_dwordx4 v128, s[52:53]
	s_mov_b32 m0, s57
	s_nop 0
	global_load_lds_dwordx4 v130, s[52:53]
	s_waitcnt vmcnt(8)
	s_waitcnt lgkmcnt(0)
	s_setprio 1
	s_barrier
	v_mfma_f32_16x16x32_bf16 v[60:63], v[140:143], v[180:183], v[60:63]
	v_mfma_f32_16x16x32_bf16 v[56:59], v[156:159], v[180:183], v[56:59]
	v_mfma_f32_16x16x32_bf16 v[44:47], v[140:143], v[188:191], v[44:47]
	v_mfma_f32_16x16x32_bf16 v[40:43], v[156:159], v[188:191], v[40:43]
	v_mfma_f32_16x16x32_bf16 v[28:31], v[140:143], v[196:199], v[28:31]
	v_mfma_f32_16x16x32_bf16 v[24:27], v[156:159], v[196:199], v[24:27]
	v_mfma_f32_16x16x32_bf16 v[12:15], v[140:143], v[204:207], v[12:15]
	v_mfma_f32_16x16x32_bf16 v[8:11], v[156:159], v[204:207], v[8:11]
	v_mfma_f32_16x16x32_bf16 v[60:63], v[144:147], v[184:187], v[60:63]
	v_mfma_f32_16x16x32_bf16 v[56:59], v[160:163], v[184:187], v[56:59]
	v_mfma_f32_16x16x32_bf16 v[44:47], v[144:147], v[192:195], v[44:47]
	v_mfma_f32_16x16x32_bf16 v[40:43], v[160:163], v[192:195], v[40:43]
	v_mfma_f32_16x16x32_bf16 v[28:31], v[144:147], v[200:203], v[28:31]
	v_mfma_f32_16x16x32_bf16 v[24:27], v[160:163], v[200:203], v[24:27]
	v_mfma_f32_16x16x32_bf16 v[12:15], v[144:147], v[208:211], v[12:15]
	v_mfma_f32_16x16x32_bf16 v[8:11], v[160:163], v[208:211], v[8:11]
	v_mfma_f32_16x16x32_bf16 v[52:55], v[164:167], v[180:183], v[52:55]
	v_mfma_f32_16x16x32_bf16 v[48:51], v[172:175], v[180:183], v[48:51]
	v_mfma_f32_16x16x32_bf16 v[36:39], v[164:167], v[188:191], v[36:39]
	v_mfma_f32_16x16x32_bf16 v[32:35], v[172:175], v[188:191], v[32:35]
	v_mfma_f32_16x16x32_bf16 v[20:23], v[164:167], v[196:199], v[20:23]
	v_mfma_f32_16x16x32_bf16 v[16:19], v[172:175], v[196:199], v[16:19]
	v_mfma_f32_16x16x32_bf16 v[4:7], v[164:167], v[204:207], v[4:7]
	v_mfma_f32_16x16x32_bf16 v[0:3], v[172:175], v[204:207], v[0:3]
	v_mfma_f32_16x16x32_bf16 v[52:55], v[168:171], v[184:187], v[52:55]
	v_mfma_f32_16x16x32_bf16 v[48:51], v[176:179], v[184:187], v[48:51]
	v_mfma_f32_16x16x32_bf16 v[36:39], v[168:171], v[192:195], v[36:39]
	v_mfma_f32_16x16x32_bf16 v[32:35], v[176:179], v[192:195], v[32:35]
	v_mfma_f32_16x16x32_bf16 v[20:23], v[168:171], v[200:203], v[20:23]
	v_mfma_f32_16x16x32_bf16 v[16:19], v[176:179], v[200:203], v[16:19]
	v_mfma_f32_16x16x32_bf16 v[4:7], v[168:171], v[208:211], v[4:7]
	s_setprio 0
	v_mfma_f32_16x16x32_bf16 v[0:3], v[176:179], v[208:211], v[0:3]
	s_barrier
; #define PG8_STAGE(bufoff, gbase, voff) do { _Pragma("unroll") for (int _i = 0; _i < 2; ++_i) \
;         __builtin_amdgcn_global_load_lds((const unsigned*)((const char*)(gbase) + (voff)[_i]), (LAS unsigned*)(lds + (bufoff) + ldsw + _i * 8192), 16, 0, 0); } while (0)
; #define PG8_LDA(dst, b, h) do { _Pragma("unroll") for (int m = 0; m < 4; ++m) _Pragma("unroll") for (int k = 0; k < 2; ++k) dst[m][k] = *(const LAS bf16x8*)(lds + PG8_SA(b, h) + aoff + m * 2048 + k * 1024); } while (0)
; #define PG8_LDB(dst, b, h) do { _Pragma("unroll") for (int n = 0; n < 2; ++n) _Pragma("unroll") for (int k = 0; k < 2; ++k) dst[n][k] = *(const LAS bf16x8*)(lds + PG8_SB(b, h) + boff + n * 2048 + k * 1024); } while (0)
; #define PG8_WAIT_V(n) asm volatile("s_waitcnt vmcnt(" #n ")" ::: "memory")
; #define PG8_WAIT_L(n) asm volatile("s_waitcnt lgkmcnt(" #n ")" ::: "memory")
; #define PG8_BAR __builtin_amdgcn_s_barrier()
; #define PG8_SCHED __builtin_amdgcn_sched_barrier(0)
; template <class Epi, bool FP8 = false>
; __device__ __forceinline__ void gemm_phase(LAS unsigned char* lds, const Gemm g, const StaticOrder& S_, const Epi& E, const int tid) {
;     ...
;             PG8_LDB(B0, 1, 0); PG8_LDB(B1, 1, 1); PG8_SCHED; PG8_LDA(At, 1, 0); PG8_STAGE(PG8_SA(0, 1), a2 + hstepA, voffA);
;             PG8_WAIT_V(8); PG8_WAIT_L(0); PG8_BAR; PG8_MMA(0, 0, At, B0); PG8_MMA(0, 1, At, B1); PG8_BAR; PG8_SCHED;
;             PG8_LDA(At, 1, 1); PG8_STAGE(PG8_SB(1, 0), b3, voffB); PG8_STAGE(PG8_SB(1, 1), b3 + hstepB, voffB); PG8_STAGE(PG8_SA(1, 0), a3, voffA);
;             PG8_WAIT_V(8); PG8_WAIT_L(0); PG8_BAR; PG8_MMA(1, 0, At, B0); PG8_MMA(1, 1, At, B1); PG8_BAR; PG8_SCHED;
;         }
;         if (wr == 0) PG8_BAR;
	s_add_i32 s71, 0, 0x18000
	v_add_u32_e32 v155, s71, v150
	s_add_i32 s72, 0, 0x1c000
	ds_read_b128 v[140:143], v155
	ds_read_b128 v[144:147], v155 offset:1024
	ds_read_b128 v[156:159], v155 offset:2048
	ds_read_b128 v[160:163], v155 offset:3072
	v_add_u32_e32 v155, s72, v150
	ds_read_b128 v[164:167], v155
	ds_read_b128 v[168:171], v155 offset:1024
	ds_read_b128 v[172:175], v155 offset:2048
	ds_read_b128 v[176:179], v155 offset:3072
	s_add_u32 s52, s52, 0x80000
	s_addc_u32 s53, s53, 0
	s_mov_b32 m0, s58
	ds_read_b128 v[180:183], v154 offset:32768
	ds_read_b128 v[184:187], v154 offset:33792
	ds_read_b128 v[188:191], v154 offset:34816
	ds_read_b128 v[192:195], v154 offset:35840
	ds_read_b128 v[196:199], v154 offset:36864
	ds_read_b128 v[200:203], v154 offset:37888
	ds_read_b128 v[204:207], v154 offset:38912
	ds_read_b128 v[208:211], v154 offset:39936
	global_load_lds_dwordx4 v128, s[52:53]
	s_mov_b32 m0, s59
	s_nop 0
	global_load_lds_dwordx4 v130, s[52:53]
	s_waitcnt vmcnt(8)
	s_waitcnt lgkmcnt(0)
	s_setprio 1
	s_barrier
	v_mfma_f32_16x16x32_bf16 v[124:127], v[140:143], v[180:183], v[124:127]
	v_mfma_f32_16x16x32_bf16 v[120:123], v[156:159], v[180:183], v[120:123]
	v_mfma_f32_16x16x32_bf16 v[108:111], v[140:143], v[188:191], v[108:111]
	v_mfma_f32_16x16x32_bf16 v[104:107], v[156:159], v[188:191], v[104:107]
	v_mfma_f32_16x16x32_bf16 v[92:95], v[140:143], v[196:199], v[92:95]
	v_mfma_f32_16x16x32_bf16 v[88:91], v[156:159], v[196:199], v[88:91]
	v_mfma_f32_16x16x32_bf16 v[76:79], v[140:143], v[204:207], v[76:79]
	v_mfma_f32_16x16x32_bf16 v[72:75], v[156:159], v[204:207], v[72:75]
	v_mfma_f32_16x16x32_bf16 v[124:127], v[144:147], v[184:187], v[124:127]
	v_mfma_f32_16x16x32_bf16 v[120:123], v[160:163], v[184:187], v[120:123]
	v_mfma_f32_16x16x32_bf16 v[108:111], v[144:147], v[192:195], v[108:111]
	v_mfma_f32_16x16x32_bf16 v[104:107], v[160:163], v[192:195], v[104:107]
	v_mfma_f32_16x16x32_bf16 v[92:95], v[144:147], v[200:203], v[92:95]
	v_mfma_f32_16x16x32_bf16 v[88:91], v[160:163], v[200:203], v[88:91]
	v_mfma_f32_16x16x32_bf16 v[76:79], v[144:147], v[208:211], v[76:79]
	v_mfma_f32_16x16x32_bf16 v[72:75], v[160:163], v[208:211], v[72:75]
	v_mfma_f32_16x16x32_bf16 v[116:119], v[164:167], v[180:183], v[116:119]
	v_mfma_f32_16x16x32_bf16 v[112:115], v[172:175], v[180:183], v[112:115]
	v_mfma_f32_16x16x32_bf16 v[100:103], v[164:167], v[188:191], v[100:103]
	v_mfma_f32_16x16x32_bf16 v[96:99], v[172:175], v[188:191], v[96:99]
	v_mfma_f32_16x16x32_bf16 v[84:87], v[164:167], v[196:199], v[84:87]
	v_mfma_f32_16x16x32_bf16 v[80:83], v[172:175], v[196:199], v[80:83]
	v_mfma_f32_16x16x32_bf16 v[68:71], v[164:167], v[204:207], v[68:71]
	v_mfma_f32_16x16x32_bf16 v[64:67], v[172:175], v[204:207], v[64:67]
	v_mfma_f32_16x16x32_bf16 v[116:119], v[168:171], v[184:187], v[116:119]
	v_mfma_f32_16x16x32_bf16 v[112:115], v[176:179], v[184:187], v[112:115]
	v_mfma_f32_16x16x32_bf16 v[100:103], v[168:171], v[192:195], v[100:103]
	v_mfma_f32_16x16x32_bf16 v[96:99], v[176:179], v[192:195], v[96:99]
	v_mfma_f32_16x16x32_bf16 v[84:87], v[168:171], v[200:203], v[84:87]
	v_mfma_f32_16x16x32_bf16 v[80:83], v[176:179], v[200:203], v[80:83]
	v_mfma_f32_16x16x32_bf16 v[68:71], v[168:171], v[208:211], v[68:71]
	s_setprio 0
	v_mfma_f32_16x16x32_bf16 v[64:67], v[176:179], v[208:211], v[64:67]
	s_barrier
	s_add_i32 s52, s71, s56
	s_mov_b32 m0, s52
	ds_read_b128 v[180:183], v154 offset:49152
	ds_read_b128 v[184:187], v154 offset:50176
	ds_read_b128 v[188:191], v154 offset:51200
	ds_read_b128 v[192:195], v154 offset:52224
	ds_read_b128 v[196:199], v154 offset:53248
	ds_read_b128 v[200:203], v154 offset:54272
	ds_read_b128 v[204:207], v154 offset:55296
	ds_read_b128 v[208:211], v154 offset:56320
	global_load_lds_dwordx4 v128, s[98:99]
	s_add_i32 m0, s52, 0x2000
	s_add_u32 s50, s50, 0x80080
	s_addc_u32 s51, s51, 0
	s_add_i32 s52, s72, s56
	global_load_lds_dwordx4 v130, s[98:99]
	s_mov_b32 m0, s52
	s_nop 0
	global_load_lds_dwordx4 v128, s[50:51]
	s_add_i32 m0, s52, 0x2000
	s_nop 0
	global_load_lds_dwordx4 v130, s[50:51]
	s_mov_b32 m0, s61
	s_nop 0
	global_load_lds_dwordx4 v128, s[100:101]
	s_mov_b32 m0, s62
	s_nop 0
	global_load_lds_dwordx4 v130, s[100:101]
	s_waitcnt vmcnt(8)
	s_waitcnt lgkmcnt(0)
	s_setprio 1
	s_barrier
	v_mfma_f32_16x16x32_bf16 v[60:63], v[140:143], v[180:183], v[60:63]
	v_mfma_f32_16x16x32_bf16 v[56:59], v[156:159], v[180:183], v[56:59]
	v_mfma_f32_16x16x32_bf16 v[44:47], v[140:143], v[188:191], v[44:47]
	v_mfma_f32_16x16x32_bf16 v[40:43], v[156:159], v[188:191], v[40:43]
	v_mfma_f32_16x16x32_bf16 v[28:31], v[140:143], v[196:199], v[28:31]
	v_mfma_f32_16x16x32_bf16 v[24:27], v[156:159], v[196:199], v[24:27]
	v_mfma_f32_16x16x32_bf16 v[12:15], v[140:143], v[204:207], v[12:15]
	v_mfma_f32_16x16x32_bf16 v[8:11], v[156:159], v[204:207], v[8:11]
	v_mfma_f32_16x16x32_bf16 v[60:63], v[144:147], v[184:187], v[60:63]
	v_mfma_f32_16x16x32_bf16 v[56:59], v[160:163], v[184:187], v[56:59]
	v_mfma_f32_16x16x32_bf16 v[44:47], v[144:147], v[192:195], v[44:47]
	v_mfma_f32_16x16x32_bf16 v[40:43], v[160:163], v[192:195], v[40:43]
	v_mfma_f32_16x16x32_bf16 v[28:31], v[144:147], v[200:203], v[28:31]
	v_mfma_f32_16x16x32_bf16 v[24:27], v[160:163], v[200:203], v[24:27]
	v_mfma_f32_16x16x32_bf16 v[12:15], v[144:147], v[208:211], v[12:15]
	v_mfma_f32_16x16x32_bf16 v[8:11], v[160:163], v[208:211], v[8:11]
	v_mfma_f32_16x16x32_bf16 v[52:55], v[164:167], v[180:183], v[52:55]
	v_mfma_f32_16x16x32_bf16 v[48:51], v[172:175], v[180:183], v[48:51]
	v_mfma_f32_16x16x32_bf16 v[36:39], v[164:167], v[188:191], v[36:39]
	v_mfma_f32_16x16x32_bf16 v[32:35], v[172:175], v[188:191], v[32:35]
	v_mfma_f32_16x16x32_bf16 v[20:23], v[164:167], v[196:199], v[20:23]
	v_mfma_f32_16x16x32_bf16 v[16:19], v[172:175], v[196:199], v[16:19]
	v_mfma_f32_16x16x32_bf16 v[4:7], v[164:167], v[204:207], v[4:7]
	v_mfma_f32_16x16x32_bf16 v[0:3], v[172:175], v[204:207], v[0:3]
	v_mfma_f32_16x16x32_bf16 v[52:55], v[168:171], v[184:187], v[52:55]
	v_mfma_f32_16x16x32_bf16 v[48:51], v[176:179], v[184:187], v[48:51]
	v_mfma_f32_16x16x32_bf16 v[36:39], v[168:171], v[192:195], v[36:39]
	v_mfma_f32_16x16x32_bf16 v[32:35], v[176:179], v[192:195], v[32:35]
	v_mfma_f32_16x16x32_bf16 v[20:23], v[168:171], v[200:203], v[20:23]
	v_mfma_f32_16x16x32_bf16 v[16:19], v[176:179], v[200:203], v[16:19]
	v_mfma_f32_16x16x32_bf16 v[4:7], v[168:171], v[208:211], v[4:7]
	s_setprio 0
	v_mfma_f32_16x16x32_bf16 v[0:3], v[176:179], v[208:211], v[0:3]
	s_barrier
	s_add_i32 s70, s70, 2
	s_add_u32 s48, s48, 0x100
	s_addc_u32 s49, s49, 0
	s_add_u32 s68, s68, 0x100
	s_addc_u32 s69, s69, 0
	s_cmp_gt_u32 s70, 29
	s_cbranch_scc0 .LBB0_1197
	s_and_b64 vcc, exec, s[16:17]
	s_cbranch_vccz .LBB0_1200
	s_barrier

; #define PG8_STAGE(bufoff, gbase, voff) do { _Pragma("unroll") for (int _i = 0; _i < 2; ++_i) \
;         __builtin_amdgcn_global_load_lds((const unsigned*)((const char*)(gbase) + (voff)[_i]), (LAS unsigned*)(lds + (bufoff) + ldsw + _i * 8192), 16, 0, 0); } while (0)
; #define PG8_LDA(dst, b, h) do { _Pragma("unroll") for (int m = 0; m < 4; ++m) _Pragma("unroll") for (int k = 0; k < 2; ++k) dst[m][k] = *(const LAS bf16x8*)(lds + PG8_SA(b, h) + aoff + m * 2048 + k * 1024); } while (0)
; #define PG8_LDB(dst, b, h) do { _Pragma("unroll") for (int n = 0; n < 2; ++n) _Pragma("unroll") for (int k = 0; k < 2; ++k) dst[n][k] = *(const LAS bf16x8*)(lds + PG8_SB(b, h) + boff + n * 2048 + k * 1024); } while (0)
; #define PG8_WAIT_V(n) asm volatile("s_waitcnt vmcnt(" #n ")" ::: "memory")
; #define PG8_WAIT_L(n) asm volatile("s_waitcnt lgkmcnt(" #n ")" ::: "memory")
; #define PG8_BAR __builtin_amdgcn_s_barrier()
; #define PG8_SCHED __builtin_amdgcn_sched_barrier(0)
; template <class Epi, bool FP8 = false>
; __device__ __forceinline__ void gemm_phase(LAS unsigned char* lds, const Gemm g, const StaticOrder& S_, const Epi& E, const int tid) {
;     ...
;             PG8_LDB(B0, 0, 0); PG8_LDB(B1, 0, 1); PG8_SCHED; PG8_LDA(At, 0, 0); PG8_STAGE(PG8_SA(1, 1), a1 + hstepA, voffA);
;             PG8_WAIT_V(8); PG8_WAIT_L(0); PG8_BAR; PG8_MMA(0, 0, At, B0); PG8_MMA(0, 1, At, B1); PG8_BAR; PG8_SCHED;
;             PG8_LDA(At, 0, 1); PG8_STAGE(PG8_SB(0, 0), b2, voffB); PG8_STAGE(PG8_SB(0, 1), b2 + hstepB, voffB); PG8_STAGE(PG8_SA(0, 0), a2, voffA);
;             PG8_WAIT_V(8); PG8_WAIT_L(0); PG8_BAR; PG8_MMA(1, 0, At, B0); PG8_MMA(1, 1, At, B1); PG8_BAR; PG8_SCHED;
.LBB0_1340:
	ds_read_b128 v[150:153], v147
	ds_read_b128 v[154:157], v147 offset:1024
	ds_read_b128 v[158:161], v147 offset:2048
	ds_read_b128 v[162:165], v147 offset:3072
	ds_read_b128 v[166:169], v148
	ds_read_b128 v[170:173], v148 offset:1024
	ds_read_b128 v[174:177], v148 offset:2048
	ds_read_b128 v[178:181], v148 offset:3072
	s_add_u32 s42, s30, 0xfff80080
	s_addc_u32 s43, s31, -1
	s_cmp_eq_u32 s69, 28
	s_cselect_b32 s47, s23, s43
	s_cselect_b32 s46, s63, s42
	s_cselect_b32 s43, s21, s68
	s_cselect_b32 s42, s66, s67
	s_add_i32 m0, s29, 0xc000
	ds_read_b128 v[182:185], v149
	ds_read_b128 v[186:189], v149 offset:1024
	ds_read_b128 v[190:193], v149 offset:2048
	ds_read_b128 v[194:197], v149 offset:3072
	ds_read_b128 v[198:201], v149 offset:4096
	ds_read_b128 v[202:205], v149 offset:5120
	ds_read_b128 v[206:209], v149 offset:6144
	ds_read_b128 v[210:213], v149 offset:7168
	global_load_lds_dwordx4 v136, s[30:31]
	s_add_i32 m0, s29, 0xe000
	s_nop 0
	global_load_lds_dwordx4 v138, s[30:31]
	s_waitcnt vmcnt(8)
	s_waitcnt lgkmcnt(0)
	s_setprio 1
	s_barrier
	v_mfma_f32_16x16x32_bf16 v[124:127], v[150:153], v[182:185], v[124:127]
	v_mfma_f32_16x16x32_bf16 v[120:123], v[158:161], v[182:185], v[120:123]
	v_mfma_f32_16x16x32_bf16 v[108:111], v[150:153], v[190:193], v[108:111]
	v_mfma_f32_16x16x32_bf16 v[104:107], v[158:161], v[190:193], v[104:107]
	v_mfma_f32_16x16x32_bf16 v[92:95], v[150:153], v[198:201], v[92:95]
	v_mfma_f32_16x16x32_bf16 v[88:91], v[158:161], v[198:201], v[88:91]
	v_mfma_f32_16x16x32_bf16 v[76:79], v[150:153], v[206:209], v[76:79]
	v_mfma_f32_16x16x32_bf16 v[72:75], v[158:161], v[206:209], v[72:75]
	v_mfma_f32_16x16x32_bf16 v[124:127], v[154:157], v[186:189], v[124:127]
	v_mfma_f32_16x16x32_bf16 v[120:123], v[162:165], v[186:189], v[120:123]
	v_mfma_f32_16x16x32_bf16 v[108:111], v[154:157], v[194:197], v[108:111]
	v_mfma_f32_16x16x32_bf16 v[104:107], v[162:165], v[194:197], v[104:107]
	v_mfma_f32_16x16x32_bf16 v[92:95], v[154:157], v[202:205], v[92:95]
	v_mfma_f32_16x16x32_bf16 v[88:91], v[162:165], v[202:205], v[88:91]
	v_mfma_f32_16x16x32_bf16 v[76:79], v[154:157], v[210:213], v[76:79]
	v_mfma_f32_16x16x32_bf16 v[72:75], v[162:165], v[210:213], v[72:75]
	v_mfma_f32_16x16x32_bf16 v[116:119], v[166:169], v[182:185], v[116:119]
	v_mfma_f32_16x16x32_bf16 v[112:115], v[174:177], v[182:185], v[112:115]
	v_mfma_f32_16x16x32_bf16 v[100:103], v[166:169], v[190:193], v[100:103]
	v_mfma_f32_16x16x32_bf16 v[96:99], v[174:177], v[190:193], v[96:99]
	v_mfma_f32_16x16x32_bf16 v[84:87], v[166:169], v[198:201], v[84:87]
	v_mfma_f32_16x16x32_bf16 v[80:83], v[174:177], v[198:201], v[80:83]
	v_mfma_f32_16x16x32_bf16 v[68:71], v[166:169], v[206:209], v[68:71]
	v_mfma_f32_16x16x32_bf16 v[64:67], v[174:177], v[206:209], v[64:67]
	v_mfma_f32_16x16x32_bf16 v[116:119], v[170:173], v[186:189], v[116:119]
	v_mfma_f32_16x16x32_bf16 v[112:115], v[178:181], v[186:189], v[112:115]
	v_mfma_f32_16x16x32_bf16 v[100:103], v[170:173], v[194:197], v[100:103]
	v_mfma_f32_16x16x32_bf16 v[96:99], v[178:181], v[194:197], v[96:99]
	v_mfma_f32_16x16x32_bf16 v[84:87], v[170:173], v[202:205], v[84:87]
	v_mfma_f32_16x16x32_bf16 v[80:83], v[178:181], v[202:205], v[80:83]
	v_mfma_f32_16x16x32_bf16 v[68:71], v[170:173], v[210:213], v[68:71]
	s_setprio 0
	v_mfma_f32_16x16x32_bf16 v[64:67], v[178:181], v[210:213], v[64:67]
	s_barrier
	s_add_u32 s98, s42, s16
	s_addc_u32 s99, s43, s17
	s_add_u32 s100, s46, s16
	s_addc_u32 s101, s47, s17
	s_add_i32 s70, s59, s50
	s_mov_b32 m0, s70
	ds_read_b128 v[182:185], v149 offset:16384
	ds_read_b128 v[186:189], v149 offset:17408
	ds_read_b128 v[190:193], v149 offset:18432
	ds_read_b128 v[194:197], v149 offset:19456
	ds_read_b128 v[198:201], v149 offset:20480
	ds_read_b128 v[202:205], v149 offset:21504
	ds_read_b128 v[206:209], v149 offset:22528
	ds_read_b128 v[210:213], v149 offset:23552
	global_load_lds_dwordx4 v128, s[42:43]
	s_add_i32 m0, s70, 0x2000
	s_add_u32 s70, s42, 0x80000
	s_addc_u32 s71, s43, 0
	s_add_i32 s72, s60, s50
	global_load_lds_dwordx4 v130, s[42:43]
	s_mov_b32 m0, s72
	s_nop 0
	global_load_lds_dwordx4 v128, s[70:71]
	s_add_i32 m0, s72, 0x2000
	s_nop 0
	global_load_lds_dwordx4 v130, s[70:71]
	s_mov_b32 m0, s29
	s_nop 0
	global_load_lds_dwordx4 v134, s[46:47]
	s_mov_b32 m0, s53
	s_nop 0
	global_load_lds_dwordx4 v132, s[46:47]
	s_waitcnt vmcnt(8)
	s_waitcnt lgkmcnt(0)
	s_setprio 1
	s_barrier
	v_mfma_f32_16x16x32_bf16 v[60:63], v[150:153], v[182:185], v[60:63]
	v_mfma_f32_16x16x32_bf16 v[56:59], v[158:161], v[182:185], v[56:59]
	v_mfma_f32_16x16x32_bf16 v[44:47], v[150:153], v[190:193], v[44:47]
	v_mfma_f32_16x16x32_bf16 v[40:43], v[158:161], v[190:193], v[40:43]
	v_mfma_f32_16x16x32_bf16 v[28:31], v[150:153], v[198:201], v[28:31]
	v_mfma_f32_16x16x32_bf16 v[24:27], v[158:161], v[198:201], v[24:27]
	v_mfma_f32_16x16x32_bf16 v[12:15], v[150:153], v[206:209], v[12:15]
	v_mfma_f32_16x16x32_bf16 v[8:11], v[158:161], v[206:209], v[8:11]
	v_mfma_f32_16x16x32_bf16 v[60:63], v[154:157], v[186:189], v[60:63]
	v_mfma_f32_16x16x32_bf16 v[56:59], v[162:165], v[186:189], v[56:59]
	v_mfma_f32_16x16x32_bf16 v[44:47], v[154:157], v[194:197], v[44:47]
	v_mfma_f32_16x16x32_bf16 v[40:43], v[162:165], v[194:197], v[40:43]
	v_mfma_f32_16x16x32_bf16 v[28:31], v[154:157], v[202:205], v[28:31]
	v_mfma_f32_16x16x32_bf16 v[24:27], v[162:165], v[202:205], v[24:27]
	v_mfma_f32_16x16x32_bf16 v[12:15], v[154:157], v[210:213], v[12:15]
	v_mfma_f32_16x16x32_bf16 v[8:11], v[162:165], v[210:213], v[8:11]
	v_mfma_f32_16x16x32_bf16 v[52:55], v[166:169], v[182:185], v[52:55]
	v_mfma_f32_16x16x32_bf16 v[48:51], v[174:177], v[182:185], v[48:51]
	v_mfma_f32_16x16x32_bf16 v[36:39], v[166:169], v[190:193], v[36:39]
	v_mfma_f32_16x16x32_bf16 v[32:35], v[174:177], v[190:193], v[32:35]
	v_mfma_f32_16x16x32_bf16 v[20:23], v[166:169], v[198:201], v[20:23]
	v_mfma_f32_16x16x32_bf16 v[16:19], v[174:177], v[198:201], v[16:19]
	v_mfma_f32_16x16x32_bf16 v[4:7], v[166:169], v[206:209], v[4:7]
	v_mfma_f32_16x16x32_bf16 v[0:3], v[174:177], v[206:209], v[0:3]
	v_mfma_f32_16x16x32_bf16 v[52:55], v[170:173], v[186:189], v[52:55]
	v_mfma_f32_16x16x32_bf16 v[48:51], v[178:181], v[186:189], v[48:51]
	v_mfma_f32_16x16x32_bf16 v[36:39], v[170:173], v[194:197], v[36:39]
	v_mfma_f32_16x16x32_bf16 v[32:35], v[178:181], v[194:197], v[32:35]
	v_mfma_f32_16x16x32_bf16 v[20:23], v[170:173], v[202:205], v[20:23]
	v_mfma_f32_16x16x32_bf16 v[16:19], v[178:181], v[202:205], v[16:19]
	v_mfma_f32_16x16x32_bf16 v[4:7], v[170:173], v[210:213], v[4:7]
	s_setprio 0
	v_mfma_f32_16x16x32_bf16 v[0:3], v[178:181], v[210:213], v[0:3]
	s_barrier
; #define PG8_STAGE(bufoff, gbase, voff) do { _Pragma("unroll") for (int _i = 0; _i < 2; ++_i) \
;         __builtin_amdgcn_global_load_lds((const unsigned*)((const char*)(gbase) + (voff)[_i]), (LAS unsigned*)(lds + (bufoff) + ldsw + _i * 8192), 16, 0, 0); } while (0)
; #define PG8_LDA(dst, b, h) do { _Pragma("unroll") for (int m = 0; m < 4; ++m) _Pragma("unroll") for (int k = 0; k < 2; ++k) dst[m][k] = *(const LAS bf16x8*)(lds + PG8_SA(b, h) + aoff + m * 2048 + k * 1024); } while (0)
; #define PG8_LDB(dst, b, h) do { _Pragma("unroll") for (int n = 0; n < 2; ++n) _Pragma("unroll") for (int k = 0; k < 2; ++k) dst[n][k] = *(const LAS bf16x8*)(lds + PG8_SB(b, h) + boff + n * 2048 + k * 1024); } while (0)
; #define PG8_WAIT_V(n) asm volatile("s_waitcnt vmcnt(" #n ")" ::: "memory")
; #define PG8_WAIT_L(n) asm volatile("s_waitcnt lgkmcnt(" #n ")" ::: "memory")
; #define PG8_BAR __builtin_amdgcn_s_barrier()
; #define PG8_SCHED __builtin_amdgcn_sched_barrier(0)
; template <class Epi, bool FP8 = false>
; __device__ __forceinline__ void gemm_phase(LAS unsigned char* lds, const Gemm g, const StaticOrder& S_, const Epi& E, const int tid) {
;     ...
;             PG8_LDB(B0, 1, 0); PG8_LDB(B1, 1, 1); PG8_SCHED; PG8_LDA(At, 1, 0); PG8_STAGE(PG8_SA(0, 1), a2 + hstepA, voffA);
;             PG8_WAIT_V(8); PG8_WAIT_L(0); PG8_BAR; PG8_MMA(0, 0, At, B0); PG8_MMA(0, 1, At, B1); PG8_BAR; PG8_SCHED;
;             PG8_LDA(At, 1, 1); PG8_STAGE(PG8_SB(1, 0), b3, voffB); PG8_STAGE(PG8_SB(1, 1), b3 + hstepB, voffB); PG8_STAGE(PG8_SA(1, 0), a3, voffA);
;             PG8_WAIT_V(8); PG8_WAIT_L(0); PG8_BAR; PG8_MMA(1, 0, At, B0); PG8_MMA(1, 1, At, B1); PG8_BAR; PG8_SCHED;
;         }
;         if (wr == 0) PG8_BAR;
	s_add_i32 s70, 0, 0x18000
	s_add_i32 s71, 0, 0x1c000
	v_add_u32_e32 v162, s70, v145
	v_add_u32_e32 v178, s71, v145
	ds_read_b128 v[150:153], v162
	ds_read_b128 v[154:157], v162 offset:1024
	ds_read_b128 v[158:161], v162 offset:2048
	ds_read_b128 v[162:165], v162 offset:3072
	ds_read_b128 v[166:169], v178
	ds_read_b128 v[170:173], v178 offset:1024
	ds_read_b128 v[174:177], v178 offset:2048
	ds_read_b128 v[178:181], v178 offset:3072
	s_add_u32 s46, s46, 0x80000
	s_addc_u32 s47, s47, 0
	s_mov_b32 m0, s54
	ds_read_b128 v[182:185], v149 offset:32768
	ds_read_b128 v[186:189], v149 offset:33792
	ds_read_b128 v[190:193], v149 offset:34816
	ds_read_b128 v[194:197], v149 offset:35840
	ds_read_b128 v[198:201], v149 offset:36864
	ds_read_b128 v[202:205], v149 offset:37888
	ds_read_b128 v[206:209], v149 offset:38912
	ds_read_b128 v[210:213], v149 offset:39936
	global_load_lds_dwordx4 v134, s[46:47]
	s_mov_b32 m0, s55
	s_nop 0
	global_load_lds_dwordx4 v132, s[46:47]
	s_waitcnt vmcnt(8)
	s_waitcnt lgkmcnt(0)
	s_setprio 1
	s_barrier
	v_mfma_f32_16x16x32_bf16 v[124:127], v[150:153], v[182:185], v[124:127]
	v_mfma_f32_16x16x32_bf16 v[120:123], v[158:161], v[182:185], v[120:123]
	v_mfma_f32_16x16x32_bf16 v[108:111], v[150:153], v[190:193], v[108:111]
	v_mfma_f32_16x16x32_bf16 v[104:107], v[158:161], v[190:193], v[104:107]
	v_mfma_f32_16x16x32_bf16 v[92:95], v[150:153], v[198:201], v[92:95]
	v_mfma_f32_16x16x32_bf16 v[88:91], v[158:161], v[198:201], v[88:91]
	v_mfma_f32_16x16x32_bf16 v[76:79], v[150:153], v[206:209], v[76:79]
	v_mfma_f32_16x16x32_bf16 v[72:75], v[158:161], v[206:209], v[72:75]
	v_mfma_f32_16x16x32_bf16 v[124:127], v[154:157], v[186:189], v[124:127]
	v_mfma_f32_16x16x32_bf16 v[120:123], v[162:165], v[186:189], v[120:123]
	v_mfma_f32_16x16x32_bf16 v[108:111], v[154:157], v[194:197], v[108:111]
	v_mfma_f32_16x16x32_bf16 v[104:107], v[162:165], v[194:197], v[104:107]
	v_mfma_f32_16x16x32_bf16 v[92:95], v[154:157], v[202:205], v[92:95]
	v_mfma_f32_16x16x32_bf16 v[88:91], v[162:165], v[202:205], v[88:91]
	v_mfma_f32_16x16x32_bf16 v[76:79], v[154:157], v[210:213], v[76:79]
	v_mfma_f32_16x16x32_bf16 v[72:75], v[162:165], v[210:213], v[72:75]
	v_mfma_f32_16x16x32_bf16 v[116:119], v[166:169], v[182:185], v[116:119]
	v_mfma_f32_16x16x32_bf16 v[112:115], v[174:177], v[182:185], v[112:115]
	v_mfma_f32_16x16x32_bf16 v[100:103], v[166:169], v[190:193], v[100:103]
	v_mfma_f32_16x16x32_bf16 v[96:99], v[174:177], v[190:193], v[96:99]
	v_mfma_f32_16x16x32_bf16 v[84:87], v[166:169], v[198:201], v[84:87]
	v_mfma_f32_16x16x32_bf16 v[80:83], v[174:177], v[198:201], v[80:83]
	v_mfma_f32_16x16x32_bf16 v[68:71], v[166:169], v[206:209], v[68:71]
	v_mfma_f32_16x16x32_bf16 v[64:67], v[174:177], v[206:209], v[64:67]
	v_mfma_f32_16x16x32_bf16 v[116:119], v[170:173], v[186:189], v[116:119]
	v_mfma_f32_16x16x32_bf16 v[112:115], v[178:181], v[186:189], v[112:115]
	v_mfma_f32_16x16x32_bf16 v[100:103], v[170:173], v[194:197], v[100:103]
	v_mfma_f32_16x16x32_bf16 v[96:99], v[178:181], v[194:197], v[96:99]
	v_mfma_f32_16x16x32_bf16 v[84:87], v[170:173], v[202:205], v[84:87]
	v_mfma_f32_16x16x32_bf16 v[80:83], v[178:181], v[202:205], v[80:83]
	v_mfma_f32_16x16x32_bf16 v[68:71], v[170:173], v[210:213], v[68:71]
	s_setprio 0
	v_mfma_f32_16x16x32_bf16 v[64:67], v[178:181], v[210:213], v[64:67]
	s_barrier
	s_add_i32 s46, s70, s50
	s_mov_b32 m0, s46
	ds_read_b128 v[182:185], v149 offset:49152
	ds_read_b128 v[186:189], v149 offset:50176
	ds_read_b128 v[190:193], v149 offset:51200
	ds_read_b128 v[194:197], v149 offset:52224
	ds_read_b128 v[198:201], v149 offset:53248
	ds_read_b128 v[202:205], v149 offset:54272
	ds_read_b128 v[206:209], v149 offset:55296
	ds_read_b128 v[210:213], v149 offset:56320
	global_load_lds_dwordx4 v128, s[98:99]
	s_add_i32 m0, s46, 0x2000
	s_add_u32 s42, s42, 0x80080
	s_addc_u32 s43, s43, 0
	s_add_i32 s46, s71, s50
	global_load_lds_dwordx4 v130, s[98:99]
	s_mov_b32 m0, s46
	s_nop 0
	global_load_lds_dwordx4 v128, s[42:43]
	s_add_i32 m0, s46, 0x2000
	s_nop 0
	global_load_lds_dwordx4 v130, s[42:43]
	s_mov_b32 m0, s57
	s_nop 0
	global_load_lds_dwordx4 v134, s[100:101]
	s_mov_b32 m0, s58
	s_nop 0
	global_load_lds_dwordx4 v132, s[100:101]
	s_waitcnt vmcnt(8)
	s_waitcnt lgkmcnt(0)
	s_setprio 1
	s_barrier
	v_mfma_f32_16x16x32_bf16 v[60:63], v[150:153], v[182:185], v[60:63]
	v_mfma_f32_16x16x32_bf16 v[56:59], v[158:161], v[182:185], v[56:59]
	v_mfma_f32_16x16x32_bf16 v[44:47], v[150:153], v[190:193], v[44:47]
	v_mfma_f32_16x16x32_bf16 v[40:43], v[158:161], v[190:193], v[40:43]
	v_mfma_f32_16x16x32_bf16 v[28:31], v[150:153], v[198:201], v[28:31]
	v_mfma_f32_16x16x32_bf16 v[24:27], v[158:161], v[198:201], v[24:27]
	v_mfma_f32_16x16x32_bf16 v[12:15], v[150:153], v[206:209], v[12:15]
	v_mfma_f32_16x16x32_bf16 v[8:11], v[158:161], v[206:209], v[8:11]
	v_mfma_f32_16x16x32_bf16 v[60:63], v[154:157], v[186:189], v[60:63]
	v_mfma_f32_16x16x32_bf16 v[56:59], v[162:165], v[186:189], v[56:59]
	v_mfma_f32_16x16x32_bf16 v[44:47], v[154:157], v[194:197], v[44:47]
	v_mfma_f32_16x16x32_bf16 v[40:43], v[162:165], v[194:197], v[40:43]
	v_mfma_f32_16x16x32_bf16 v[28:31], v[154:157], v[202:205], v[28:31]
	v_mfma_f32_16x16x32_bf16 v[24:27], v[162:165], v[202:205], v[24:27]
	v_mfma_f32_16x16x32_bf16 v[12:15], v[154:157], v[210:213], v[12:15]
	v_mfma_f32_16x16x32_bf16 v[8:11], v[162:165], v[210:213], v[8:11]
	v_mfma_f32_16x16x32_bf16 v[52:55], v[166:169], v[182:185], v[52:55]
	v_mfma_f32_16x16x32_bf16 v[48:51], v[174:177], v[182:185], v[48:51]
	v_mfma_f32_16x16x32_bf16 v[36:39], v[166:169], v[190:193], v[36:39]
	v_mfma_f32_16x16x32_bf16 v[32:35], v[174:177], v[190:193], v[32:35]
	v_mfma_f32_16x16x32_bf16 v[20:23], v[166:169], v[198:201], v[20:23]
	v_mfma_f32_16x16x32_bf16 v[16:19], v[174:177], v[198:201], v[16:19]
	v_mfma_f32_16x16x32_bf16 v[4:7], v[166:169], v[206:209], v[4:7]
	v_mfma_f32_16x16x32_bf16 v[0:3], v[174:177], v[206:209], v[0:3]
	v_mfma_f32_16x16x32_bf16 v[52:55], v[170:173], v[186:189], v[52:55]
	v_mfma_f32_16x16x32_bf16 v[48:51], v[178:181], v[186:189], v[48:51]
	v_mfma_f32_16x16x32_bf16 v[36:39], v[170:173], v[194:197], v[36:39]
	v_mfma_f32_16x16x32_bf16 v[32:35], v[178:181], v[194:197], v[32:35]
	v_mfma_f32_16x16x32_bf16 v[20:23], v[170:173], v[202:205], v[20:23]
	v_mfma_f32_16x16x32_bf16 v[16:19], v[178:181], v[202:205], v[16:19]
	v_mfma_f32_16x16x32_bf16 v[4:7], v[170:173], v[210:213], v[4:7]
	s_setprio 0
	v_mfma_f32_16x16x32_bf16 v[0:3], v[178:181], v[210:213], v[0:3]
	s_barrier
	s_add_i32 s69, s69, 2
	s_add_u32 s30, s30, 0x100
	s_addc_u32 s31, s31, 0
	s_add_u32 s67, s67, 0x100
	s_addc_u32 s68, s68, 0
	s_cmp_gt_u32 s69, 29
	s_cbranch_scc0 .LBB0_1340
	s_and_b64 vcc, exec, s[18:19]
	s_cbranch_vccz .LBB0_1343
	s_barrier

; #define PG8_STAGE(bufoff, gbase, voff) do { _Pragma("unroll") for (int _i = 0; _i < 2; ++_i) \
;         __builtin_amdgcn_global_load_lds((const unsigned*)((const char*)(gbase) + (voff)[_i]), (LAS unsigned*)(lds + (bufoff) + ldsw + _i * 8192), 16, 0, 0); } while (0)
; #define PG8_LDA(dst, b, h) do { _Pragma("unroll") for (int m = 0; m < 4; ++m) _Pragma("unroll") for (int k = 0; k < 2; ++k) dst[m][k] = *(const LAS bf16x8*)(lds + PG8_SA(b, h) + aoff + m * 2048 + k * 1024); } while (0)
; #define PG8_LDB(dst, b, h) do { _Pragma("unroll") for (int n = 0; n < 2; ++n) _Pragma("unroll") for (int k = 0; k < 2; ++k) dst[n][k] = *(const LAS bf16x8*)(lds + PG8_SB(b, h) + boff + n * 2048 + k * 1024); } while (0)
; #define PG8_WAIT_V(n) asm volatile("s_waitcnt vmcnt(" #n ")" ::: "memory")
; #define PG8_WAIT_L(n) asm volatile("s_waitcnt lgkmcnt(" #n ")" ::: "memory")
; #define PG8_BAR __builtin_amdgcn_s_barrier()
; #define PG8_SCHED __builtin_amdgcn_sched_barrier(0)
; template <class Epi, bool FP8 = false>
; __device__ __forceinline__ void gemm_phase(LAS unsigned char* lds, const Gemm g, const StaticOrder& S_, const Epi& E, const int tid) {
;     ...
;             PG8_LDB(B0, 0, 0); PG8_LDB(B1, 0, 1); PG8_SCHED; PG8_LDA(At, 0, 0); PG8_STAGE(PG8_SA(1, 1), a1 + hstepA, voffA);
;             PG8_WAIT_V(8); PG8_WAIT_L(0); PG8_BAR; PG8_MMA(0, 0, At, B0); PG8_MMA(0, 1, At, B1); PG8_BAR; PG8_SCHED;
;             PG8_LDA(At, 0, 1); PG8_STAGE(PG8_SB(0, 0), b2, voffB); PG8_STAGE(PG8_SB(0, 1), b2 + hstepB, voffB); PG8_STAGE(PG8_SA(0, 0), a2, voffA);
;             PG8_WAIT_V(8); PG8_WAIT_L(0); PG8_BAR; PG8_MMA(1, 0, At, B0); PG8_MMA(1, 1, At, B1); PG8_BAR; PG8_SCHED;
.LBB0_1420:
	ds_read_b128 v[140:143], v152
	ds_read_b128 v[144:147], v152 offset:1024
	ds_read_b128 v[156:159], v152 offset:2048
	ds_read_b128 v[160:163], v152 offset:3072
	ds_read_b128 v[164:167], v153
	ds_read_b128 v[168:171], v153 offset:1024
	ds_read_b128 v[172:175], v153 offset:2048
	ds_read_b128 v[176:179], v153 offset:3072
	s_add_u32 s28, s26, 0x100
	s_addc_u32 s29, s27, 0
	s_cmpk_eq_i32 s66, 0x54
	s_cselect_b32 s43, s7, s29
	s_cselect_b32 s42, s6, s28
	s_cselect_b32 s31, s25, s63
	s_cselect_b32 s30, s24, s62
	s_add_i32 m0, s49, 0xc000
	ds_read_b128 v[180:183], v154
	ds_read_b128 v[184:187], v154 offset:1024
	ds_read_b128 v[188:191], v154 offset:2048
	ds_read_b128 v[192:195], v154 offset:3072
	ds_read_b128 v[196:199], v154 offset:4096
	ds_read_b128 v[200:203], v154 offset:5120
	ds_read_b128 v[204:207], v154 offset:6144
	ds_read_b128 v[208:211], v154 offset:7168
	global_load_lds_dwordx4 v132, s[26:27]
	s_add_i32 m0, s49, 0xe000
	s_nop 0
	global_load_lds_dwordx4 v134, s[26:27]
	s_waitcnt vmcnt(8)
	s_waitcnt lgkmcnt(0)
	s_setprio 1
	s_barrier
	v_mfma_f32_16x16x32_bf16 v[124:127], v[140:143], v[180:183], v[124:127]
	v_mfma_f32_16x16x32_bf16 v[120:123], v[156:159], v[180:183], v[120:123]
	v_mfma_f32_16x16x32_bf16 v[108:111], v[140:143], v[188:191], v[108:111]
	v_mfma_f32_16x16x32_bf16 v[104:107], v[156:159], v[188:191], v[104:107]
	v_mfma_f32_16x16x32_bf16 v[92:95], v[140:143], v[196:199], v[92:95]
	v_mfma_f32_16x16x32_bf16 v[88:91], v[156:159], v[196:199], v[88:91]
	v_mfma_f32_16x16x32_bf16 v[76:79], v[140:143], v[204:207], v[76:79]
	v_mfma_f32_16x16x32_bf16 v[72:75], v[156:159], v[204:207], v[72:75]
	v_mfma_f32_16x16x32_bf16 v[124:127], v[144:147], v[184:187], v[124:127]
	v_mfma_f32_16x16x32_bf16 v[120:123], v[160:163], v[184:187], v[120:123]
	v_mfma_f32_16x16x32_bf16 v[108:111], v[144:147], v[192:195], v[108:111]
	v_mfma_f32_16x16x32_bf16 v[104:107], v[160:163], v[192:195], v[104:107]
	v_mfma_f32_16x16x32_bf16 v[92:95], v[144:147], v[200:203], v[92:95]
	v_mfma_f32_16x16x32_bf16 v[88:91], v[160:163], v[200:203], v[88:91]
	v_mfma_f32_16x16x32_bf16 v[76:79], v[144:147], v[208:211], v[76:79]
	v_mfma_f32_16x16x32_bf16 v[72:75], v[160:163], v[208:211], v[72:75]
	v_mfma_f32_16x16x32_bf16 v[116:119], v[164:167], v[180:183], v[116:119]
	v_mfma_f32_16x16x32_bf16 v[112:115], v[172:175], v[180:183], v[112:115]
	v_mfma_f32_16x16x32_bf16 v[100:103], v[164:167], v[188:191], v[100:103]
	v_mfma_f32_16x16x32_bf16 v[96:99], v[172:175], v[188:191], v[96:99]
	v_mfma_f32_16x16x32_bf16 v[84:87], v[164:167], v[196:199], v[84:87]
	v_mfma_f32_16x16x32_bf16 v[80:83], v[172:175], v[196:199], v[80:83]
	v_mfma_f32_16x16x32_bf16 v[68:71], v[164:167], v[204:207], v[68:71]
	v_mfma_f32_16x16x32_bf16 v[64:67], v[172:175], v[204:207], v[64:67]
	v_mfma_f32_16x16x32_bf16 v[116:119], v[168:171], v[184:187], v[116:119]
	v_mfma_f32_16x16x32_bf16 v[112:115], v[176:179], v[184:187], v[112:115]
	v_mfma_f32_16x16x32_bf16 v[100:103], v[168:171], v[192:195], v[100:103]
	v_mfma_f32_16x16x32_bf16 v[96:99], v[176:179], v[192:195], v[96:99]
	v_mfma_f32_16x16x32_bf16 v[84:87], v[168:171], v[200:203], v[84:87]
	v_mfma_f32_16x16x32_bf16 v[80:83], v[176:179], v[200:203], v[80:83]
	v_mfma_f32_16x16x32_bf16 v[68:71], v[168:171], v[208:211], v[68:71]
	s_setprio 0
	v_mfma_f32_16x16x32_bf16 v[64:67], v[176:179], v[208:211], v[64:67]
	s_barrier
	s_add_u32 s98, s30, s18
	s_addc_u32 s99, s31, s19
	s_add_u32 s100, s42, s18
	s_addc_u32 s101, s43, s19
	s_add_i32 s26, s56, s48
	s_mov_b32 m0, s26
	ds_read_b128 v[180:183], v154 offset:16384
	ds_read_b128 v[184:187], v154 offset:17408
	ds_read_b128 v[188:191], v154 offset:18432
	ds_read_b128 v[192:195], v154 offset:19456
	ds_read_b128 v[196:199], v154 offset:20480
	ds_read_b128 v[200:203], v154 offset:21504
	ds_read_b128 v[204:207], v154 offset:22528
	ds_read_b128 v[208:211], v154 offset:23552
	global_load_lds_dwordx4 v128, s[30:31]
	s_add_i32 m0, s26, 0x2000
	s_add_u32 s26, s30, 0x160000
	s_addc_u32 s27, s31, 0
	s_add_i32 s67, s57, s48
	global_load_lds_dwordx4 v130, s[30:31]
	s_mov_b32 m0, s67
	s_nop 0
	global_load_lds_dwordx4 v128, s[26:27]
	s_add_i32 m0, s67, 0x2000
	s_nop 0
	global_load_lds_dwordx4 v130, s[26:27]
	s_mov_b32 m0, s49
	s_nop 0
	global_load_lds_dwordx4 v128, s[42:43]
	s_mov_b32 m0, s50
	s_nop 0
	global_load_lds_dwordx4 v130, s[42:43]
	s_waitcnt vmcnt(8)
	s_waitcnt lgkmcnt(0)
	s_setprio 1
	s_barrier
	v_mfma_f32_16x16x32_bf16 v[60:63], v[140:143], v[180:183], v[60:63]
	v_mfma_f32_16x16x32_bf16 v[56:59], v[156:159], v[180:183], v[56:59]
	v_mfma_f32_16x16x32_bf16 v[44:47], v[140:143], v[188:191], v[44:47]
	v_mfma_f32_16x16x32_bf16 v[40:43], v[156:159], v[188:191], v[40:43]
	v_mfma_f32_16x16x32_bf16 v[28:31], v[140:143], v[196:199], v[28:31]
	v_mfma_f32_16x16x32_bf16 v[24:27], v[156:159], v[196:199], v[24:27]
	v_mfma_f32_16x16x32_bf16 v[12:15], v[140:143], v[204:207], v[12:15]
	v_mfma_f32_16x16x32_bf16 v[8:11], v[156:159], v[204:207], v[8:11]
	v_mfma_f32_16x16x32_bf16 v[60:63], v[144:147], v[184:187], v[60:63]
	v_mfma_f32_16x16x32_bf16 v[56:59], v[160:163], v[184:187], v[56:59]
	v_mfma_f32_16x16x32_bf16 v[44:47], v[144:147], v[192:195], v[44:47]
	v_mfma_f32_16x16x32_bf16 v[40:43], v[160:163], v[192:195], v[40:43]
	v_mfma_f32_16x16x32_bf16 v[28:31], v[144:147], v[200:203], v[28:31]
	v_mfma_f32_16x16x32_bf16 v[24:27], v[160:163], v[200:203], v[24:27]
	v_mfma_f32_16x16x32_bf16 v[12:15], v[144:147], v[208:211], v[12:15]
	v_mfma_f32_16x16x32_bf16 v[8:11], v[160:163], v[208:211], v[8:11]
	v_mfma_f32_16x16x32_bf16 v[52:55], v[164:167], v[180:183], v[52:55]
	v_mfma_f32_16x16x32_bf16 v[48:51], v[172:175], v[180:183], v[48:51]
	v_mfma_f32_16x16x32_bf16 v[36:39], v[164:167], v[188:191], v[36:39]
	v_mfma_f32_16x16x32_bf16 v[32:35], v[172:175], v[188:191], v[32:35]
	v_mfma_f32_16x16x32_bf16 v[20:23], v[164:167], v[196:199], v[20:23]
	v_mfma_f32_16x16x32_bf16 v[16:19], v[172:175], v[196:199], v[16:19]
	v_mfma_f32_16x16x32_bf16 v[4:7], v[164:167], v[204:207], v[4:7]
	v_mfma_f32_16x16x32_bf16 v[0:3], v[172:175], v[204:207], v[0:3]
	v_mfma_f32_16x16x32_bf16 v[52:55], v[168:171], v[184:187], v[52:55]
	v_mfma_f32_16x16x32_bf16 v[48:51], v[176:179], v[184:187], v[48:51]
	v_mfma_f32_16x16x32_bf16 v[36:39], v[168:171], v[192:195], v[36:39]
	v_mfma_f32_16x16x32_bf16 v[32:35], v[176:179], v[192:195], v[32:35]
	v_mfma_f32_16x16x32_bf16 v[20:23], v[168:171], v[200:203], v[20:23]
	v_mfma_f32_16x16x32_bf16 v[16:19], v[176:179], v[200:203], v[16:19]
	v_mfma_f32_16x16x32_bf16 v[4:7], v[168:171], v[208:211], v[4:7]
	s_setprio 0
	v_mfma_f32_16x16x32_bf16 v[0:3], v[176:179], v[208:211], v[0:3]
	s_barrier
; #define PG8_STAGE(bufoff, gbase, voff) do { _Pragma("unroll") for (int _i = 0; _i < 2; ++_i) \
;         __builtin_amdgcn_global_load_lds((const unsigned*)((const char*)(gbase) + (voff)[_i]), (LAS unsigned*)(lds + (bufoff) + ldsw + _i * 8192), 16, 0, 0); } while (0)
; #define PG8_LDA(dst, b, h) do { _Pragma("unroll") for (int m = 0; m < 4; ++m) _Pragma("unroll") for (int k = 0; k < 2; ++k) dst[m][k] = *(const LAS bf16x8*)(lds + PG8_SA(b, h) + aoff + m * 2048 + k * 1024); } while (0)
; #define PG8_LDB(dst, b, h) do { _Pragma("unroll") for (int n = 0; n < 2; ++n) _Pragma("unroll") for (int k = 0; k < 2; ++k) dst[n][k] = *(const LAS bf16x8*)(lds + PG8_SB(b, h) + boff + n * 2048 + k * 1024); } while (0)
; #define PG8_WAIT_V(n) asm volatile("s_waitcnt vmcnt(" #n ")" ::: "memory")
; #define PG8_WAIT_L(n) asm volatile("s_waitcnt lgkmcnt(" #n ")" ::: "memory")
; #define PG8_BAR __builtin_amdgcn_s_barrier()
; #define PG8_SCHED __builtin_amdgcn_sched_barrier(0)
; template <class Epi, bool FP8 = false>
; __device__ __forceinline__ void gemm_phase(LAS unsigned char* lds, const Gemm g, const StaticOrder& S_, const Epi& E, const int tid) {
;     ...
;             PG8_LDB(B0, 1, 0); PG8_LDB(B1, 1, 1); PG8_SCHED; PG8_LDA(At, 1, 0); PG8_STAGE(PG8_SA(0, 1), a2 + hstepA, voffA);
;             PG8_WAIT_V(8); PG8_WAIT_L(0); PG8_BAR; PG8_MMA(0, 0, At, B0); PG8_MMA(0, 1, At, B1); PG8_BAR; PG8_SCHED;
;             PG8_LDA(At, 1, 1); PG8_STAGE(PG8_SB(1, 0), b3, voffB); PG8_STAGE(PG8_SB(1, 1), b3 + hstepB, voffB); PG8_STAGE(PG8_SA(1, 0), a3, voffA);
;             PG8_WAIT_V(8); PG8_WAIT_L(0); PG8_BAR; PG8_MMA(1, 0, At, B0); PG8_MMA(1, 1, At, B1); PG8_BAR; PG8_SCHED;
;         }
;         if (wr == 0) PG8_BAR;
	s_add_i32 s67, 0, 0x18000
	v_add_u32_e32 v155, s67, v150
	s_add_i32 s68, 0, 0x1c000
	ds_read_b128 v[140:143], v155
	ds_read_b128 v[144:147], v155 offset:1024
	ds_read_b128 v[156:159], v155 offset:2048
	ds_read_b128 v[160:163], v155 offset:3072
	v_add_u32_e32 v155, s68, v150
	ds_read_b128 v[164:167], v155
	ds_read_b128 v[168:171], v155 offset:1024
	ds_read_b128 v[172:175], v155 offset:2048
	ds_read_b128 v[176:179], v155 offset:3072
	s_add_u32 s26, s42, 0x160000
	s_addc_u32 s27, s43, 0
	s_mov_b32 m0, s51
	ds_read_b128 v[180:183], v154 offset:32768
	ds_read_b128 v[184:187], v154 offset:33792
	ds_read_b128 v[188:191], v154 offset:34816
	ds_read_b128 v[192:195], v154 offset:35840
	ds_read_b128 v[196:199], v154 offset:36864
	ds_read_b128 v[200:203], v154 offset:37888
	ds_read_b128 v[204:207], v154 offset:38912
	ds_read_b128 v[208:211], v154 offset:39936
	global_load_lds_dwordx4 v128, s[26:27]
	s_mov_b32 m0, s52
	s_nop 0
	global_load_lds_dwordx4 v130, s[26:27]
	s_waitcnt vmcnt(8)
	s_waitcnt lgkmcnt(0)
	s_setprio 1
	s_barrier
	v_mfma_f32_16x16x32_bf16 v[124:127], v[140:143], v[180:183], v[124:127]
	v_mfma_f32_16x16x32_bf16 v[120:123], v[156:159], v[180:183], v[120:123]
	v_mfma_f32_16x16x32_bf16 v[108:111], v[140:143], v[188:191], v[108:111]
	v_mfma_f32_16x16x32_bf16 v[104:107], v[156:159], v[188:191], v[104:107]
	v_mfma_f32_16x16x32_bf16 v[92:95], v[140:143], v[196:199], v[92:95]
	v_mfma_f32_16x16x32_bf16 v[88:91], v[156:159], v[196:199], v[88:91]
	v_mfma_f32_16x16x32_bf16 v[76:79], v[140:143], v[204:207], v[76:79]
	v_mfma_f32_16x16x32_bf16 v[72:75], v[156:159], v[204:207], v[72:75]
	v_mfma_f32_16x16x32_bf16 v[124:127], v[144:147], v[184:187], v[124:127]
	v_mfma_f32_16x16x32_bf16 v[120:123], v[160:163], v[184:187], v[120:123]
	v_mfma_f32_16x16x32_bf16 v[108:111], v[144:147], v[192:195], v[108:111]
	v_mfma_f32_16x16x32_bf16 v[104:107], v[160:163], v[192:195], v[104:107]
	v_mfma_f32_16x16x32_bf16 v[92:95], v[144:147], v[200:203], v[92:95]
	v_mfma_f32_16x16x32_bf16 v[88:91], v[160:163], v[200:203], v[88:91]
	v_mfma_f32_16x16x32_bf16 v[76:79], v[144:147], v[208:211], v[76:79]
	v_mfma_f32_16x16x32_bf16 v[72:75], v[160:163], v[208:211], v[72:75]
	v_mfma_f32_16x16x32_bf16 v[116:119], v[164:167], v[180:183], v[116:119]
	v_mfma_f32_16x16x32_bf16 v[112:115], v[172:175], v[180:183], v[112:115]
	v_mfma_f32_16x16x32_bf16 v[100:103], v[164:167], v[188:191], v[100:103]
	v_mfma_f32_16x16x32_bf16 v[96:99], v[172:175], v[188:191], v[96:99]
	v_mfma_f32_16x16x32_bf16 v[84:87], v[164:167], v[196:199], v[84:87]
	v_mfma_f32_16x16x32_bf16 v[80:83], v[172:175], v[196:199], v[80:83]
	v_mfma_f32_16x16x32_bf16 v[68:71], v[164:167], v[204:207], v[68:71]
	v_mfma_f32_16x16x32_bf16 v[64:67], v[172:175], v[204:207], v[64:67]
	v_mfma_f32_16x16x32_bf16 v[116:119], v[168:171], v[184:187], v[116:119]
	v_mfma_f32_16x16x32_bf16 v[112:115], v[176:179], v[184:187], v[112:115]
	v_mfma_f32_16x16x32_bf16 v[100:103], v[168:171], v[192:195], v[100:103]
	v_mfma_f32_16x16x32_bf16 v[96:99], v[176:179], v[192:195], v[96:99]
	v_mfma_f32_16x16x32_bf16 v[84:87], v[168:171], v[200:203], v[84:87]
	v_mfma_f32_16x16x32_bf16 v[80:83], v[176:179], v[200:203], v[80:83]
	v_mfma_f32_16x16x32_bf16 v[68:71], v[168:171], v[208:211], v[68:71]
	s_setprio 0
	v_mfma_f32_16x16x32_bf16 v[64:67], v[176:179], v[208:211], v[64:67]
	s_barrier
	s_add_i32 s26, s67, s48
	s_mov_b32 m0, s26
	ds_read_b128 v[180:183], v154 offset:49152
	ds_read_b128 v[184:187], v154 offset:50176
	ds_read_b128 v[188:191], v154 offset:51200
	ds_read_b128 v[192:195], v154 offset:52224
	ds_read_b128 v[196:199], v154 offset:53248
	ds_read_b128 v[200:203], v154 offset:54272
	ds_read_b128 v[204:207], v154 offset:55296
	ds_read_b128 v[208:211], v154 offset:56320
	global_load_lds_dwordx4 v128, s[98:99]
	s_add_i32 m0, s26, 0x2000
	s_add_u32 s26, s30, 0x160080
	s_addc_u32 s27, s31, 0
	s_add_i32 s30, s68, s48
	global_load_lds_dwordx4 v130, s[98:99]
	s_mov_b32 m0, s30
	s_nop 0
	global_load_lds_dwordx4 v128, s[26:27]
	s_add_i32 m0, s30, 0x2000
	s_nop 0
	global_load_lds_dwordx4 v130, s[26:27]
	s_mov_b32 m0, s54
	s_nop 0
	global_load_lds_dwordx4 v128, s[100:101]
	s_mov_b32 m0, s55
	s_nop 0
	global_load_lds_dwordx4 v130, s[100:101]
	s_waitcnt vmcnt(8)
	s_waitcnt lgkmcnt(0)
	s_setprio 1
	s_barrier
	v_mfma_f32_16x16x32_bf16 v[60:63], v[140:143], v[180:183], v[60:63]
	v_mfma_f32_16x16x32_bf16 v[56:59], v[156:159], v[180:183], v[56:59]
	v_mfma_f32_16x16x32_bf16 v[44:47], v[140:143], v[188:191], v[44:47]
	v_mfma_f32_16x16x32_bf16 v[40:43], v[156:159], v[188:191], v[40:43]
	v_mfma_f32_16x16x32_bf16 v[28:31], v[140:143], v[196:199], v[28:31]
	v_mfma_f32_16x16x32_bf16 v[24:27], v[156:159], v[196:199], v[24:27]
	v_mfma_f32_16x16x32_bf16 v[12:15], v[140:143], v[204:207], v[12:15]
	v_mfma_f32_16x16x32_bf16 v[8:11], v[156:159], v[204:207], v[8:11]
	v_mfma_f32_16x16x32_bf16 v[60:63], v[144:147], v[184:187], v[60:63]
	v_mfma_f32_16x16x32_bf16 v[56:59], v[160:163], v[184:187], v[56:59]
	v_mfma_f32_16x16x32_bf16 v[44:47], v[144:147], v[192:195], v[44:47]
	v_mfma_f32_16x16x32_bf16 v[40:43], v[160:163], v[192:195], v[40:43]
	v_mfma_f32_16x16x32_bf16 v[28:31], v[144:147], v[200:203], v[28:31]
	v_mfma_f32_16x16x32_bf16 v[24:27], v[160:163], v[200:203], v[24:27]
	v_mfma_f32_16x16x32_bf16 v[12:15], v[144:147], v[208:211], v[12:15]
	v_mfma_f32_16x16x32_bf16 v[8:11], v[160:163], v[208:211], v[8:11]
	v_mfma_f32_16x16x32_bf16 v[52:55], v[164:167], v[180:183], v[52:55]
	v_mfma_f32_16x16x32_bf16 v[48:51], v[172:175], v[180:183], v[48:51]
	v_mfma_f32_16x16x32_bf16 v[36:39], v[164:167], v[188:191], v[36:39]
	v_mfma_f32_16x16x32_bf16 v[32:35], v[172:175], v[188:191], v[32:35]
	v_mfma_f32_16x16x32_bf16 v[20:23], v[164:167], v[196:199], v[20:23]
	v_mfma_f32_16x16x32_bf16 v[16:19], v[172:175], v[196:199], v[16:19]
	v_mfma_f32_16x16x32_bf16 v[4:7], v[164:167], v[204:207], v[4:7]
	v_mfma_f32_16x16x32_bf16 v[0:3], v[172:175], v[204:207], v[0:3]
	v_mfma_f32_16x16x32_bf16 v[52:55], v[168:171], v[184:187], v[52:55]
	v_mfma_f32_16x16x32_bf16 v[48:51], v[176:179], v[184:187], v[48:51]
	v_mfma_f32_16x16x32_bf16 v[36:39], v[168:171], v[192:195], v[36:39]
	v_mfma_f32_16x16x32_bf16 v[32:35], v[176:179], v[192:195], v[32:35]
	v_mfma_f32_16x16x32_bf16 v[20:23], v[168:171], v[200:203], v[20:23]
	v_mfma_f32_16x16x32_bf16 v[16:19], v[176:179], v[200:203], v[16:19]
	v_mfma_f32_16x16x32_bf16 v[4:7], v[168:171], v[208:211], v[4:7]
	s_setprio 0
	v_mfma_f32_16x16x32_bf16 v[0:3], v[176:179], v[208:211], v[0:3]
	s_barrier
	s_add_i32 s66, s66, 2
	s_add_u32 s62, s62, 0x100
	s_addc_u32 s63, s63, 0
	s_cmpk_gt_u32 s66, 0x55
	s_mov_b64 s[26:27], s[28:29]
	s_cbranch_scc0 .LBB0_1420
	s_and_b64 vcc, exec, s[20:21]
	s_cbranch_vccz .LBB0_1423
	s_barrier
